# VALU-free LDS-DMA address math (saddr form) in all GEMM loops, priority raised before pre-MMA barrier
# speedup vs baseline: 1.0203x; 1.0203x over previous
; #define PG8_STAGE(bufoff, gbase, voff) do { _Pragma("unroll") for (int _i = 0; _i < 2; ++_i) \
;         __builtin_amdgcn_global_load_lds((const unsigned*)((const char*)(gbase) + (voff)[_i]), (PG8_LAS unsigned*)(lds + (bufoff) + ldsw + _i * 8192), 16, 0, 0); } while (0)
; #define PG8_LDA(dst, b, h) do { _Pragma("unroll") for (int m = 0; m < 4; ++m) _Pragma("unroll") for (int k = 0; k < 2; ++k) dst[m][k] = *(const PG8_LAS bf16x8*)(lds + PG8_SA(b, h) + aoff + m * 2048 + k * 1024); } while (0)
; #define PG8_WAIT_L(n) asm volatile("s_waitcnt lgkmcnt(" #n ")" ::: "memory")
; #define PG8_BAR __builtin_amdgcn_s_barrier()
; #define PG8_SCHED __builtin_amdgcn_sched_barrier(0)
; template <class Epi, class Sched, bool ALIGN_EPI = false, bool SP2 = false>
; __device__ __forceinline__ void gemm_phase(PG8_LAS unsigned char* lds, const Gemm g, const Sched& S, const Epi& E) {
;     ...
;         const bool has_next = S.next(ui + 1, nxt);
;         const char* nA = has_next ? (const char*)g.A + (size_t)nxt.pm * tstep : cA; const char* nB = has_next ? (const char*)g.Bt + (size_t)nxt.pn * tstep : cB;
;         for (int t = 0; t < nt; t += 2) {
;             const bool last = (t == nt - 2);
;             const char* a1 = cA + (size_t)(t + 1) * kstep;
;             const char* a2 = last ? nA : cA + (size_t)(t + 2) * kstep; const char* b2 = last ? nB : cB + (size_t)(t + 2) * kstep;
;             const char* a3 = a2 + kstep; const char* b3 = b2 + kstep;
;             if (last && has_next) S.a_ready(nxt);
;             if constexpr (SP2) {
;             const int relax = __builtin_amdgcn_readfirstlane((t == 0 && ui > 0) ? 1 : 0);
;             PG8_LDB(B0, 0, 0); PG8_LDB(B1, 0, 1); PG8_SCHED; PG8_LDA(At, 0, 0); PG8_STAGE(PG8_SA(1, 1), a1 + hstep, voffA);
;             asm volatile("s_cmp_lg_u32 %0, 0\n\ts_cbranch_scc1 .Lrelax%=\n\ts_waitcnt vmcnt(8)\n.Lrelax%=:\n\ts_waitcnt vmcnt(%1)" :: "s"(relax), "n"(8 + Epi::NST) : "memory", "scc");
;             PG8_WAIT_L(0); PG8_BAR; PG8_MMA(0, 0, At, B0); PG8_MMA(0, 1, At, B1); PG8_BAR; PG8_SCHED;
;             PG8_LDA(At, 0, 1); PG8_STAGE(PG8_SB(0, 0), b2, voffB); PG8_STAGE(PG8_SB(0, 1), b2 + hstep, voffB); PG8_STAGE(PG8_SA(0, 0), a2, voffA);
;             asm volatile("s_cmp_lg_u32 %0, 0\n\ts_cbranch_scc1 .Lrelax%=\n\ts_waitcnt vmcnt(8)\n.Lrelax%=:\n\ts_waitcnt vmcnt(%1)" :: "s"(relax), "n"(8 + Epi::NST) : "memory", "scc");
.LBB0_123:
	s_ashr_i32 s51, s50, 31
	s_lshl_b64 s[30:31], s[50:51], 19
	s_add_u32 s52, s82, s30
	s_addc_u32 s53, s83, s31
	s_and_b64 s[30:31], s[38:39], exec
	s_cselect_b32 s51, s53, s29
	s_cselect_b32 s66, s52, s28
	s_ashr_i32 s49, s48, 31
	s_lshl_b64 s[30:31], s[48:49], 19
	v_readlane_b32 s34, v253, 38
	v_readlane_b32 s35, v253, 39
	s_add_u32 s54, s34, s30
	s_addc_u32 s55, s35, s31
	s_and_b64 s[30:31], s[38:39], exec
	s_cselect_b32 s49, s55, s5
	s_cselect_b32 s67, s54, s4
	s_cmp_lg_u32 s65, 0
	s_cselect_b64 s[30:31], -1, 0
	s_add_u32 s34, s28, 0x40080
	s_addc_u32 s35, s29, 0
	s_add_u32 s68, s4, 0x100
	s_waitcnt vmcnt(16)
	v_lshl_add_u64 v[128:129], s[34:35], 0, v[146:147]
	v_lshl_add_u64 v[130:131], s[34:35], 0, v[148:149]
	s_addc_u32 s69, s5, 0
	s_mov_b32 s70, -2
	s_mov_b64 s[42:43], 0
	v_add_u32_e32 v154, 0x10000, v159
	s_add_u32 s34, s28, s42
	s_addc_u32 s35, s29, s43
	s_add_u32 s72, s34, 0x40080
	s_addc_u32 s73, s35, 0
	s_add_u32 s34, s34, 0x100
	s_addc_u32 s35, s35, 0
	s_add_u32 s4, s68, s42
	s_addc_u32 s5, s69, s43
	s_cmpk_eq_i32 s42, 0x700
	s_cselect_b32 s35, s51, s35
	s_cselect_b32 s34, s66, s34
	s_cselect_b32 s5, s49, s5
	s_cselect_b32 s4, s67, s4
	ds_read_b128 v[132:135], v154
	ds_read_b128 v[150:153], v154 offset:1024
	ds_read_b128 v[164:167], v154 offset:2048
	ds_read_b128 v[168:171], v154 offset:3072
	ds_read_b128 v[172:175], v154 offset:16384
	ds_read_b128 v[186:189], v154 offset:17408
	ds_read_b128 v[190:193], v154 offset:18432
	ds_read_b128 v[194:197], v154 offset:19456
	s_add_i32 m0, s37, 0xc000
	ds_read_b128 v[198:201], v163
	ds_read_b128 v[202:205], v163 offset:1024
	ds_read_b128 v[206:209], v163 offset:2048
	ds_read_b128 v[210:213], v163 offset:3072
	ds_read_b128 v[214:217], v163 offset:4096
	ds_read_b128 v[234:237], v163 offset:5120
	ds_read_b128 v[238:241], v163 offset:6144
	ds_read_b128 v[242:245], v163 offset:7168
	global_load_lds_dwordx4 v146, s[72:73]
	s_add_i32 m0, s37, 0xe000
	s_nop 0
	global_load_lds_dwordx4 v148, s[72:73]
	s_cmp_lg_u32 s30, 0
	s_cbranch_scc1 .Lmy_qkvp_rx1
	s_waitcnt vmcnt(8)
.Lmy_qkvp_rx1:
	s_waitcnt vmcnt(24)
	s_waitcnt lgkmcnt(0)
	s_setprio 1
	s_barrier
	v_mfma_f32_16x16x32_bf16 v[124:127], v[132:135], v[198:201], 0
	v_mfma_f32_16x16x32_bf16 v[120:123], v[164:167], v[198:201], 0
	v_mfma_f32_16x16x32_bf16 v[112:115], v[132:135], v[206:209], 0
	v_mfma_f32_16x16x32_bf16 v[104:107], v[164:167], v[206:209], 0
	v_mfma_f32_16x16x32_bf16 v[96:99], v[132:135], v[214:217], 0
	v_mfma_f32_16x16x32_bf16 v[88:91], v[164:167], v[214:217], 0
	v_mfma_f32_16x16x32_bf16 v[80:83], v[132:135], v[238:241], 0
	v_mfma_f32_16x16x32_bf16 v[72:75], v[164:167], v[238:241], 0
	v_mfma_f32_16x16x32_bf16 v[124:127], v[150:153], v[202:205], v[124:127]
	v_mfma_f32_16x16x32_bf16 v[120:123], v[168:171], v[202:205], v[120:123]
	v_mfma_f32_16x16x32_bf16 v[112:115], v[150:153], v[210:213], v[112:115]
	v_mfma_f32_16x16x32_bf16 v[104:107], v[168:171], v[210:213], v[104:107]
	v_mfma_f32_16x16x32_bf16 v[96:99], v[150:153], v[234:237], v[96:99]
	v_mfma_f32_16x16x32_bf16 v[88:91], v[168:171], v[234:237], v[88:91]
	v_mfma_f32_16x16x32_bf16 v[80:83], v[150:153], v[242:245], v[80:83]
	v_mfma_f32_16x16x32_bf16 v[72:75], v[168:171], v[242:245], v[72:75]
	s_setprio 0
	s_setprio 1
	v_mfma_f32_16x16x32_bf16 v[116:119], v[172:175], v[198:201], 0
	v_mfma_f32_16x16x32_bf16 v[108:111], v[190:193], v[198:201], 0
	v_mfma_f32_16x16x32_bf16 v[100:103], v[172:175], v[206:209], 0
	v_mfma_f32_16x16x32_bf16 v[92:95], v[190:193], v[206:209], 0
	v_mfma_f32_16x16x32_bf16 v[84:87], v[172:175], v[214:217], 0
	v_mfma_f32_16x16x32_bf16 v[76:79], v[190:193], v[214:217], 0
	v_mfma_f32_16x16x32_bf16 v[68:71], v[172:175], v[238:241], 0
	v_mfma_f32_16x16x32_bf16 v[64:67], v[190:193], v[238:241], 0
	v_mfma_f32_16x16x32_bf16 v[116:119], v[186:189], v[202:205], v[116:119]
	v_mfma_f32_16x16x32_bf16 v[108:111], v[194:197], v[202:205], v[108:111]
	v_mfma_f32_16x16x32_bf16 v[100:103], v[186:189], v[210:213], v[100:103]
	v_mfma_f32_16x16x32_bf16 v[92:95], v[194:197], v[210:213], v[92:95]
	v_mfma_f32_16x16x32_bf16 v[84:87], v[186:189], v[234:237], v[84:87]
	v_mfma_f32_16x16x32_bf16 v[76:79], v[194:197], v[234:237], v[76:79]
	v_mfma_f32_16x16x32_bf16 v[68:71], v[186:189], v[242:245], v[68:71]
	v_mfma_f32_16x16x32_bf16 v[64:67], v[194:197], v[242:245], v[64:67]
	s_setprio 0
	s_barrier
	s_add_i32 m0, s2, 0x10000
	ds_read_b128 v[198:201], v163 offset:16384
	ds_read_b128 v[202:205], v163 offset:17408
	ds_read_b128 v[206:209], v163 offset:18432
	ds_read_b128 v[210:213], v163 offset:19456
	ds_read_b128 v[214:217], v163 offset:20480
	ds_read_b128 v[234:237], v163 offset:21504
	ds_read_b128 v[238:241], v163 offset:22528
	ds_read_b128 v[242:245], v163 offset:23552
	global_load_lds_dwordx4 v138, s[4:5]
	s_add_i32 m0, s2, 0x12000
	s_add_u32 s72, s4, 0x40000
	s_addc_u32 s73, s5, 0
	global_load_lds_dwordx4 v142, s[4:5]
	s_add_i32 m0, s2, 0x14000
	s_nop 0
	global_load_lds_dwordx4 v138, s[72:73]
	s_add_i32 m0, s2, 0x16000
	s_nop 0
	global_load_lds_dwordx4 v142, s[72:73]
	s_mov_b32 m0, s37
	s_nop 0
	global_load_lds_dwordx4 v136, s[34:35]
	s_mov_b32 m0, s57
	s_nop 0
	global_load_lds_dwordx4 v140, s[34:35]
	s_cmp_lg_u32 s30, 0
	s_cbranch_scc1 .Lmy_qkvp_rx2
	s_waitcnt vmcnt(8)
; #define PG8_STAGE(bufoff, gbase, voff) do { _Pragma("unroll") for (int _i = 0; _i < 2; ++_i) \
;         __builtin_amdgcn_global_load_lds((const unsigned*)((const char*)(gbase) + (voff)[_i]), (PG8_LAS unsigned*)(lds + (bufoff) + ldsw + _i * 8192), 16, 0, 0); } while (0)
; #define PG8_LDA(dst, b, h) do { _Pragma("unroll") for (int m = 0; m < 4; ++m) _Pragma("unroll") for (int k = 0; k < 2; ++k) dst[m][k] = *(const PG8_LAS bf16x8*)(lds + PG8_SA(b, h) + aoff + m * 2048 + k * 1024); } while (0)
; #define PG8_LDB(dst, b, h) do { _Pragma("unroll") for (int n = 0; n < 2; ++n) _Pragma("unroll") for (int k = 0; k < 2; ++k) dst[n][k] = *(const PG8_LAS bf16x8*)(lds + PG8_SB(b, h) + boff + n * 2048 + k * 1024); } while (0)
; #define PG8_MMA(ai, bj, At, Bt) do { __builtin_amdgcn_s_setprio(1); _Pragma("unroll") for (int m = 0; m < 4; ++m) _Pragma("unroll") for (int n = 0; n < 2; ++n) _Pragma("unroll") for (int k = 0; k < 2; ++k) \
;         acc[ai][bj][m][n] = __builtin_amdgcn_mfma_f32_16x16x32_bf16(Bt[n][k], At[m][k], acc[ai][bj][m][n], 0, 0, 0); __builtin_amdgcn_s_setprio(0); } while (0)
; #define PG8_WAIT_V(n) asm volatile("s_waitcnt vmcnt(" #n ")" ::: "memory")
; #define PG8_WAIT_L(n) asm volatile("s_waitcnt lgkmcnt(" #n ")" ::: "memory")
; #define PG8_BAR __builtin_amdgcn_s_barrier()
; #define PG8_SCHED __builtin_amdgcn_sched_barrier(0)
; template <class Epi, class Sched, bool ALIGN_EPI = false, bool SP2 = false>
; __device__ __forceinline__ void gemm_phase(PG8_LAS unsigned char* lds, const Gemm g, const Sched& S, const Epi& E) {
;     ...
;             asm volatile("s_cmp_lg_u32 %0, 0\n\ts_cbranch_scc1 .Lrelax%=\n\ts_waitcnt vmcnt(8)\n.Lrelax%=:\n\ts_waitcnt vmcnt(%1)" :: "s"(relax), "n"(8 + Epi::NST) : "memory", "scc");
;             PG8_WAIT_L(0); PG8_BAR; PG8_MMA(1, 0, At, B0); PG8_MMA(1, 1, At, B1); PG8_BAR; PG8_SCHED;
;             PG8_LDB(B0, 1, 0); PG8_LDB(B1, 1, 1); PG8_SCHED; PG8_LDA(At, 1, 0); PG8_STAGE(PG8_SA(0, 1), a2 + hstep, voffA);
;             PG8_WAIT_V(8); PG8_WAIT_L(0); PG8_BAR; PG8_MMA(0, 0, At, B0); PG8_MMA(0, 1, At, B1); PG8_BAR; PG8_SCHED;
.Lmy_qkvp_rx2:
	s_waitcnt vmcnt(24)
	s_waitcnt lgkmcnt(0)
	s_setprio 1
	s_barrier
	v_mfma_f32_16x16x32_bf16 v[60:63], v[132:135], v[198:201], 0
	v_mfma_f32_16x16x32_bf16 v[56:59], v[164:167], v[198:201], 0
	v_mfma_f32_16x16x32_bf16 v[48:51], v[132:135], v[206:209], 0
	v_mfma_f32_16x16x32_bf16 v[40:43], v[164:167], v[206:209], 0
	v_mfma_f32_16x16x32_bf16 v[32:35], v[132:135], v[214:217], 0
	v_mfma_f32_16x16x32_bf16 v[24:27], v[164:167], v[214:217], 0
	v_mfma_f32_16x16x32_bf16 v[16:19], v[132:135], v[238:241], 0
	v_mfma_f32_16x16x32_bf16 v[8:11], v[164:167], v[238:241], 0
	v_mfma_f32_16x16x32_bf16 v[60:63], v[150:153], v[202:205], v[60:63]
	v_mfma_f32_16x16x32_bf16 v[56:59], v[168:171], v[202:205], v[56:59]
	v_mfma_f32_16x16x32_bf16 v[48:51], v[150:153], v[210:213], v[48:51]
	v_mfma_f32_16x16x32_bf16 v[40:43], v[168:171], v[210:213], v[40:43]
	v_mfma_f32_16x16x32_bf16 v[32:35], v[150:153], v[234:237], v[32:35]
	v_mfma_f32_16x16x32_bf16 v[24:27], v[168:171], v[234:237], v[24:27]
	v_mfma_f32_16x16x32_bf16 v[16:19], v[150:153], v[242:245], v[16:19]
	v_mfma_f32_16x16x32_bf16 v[8:11], v[168:171], v[242:245], v[8:11]
	s_setprio 0
	s_setprio 1
	v_mfma_f32_16x16x32_bf16 v[52:55], v[172:175], v[198:201], 0
	v_mfma_f32_16x16x32_bf16 v[44:47], v[190:193], v[198:201], 0
	v_mfma_f32_16x16x32_bf16 v[36:39], v[172:175], v[206:209], 0
	v_mfma_f32_16x16x32_bf16 v[28:31], v[190:193], v[206:209], 0
	v_mfma_f32_16x16x32_bf16 v[20:23], v[172:175], v[214:217], 0
	v_mfma_f32_16x16x32_bf16 v[12:15], v[190:193], v[214:217], 0
	v_mfma_f32_16x16x32_bf16 v[4:7], v[172:175], v[238:241], 0
	v_mfma_f32_16x16x32_bf16 v[0:3], v[190:193], v[238:241], 0
	v_mfma_f32_16x16x32_bf16 v[52:55], v[186:189], v[202:205], v[52:55]
	v_mfma_f32_16x16x32_bf16 v[44:47], v[194:197], v[202:205], v[44:47]
	v_mfma_f32_16x16x32_bf16 v[36:39], v[186:189], v[210:213], v[36:39]
	v_mfma_f32_16x16x32_bf16 v[28:31], v[194:197], v[210:213], v[28:31]
	v_mfma_f32_16x16x32_bf16 v[20:23], v[186:189], v[234:237], v[20:23]
	v_mfma_f32_16x16x32_bf16 v[12:15], v[194:197], v[234:237], v[12:15]
	v_mfma_f32_16x16x32_bf16 v[4:7], v[186:189], v[242:245], v[4:7]
	v_mfma_f32_16x16x32_bf16 v[0:3], v[194:197], v[242:245], v[0:3]
	s_setprio 0
	s_barrier
	ds_read_b128 v[132:135], v154 offset:32768
	ds_read_b128 v[150:153], v154 offset:33792
	ds_read_b128 v[164:167], v154 offset:34816
	ds_read_b128 v[168:171], v154 offset:35840
	ds_read_b128 v[172:175], v154 offset:49152
	ds_read_b128 v[186:189], v154 offset:50176
	ds_read_b128 v[190:193], v154 offset:51200
	ds_read_b128 v[194:197], v154 offset:52224
	s_add_u32 s34, s34, 0x40000
	s_addc_u32 s35, s35, 0
	s_mov_b32 m0, s58
	ds_read_b128 v[198:201], v163 offset:32768
	ds_read_b128 v[202:205], v163 offset:33792
	ds_read_b128 v[206:209], v163 offset:34816
	ds_read_b128 v[210:213], v163 offset:35840
	ds_read_b128 v[214:217], v163 offset:36864
	ds_read_b128 v[234:237], v163 offset:37888
	ds_read_b128 v[238:241], v163 offset:38912
	ds_read_b128 v[242:245], v163 offset:39936
	global_load_lds_dwordx4 v136, s[34:35]
	s_mov_b32 m0, s59
	s_nop 0
	global_load_lds_dwordx4 v140, s[34:35]
	s_waitcnt vmcnt(8)
	s_waitcnt lgkmcnt(0)
	s_setprio 1
	s_barrier
	v_mfma_f32_16x16x32_bf16 v[124:127], v[132:135], v[198:201], v[124:127]
	v_mfma_f32_16x16x32_bf16 v[120:123], v[164:167], v[198:201], v[120:123]
	v_mfma_f32_16x16x32_bf16 v[112:115], v[132:135], v[206:209], v[112:115]
	v_mfma_f32_16x16x32_bf16 v[104:107], v[164:167], v[206:209], v[104:107]
	v_mfma_f32_16x16x32_bf16 v[96:99], v[132:135], v[214:217], v[96:99]
	v_mfma_f32_16x16x32_bf16 v[88:91], v[164:167], v[214:217], v[88:91]
	v_mfma_f32_16x16x32_bf16 v[80:83], v[132:135], v[238:241], v[80:83]
	v_mfma_f32_16x16x32_bf16 v[72:75], v[164:167], v[238:241], v[72:75]
	v_mfma_f32_16x16x32_bf16 v[124:127], v[150:153], v[202:205], v[124:127]
	v_mfma_f32_16x16x32_bf16 v[120:123], v[168:171], v[202:205], v[120:123]
	v_mfma_f32_16x16x32_bf16 v[112:115], v[150:153], v[210:213], v[112:115]
	v_mfma_f32_16x16x32_bf16 v[104:107], v[168:171], v[210:213], v[104:107]
	v_mfma_f32_16x16x32_bf16 v[96:99], v[150:153], v[234:237], v[96:99]
	v_mfma_f32_16x16x32_bf16 v[88:91], v[168:171], v[234:237], v[88:91]
	v_mfma_f32_16x16x32_bf16 v[80:83], v[150:153], v[242:245], v[80:83]
	v_mfma_f32_16x16x32_bf16 v[72:75], v[168:171], v[242:245], v[72:75]
	s_setprio 0
	s_setprio 1
	v_mfma_f32_16x16x32_bf16 v[116:119], v[172:175], v[198:201], v[116:119]
	v_mfma_f32_16x16x32_bf16 v[108:111], v[190:193], v[198:201], v[108:111]
	v_mfma_f32_16x16x32_bf16 v[100:103], v[172:175], v[206:209], v[100:103]
	v_mfma_f32_16x16x32_bf16 v[92:95], v[190:193], v[206:209], v[92:95]
	v_mfma_f32_16x16x32_bf16 v[84:87], v[172:175], v[214:217], v[84:87]
	v_mfma_f32_16x16x32_bf16 v[76:79], v[190:193], v[214:217], v[76:79]
	v_mfma_f32_16x16x32_bf16 v[68:71], v[172:175], v[238:241], v[68:71]
	v_mfma_f32_16x16x32_bf16 v[64:67], v[190:193], v[238:241], v[64:67]
	v_mfma_f32_16x16x32_bf16 v[116:119], v[186:189], v[202:205], v[116:119]
	v_mfma_f32_16x16x32_bf16 v[108:111], v[194:197], v[202:205], v[108:111]
	v_mfma_f32_16x16x32_bf16 v[100:103], v[186:189], v[210:213], v[100:103]
	v_mfma_f32_16x16x32_bf16 v[92:95], v[194:197], v[210:213], v[92:95]
	v_mfma_f32_16x16x32_bf16 v[84:87], v[186:189], v[234:237], v[84:87]
	v_mfma_f32_16x16x32_bf16 v[76:79], v[194:197], v[234:237], v[76:79]
	v_mfma_f32_16x16x32_bf16 v[68:71], v[186:189], v[242:245], v[68:71]
	v_mfma_f32_16x16x32_bf16 v[64:67], v[194:197], v[242:245], v[64:67]
	s_setprio 0
	s_barrier
; #define PG8_STAGE(bufoff, gbase, voff) do { _Pragma("unroll") for (int _i = 0; _i < 2; ++_i) \
;         __builtin_amdgcn_global_load_lds((const unsigned*)((const char*)(gbase) + (voff)[_i]), (PG8_LAS unsigned*)(lds + (bufoff) + ldsw + _i * 8192), 16, 0, 0); } while (0)
; #define PG8_LDA(dst, b, h) do { _Pragma("unroll") for (int m = 0; m < 4; ++m) _Pragma("unroll") for (int k = 0; k < 2; ++k) dst[m][k] = *(const PG8_LAS bf16x8*)(lds + PG8_SA(b, h) + aoff + m * 2048 + k * 1024); } while (0)
; #define PG8_LDB(dst, b, h) do { _Pragma("unroll") for (int n = 0; n < 2; ++n) _Pragma("unroll") for (int k = 0; k < 2; ++k) dst[n][k] = *(const PG8_LAS bf16x8*)(lds + PG8_SB(b, h) + boff + n * 2048 + k * 1024); } while (0)
; #define PG8_WAIT_V(n) asm volatile("s_waitcnt vmcnt(" #n ")" ::: "memory")
; #define PG8_WAIT_L(n) asm volatile("s_waitcnt lgkmcnt(" #n ")" ::: "memory")
; #define PG8_BAR __builtin_amdgcn_s_barrier()
; #define PG8_SCHED __builtin_amdgcn_sched_barrier(0)
; template <class Epi, class Sched, bool ALIGN_EPI = false, bool SP2 = false>
; __device__ __forceinline__ void gemm_phase(PG8_LAS unsigned char* lds, const Gemm g, const Sched& S, const Epi& E) {
;     ...
;         for (int t = 0; t < nt; t += 2) {
;             const bool last = (t == nt - 2);
;             const char* a1 = cA + (size_t)(t + 1) * kstep;
;             const char* a2 = last ? nA : cA + (size_t)(t + 2) * kstep; const char* b2 = last ? nB : cB + (size_t)(t + 2) * kstep;
;             const char* a3 = a2 + kstep; const char* b3 = b2 + kstep;
;             if (last && has_next) S.a_ready(nxt);
;             if constexpr (SP2) {
;             const int relax = __builtin_amdgcn_readfirstlane((t == 0 && ui > 0) ? 1 : 0);
;             PG8_LDB(B0, 0, 0); PG8_LDB(B1, 0, 1); PG8_SCHED; PG8_LDA(At, 0, 0); PG8_STAGE(PG8_SA(1, 1), a1 + hstep, voffA);
;             asm volatile("s_cmp_lg_u32 %0, 0\n\ts_cbranch_scc1 .Lrelax%=\n\ts_waitcnt vmcnt(8)\n.Lrelax%=:\n\ts_waitcnt vmcnt(%1)" :: "s"(relax), "n"(8 + Epi::NST) : "memory", "scc");
;             PG8_WAIT_L(0); PG8_BAR; PG8_MMA(0, 0, At, B0); PG8_MMA(0, 1, At, B1); PG8_BAR; PG8_SCHED;
;     ...
;             PG8_LDA(At, 1, 1); PG8_STAGE(PG8_SB(1, 0), b3, voffB); PG8_STAGE(PG8_SB(1, 1), b3 + hstep, voffB); PG8_STAGE(PG8_SA(1, 0), a3, voffA);
;             PG8_WAIT_V(8); PG8_WAIT_L(0); PG8_BAR; PG8_MMA(1, 0, At, B0); PG8_MMA(1, 1, At, B1); PG8_BAR; PG8_SCHED;
	s_add_i32 m0, s2, 0x18000
	s_add_u32 s4, s4, 0x80
	s_addc_u32 s5, s5, 0
	ds_read_b128 v[198:201], v163 offset:49152
	ds_read_b128 v[202:205], v163 offset:50176
	ds_read_b128 v[206:209], v163 offset:51200
	ds_read_b128 v[210:213], v163 offset:52224
	ds_read_b128 v[214:217], v163 offset:53248
	ds_read_b128 v[234:237], v163 offset:54272
	ds_read_b128 v[238:241], v163 offset:55296
	ds_read_b128 v[242:245], v163 offset:56320
	global_load_lds_dwordx4 v138, s[4:5]
	s_add_i32 m0, s2, 0x1a000
	s_add_u32 s72, s4, 0x40000
	s_addc_u32 s73, s5, 0
	global_load_lds_dwordx4 v142, s[4:5]
	s_add_i32 m0, s2, 0x1c000
	s_sub_u32 s34, s34, 0x40000
	s_subb_u32 s35, s35, 0
	global_load_lds_dwordx4 v138, s[72:73]
	s_add_i32 m0, s2, 0x1e000
	s_add_u32 s34, s34, 0x80
	s_addc_u32 s35, s35, 0
	global_load_lds_dwordx4 v142, s[72:73]
	s_mov_b32 m0, s60
	s_nop 0
	global_load_lds_dwordx4 v136, s[34:35]
	s_mov_b32 m0, s61
	s_nop 0
	global_load_lds_dwordx4 v140, s[34:35]
	s_waitcnt vmcnt(8)
	s_waitcnt lgkmcnt(0)
	s_setprio 1
	s_barrier
	v_mfma_f32_16x16x32_bf16 v[60:63], v[132:135], v[198:201], v[60:63]
	v_mfma_f32_16x16x32_bf16 v[56:59], v[164:167], v[198:201], v[56:59]
	v_mfma_f32_16x16x32_bf16 v[48:51], v[132:135], v[206:209], v[48:51]
	v_mfma_f32_16x16x32_bf16 v[40:43], v[164:167], v[206:209], v[40:43]
	v_mfma_f32_16x16x32_bf16 v[32:35], v[132:135], v[214:217], v[32:35]
	v_mfma_f32_16x16x32_bf16 v[24:27], v[164:167], v[214:217], v[24:27]
	v_mfma_f32_16x16x32_bf16 v[16:19], v[132:135], v[238:241], v[16:19]
	v_mfma_f32_16x16x32_bf16 v[8:11], v[164:167], v[238:241], v[8:11]
	v_mfma_f32_16x16x32_bf16 v[60:63], v[150:153], v[202:205], v[60:63]
	v_mfma_f32_16x16x32_bf16 v[56:59], v[168:171], v[202:205], v[56:59]
	v_mfma_f32_16x16x32_bf16 v[48:51], v[150:153], v[210:213], v[48:51]
	v_mfma_f32_16x16x32_bf16 v[40:43], v[168:171], v[210:213], v[40:43]
	v_mfma_f32_16x16x32_bf16 v[32:35], v[150:153], v[234:237], v[32:35]
	v_mfma_f32_16x16x32_bf16 v[24:27], v[168:171], v[234:237], v[24:27]
	v_mfma_f32_16x16x32_bf16 v[16:19], v[150:153], v[242:245], v[16:19]
	v_mfma_f32_16x16x32_bf16 v[8:11], v[168:171], v[242:245], v[8:11]
	s_setprio 0
	s_setprio 1
	v_mfma_f32_16x16x32_bf16 v[52:55], v[172:175], v[198:201], v[52:55]
	v_mfma_f32_16x16x32_bf16 v[44:47], v[190:193], v[198:201], v[44:47]
	v_mfma_f32_16x16x32_bf16 v[36:39], v[172:175], v[206:209], v[36:39]
	v_mfma_f32_16x16x32_bf16 v[28:31], v[190:193], v[206:209], v[28:31]
	v_mfma_f32_16x16x32_bf16 v[20:23], v[172:175], v[214:217], v[20:23]
	v_mfma_f32_16x16x32_bf16 v[12:15], v[190:193], v[214:217], v[12:15]
	v_mfma_f32_16x16x32_bf16 v[4:7], v[172:175], v[238:241], v[4:7]
	v_mfma_f32_16x16x32_bf16 v[0:3], v[190:193], v[238:241], v[0:3]
	v_mfma_f32_16x16x32_bf16 v[52:55], v[186:189], v[202:205], v[52:55]
	v_mfma_f32_16x16x32_bf16 v[44:47], v[194:197], v[202:205], v[44:47]
	v_mfma_f32_16x16x32_bf16 v[36:39], v[186:189], v[210:213], v[36:39]
	v_mfma_f32_16x16x32_bf16 v[28:31], v[194:197], v[210:213], v[28:31]
	v_mfma_f32_16x16x32_bf16 v[20:23], v[186:189], v[234:237], v[20:23]
	v_mfma_f32_16x16x32_bf16 v[12:15], v[194:197], v[234:237], v[12:15]
	v_mfma_f32_16x16x32_bf16 v[4:7], v[186:189], v[242:245], v[4:7]
	v_mfma_f32_16x16x32_bf16 v[0:3], v[194:197], v[242:245], v[0:3]
	s_setprio 0
	s_barrier
	s_add_i32 s70, s70, 2
	s_add_u32 s42, s42, 0x100
	s_addc_u32 s43, s43, 0
	s_cmp_gt_u32 s70, 13
.LBB0_124:
	s_add_u32 s34, s28, s42
	s_addc_u32 s35, s29, s43
	s_add_u32 s72, s34, 0x40080
	s_addc_u32 s73, s35, 0
	s_add_u32 s34, s34, 0x100
	s_addc_u32 s35, s35, 0
	s_add_u32 s4, s68, s42
	s_addc_u32 s5, s69, s43
	s_cmpk_eq_i32 s42, 0x700
	s_cselect_b32 s35, s51, s35
	s_cselect_b32 s34, s66, s34
	s_cselect_b32 s5, s49, s5
	s_cselect_b32 s4, s67, s4
	ds_read_b128 v[132:135], v154
	ds_read_b128 v[150:153], v154 offset:1024
	ds_read_b128 v[164:167], v154 offset:2048
	ds_read_b128 v[168:171], v154 offset:3072
	ds_read_b128 v[172:175], v154 offset:16384
	ds_read_b128 v[186:189], v154 offset:17408
	ds_read_b128 v[190:193], v154 offset:18432
	ds_read_b128 v[194:197], v154 offset:19456
	s_add_i32 m0, s37, 0xc000
	ds_read_b128 v[198:201], v163
	ds_read_b128 v[202:205], v163 offset:1024
	ds_read_b128 v[206:209], v163 offset:2048
	ds_read_b128 v[210:213], v163 offset:3072
	ds_read_b128 v[214:217], v163 offset:4096
	ds_read_b128 v[234:237], v163 offset:5120
	ds_read_b128 v[238:241], v163 offset:6144
	ds_read_b128 v[242:245], v163 offset:7168
	global_load_lds_dwordx4 v146, s[72:73]
	s_add_i32 m0, s37, 0xe000
	s_nop 0
	global_load_lds_dwordx4 v148, s[72:73]
	s_waitcnt vmcnt(8)
	s_waitcnt lgkmcnt(0)
	s_setprio 1
	s_barrier
; #define PG8_STAGE(bufoff, gbase, voff) do { _Pragma("unroll") for (int _i = 0; _i < 2; ++_i) \
;         __builtin_amdgcn_global_load_lds((const unsigned*)((const char*)(gbase) + (voff)[_i]), (PG8_LAS unsigned*)(lds + (bufoff) + ldsw + _i * 8192), 16, 0, 0); } while (0)
; #define PG8_LDA(dst, b, h) do { _Pragma("unroll") for (int m = 0; m < 4; ++m) _Pragma("unroll") for (int k = 0; k < 2; ++k) dst[m][k] = *(const PG8_LAS bf16x8*)(lds + PG8_SA(b, h) + aoff + m * 2048 + k * 1024); } while (0)
; #define PG8_MMA(ai, bj, At, Bt) do { __builtin_amdgcn_s_setprio(1); _Pragma("unroll") for (int m = 0; m < 4; ++m) _Pragma("unroll") for (int n = 0; n < 2; ++n) _Pragma("unroll") for (int k = 0; k < 2; ++k) \
;         acc[ai][bj][m][n] = __builtin_amdgcn_mfma_f32_16x16x32_bf16(Bt[n][k], At[m][k], acc[ai][bj][m][n], 0, 0, 0); __builtin_amdgcn_s_setprio(0); } while (0)
; #define PG8_WAIT_L(n) asm volatile("s_waitcnt lgkmcnt(" #n ")" ::: "memory")
; #define PG8_BAR __builtin_amdgcn_s_barrier()
; #define PG8_SCHED __builtin_amdgcn_sched_barrier(0)
; template <class Epi, class Sched, bool ALIGN_EPI = false, bool SP2 = false>
; __device__ __forceinline__ void gemm_phase(PG8_LAS unsigned char* lds, const Gemm g, const Sched& S, const Epi& E) {
;     ...
;             PG8_WAIT_L(0); PG8_BAR; PG8_MMA(0, 0, At, B0); PG8_MMA(0, 1, At, B1); PG8_BAR; PG8_SCHED;
;             PG8_LDA(At, 0, 1); PG8_STAGE(PG8_SB(0, 0), b2, voffB); PG8_STAGE(PG8_SB(0, 1), b2 + hstep, voffB); PG8_STAGE(PG8_SA(0, 0), a2, voffA);
;             asm volatile("s_cmp_lg_u32 %0, 0\n\ts_cbranch_scc1 .Lrelax%=\n\ts_waitcnt vmcnt(8)\n.Lrelax%=:\n\ts_waitcnt vmcnt(%1)" :: "s"(relax), "n"(8 + Epi::NST) : "memory", "scc");
;             PG8_WAIT_L(0); PG8_BAR; PG8_MMA(1, 0, At, B0); PG8_MMA(1, 1, At, B1); PG8_BAR; PG8_SCHED;
	v_mfma_f32_16x16x32_bf16 v[124:127], v[132:135], v[198:201], v[124:127]
	v_mfma_f32_16x16x32_bf16 v[120:123], v[164:167], v[198:201], v[120:123]
	v_mfma_f32_16x16x32_bf16 v[112:115], v[132:135], v[206:209], v[112:115]
	v_mfma_f32_16x16x32_bf16 v[104:107], v[164:167], v[206:209], v[104:107]
	v_mfma_f32_16x16x32_bf16 v[96:99], v[132:135], v[214:217], v[96:99]
	v_mfma_f32_16x16x32_bf16 v[88:91], v[164:167], v[214:217], v[88:91]
	v_mfma_f32_16x16x32_bf16 v[80:83], v[132:135], v[238:241], v[80:83]
	v_mfma_f32_16x16x32_bf16 v[72:75], v[164:167], v[238:241], v[72:75]
	v_mfma_f32_16x16x32_bf16 v[124:127], v[150:153], v[202:205], v[124:127]
	v_mfma_f32_16x16x32_bf16 v[120:123], v[168:171], v[202:205], v[120:123]
	v_mfma_f32_16x16x32_bf16 v[112:115], v[150:153], v[210:213], v[112:115]
	v_mfma_f32_16x16x32_bf16 v[104:107], v[168:171], v[210:213], v[104:107]
	v_mfma_f32_16x16x32_bf16 v[96:99], v[150:153], v[234:237], v[96:99]
	v_mfma_f32_16x16x32_bf16 v[88:91], v[168:171], v[234:237], v[88:91]
	v_mfma_f32_16x16x32_bf16 v[80:83], v[150:153], v[242:245], v[80:83]
	v_mfma_f32_16x16x32_bf16 v[72:75], v[168:171], v[242:245], v[72:75]
	s_setprio 0
	s_setprio 1
	v_mfma_f32_16x16x32_bf16 v[116:119], v[172:175], v[198:201], v[116:119]
	v_mfma_f32_16x16x32_bf16 v[108:111], v[190:193], v[198:201], v[108:111]
	v_mfma_f32_16x16x32_bf16 v[100:103], v[172:175], v[206:209], v[100:103]
	v_mfma_f32_16x16x32_bf16 v[92:95], v[190:193], v[206:209], v[92:95]
	v_mfma_f32_16x16x32_bf16 v[84:87], v[172:175], v[214:217], v[84:87]
	v_mfma_f32_16x16x32_bf16 v[76:79], v[190:193], v[214:217], v[76:79]
	v_mfma_f32_16x16x32_bf16 v[68:71], v[172:175], v[238:241], v[68:71]
	v_mfma_f32_16x16x32_bf16 v[64:67], v[190:193], v[238:241], v[64:67]
	v_mfma_f32_16x16x32_bf16 v[116:119], v[186:189], v[202:205], v[116:119]
	v_mfma_f32_16x16x32_bf16 v[108:111], v[194:197], v[202:205], v[108:111]
	v_mfma_f32_16x16x32_bf16 v[100:103], v[186:189], v[210:213], v[100:103]
	v_mfma_f32_16x16x32_bf16 v[92:95], v[194:197], v[210:213], v[92:95]
	v_mfma_f32_16x16x32_bf16 v[84:87], v[186:189], v[234:237], v[84:87]
	v_mfma_f32_16x16x32_bf16 v[76:79], v[194:197], v[234:237], v[76:79]
	v_mfma_f32_16x16x32_bf16 v[68:71], v[186:189], v[242:245], v[68:71]
	v_mfma_f32_16x16x32_bf16 v[64:67], v[194:197], v[242:245], v[64:67]
	s_setprio 0
	s_barrier
	s_add_i32 m0, s2, 0x10000
	ds_read_b128 v[198:201], v163 offset:16384
	ds_read_b128 v[202:205], v163 offset:17408
	ds_read_b128 v[206:209], v163 offset:18432
	ds_read_b128 v[210:213], v163 offset:19456
	ds_read_b128 v[214:217], v163 offset:20480
	ds_read_b128 v[234:237], v163 offset:21504
	ds_read_b128 v[238:241], v163 offset:22528
	ds_read_b128 v[242:245], v163 offset:23552
	global_load_lds_dwordx4 v138, s[4:5]
	s_add_i32 m0, s2, 0x12000
	s_add_u32 s72, s4, 0x40000
	s_addc_u32 s73, s5, 0
	global_load_lds_dwordx4 v142, s[4:5]
	s_add_i32 m0, s2, 0x14000
	s_nop 0
	global_load_lds_dwordx4 v138, s[72:73]
	s_add_i32 m0, s2, 0x16000
	s_nop 0
	global_load_lds_dwordx4 v142, s[72:73]
	s_mov_b32 m0, s37
	s_nop 0
	global_load_lds_dwordx4 v136, s[34:35]
	s_mov_b32 m0, s57
	s_nop 0
	global_load_lds_dwordx4 v140, s[34:35]
	s_waitcnt vmcnt(8)
	s_waitcnt lgkmcnt(0)
	s_setprio 1
	s_barrier
	v_mfma_f32_16x16x32_bf16 v[60:63], v[132:135], v[198:201], v[60:63]
	v_mfma_f32_16x16x32_bf16 v[56:59], v[164:167], v[198:201], v[56:59]
	v_mfma_f32_16x16x32_bf16 v[48:51], v[132:135], v[206:209], v[48:51]
	v_mfma_f32_16x16x32_bf16 v[40:43], v[164:167], v[206:209], v[40:43]
	v_mfma_f32_16x16x32_bf16 v[32:35], v[132:135], v[214:217], v[32:35]
	v_mfma_f32_16x16x32_bf16 v[24:27], v[164:167], v[214:217], v[24:27]
	v_mfma_f32_16x16x32_bf16 v[16:19], v[132:135], v[238:241], v[16:19]
	v_mfma_f32_16x16x32_bf16 v[8:11], v[164:167], v[238:241], v[8:11]
	v_mfma_f32_16x16x32_bf16 v[60:63], v[150:153], v[202:205], v[60:63]
	v_mfma_f32_16x16x32_bf16 v[56:59], v[168:171], v[202:205], v[56:59]
	v_mfma_f32_16x16x32_bf16 v[48:51], v[150:153], v[210:213], v[48:51]
	v_mfma_f32_16x16x32_bf16 v[40:43], v[168:171], v[210:213], v[40:43]
	v_mfma_f32_16x16x32_bf16 v[32:35], v[150:153], v[234:237], v[32:35]
	v_mfma_f32_16x16x32_bf16 v[24:27], v[168:171], v[234:237], v[24:27]
	v_mfma_f32_16x16x32_bf16 v[16:19], v[150:153], v[242:245], v[16:19]
	v_mfma_f32_16x16x32_bf16 v[8:11], v[168:171], v[242:245], v[8:11]
	s_setprio 0
	s_setprio 1
	v_mfma_f32_16x16x32_bf16 v[52:55], v[172:175], v[198:201], v[52:55]
	v_mfma_f32_16x16x32_bf16 v[44:47], v[190:193], v[198:201], v[44:47]
	v_mfma_f32_16x16x32_bf16 v[36:39], v[172:175], v[206:209], v[36:39]
	v_mfma_f32_16x16x32_bf16 v[28:31], v[190:193], v[206:209], v[28:31]
	v_mfma_f32_16x16x32_bf16 v[20:23], v[172:175], v[214:217], v[20:23]
	v_mfma_f32_16x16x32_bf16 v[12:15], v[190:193], v[214:217], v[12:15]
	v_mfma_f32_16x16x32_bf16 v[4:7], v[172:175], v[238:241], v[4:7]
	v_mfma_f32_16x16x32_bf16 v[0:3], v[190:193], v[238:241], v[0:3]
	v_mfma_f32_16x16x32_bf16 v[52:55], v[186:189], v[202:205], v[52:55]
	v_mfma_f32_16x16x32_bf16 v[44:47], v[194:197], v[202:205], v[44:47]
	v_mfma_f32_16x16x32_bf16 v[36:39], v[186:189], v[210:213], v[36:39]
	v_mfma_f32_16x16x32_bf16 v[28:31], v[194:197], v[210:213], v[28:31]
	v_mfma_f32_16x16x32_bf16 v[20:23], v[186:189], v[234:237], v[20:23]
	v_mfma_f32_16x16x32_bf16 v[12:15], v[194:197], v[234:237], v[12:15]
	v_mfma_f32_16x16x32_bf16 v[4:7], v[186:189], v[242:245], v[4:7]
	v_mfma_f32_16x16x32_bf16 v[0:3], v[194:197], v[242:245], v[0:3]
	s_setprio 0
	s_barrier
; #define PG8_STAGE(bufoff, gbase, voff) do { _Pragma("unroll") for (int _i = 0; _i < 2; ++_i) \
;         __builtin_amdgcn_global_load_lds((const unsigned*)((const char*)(gbase) + (voff)[_i]), (PG8_LAS unsigned*)(lds + (bufoff) + ldsw + _i * 8192), 16, 0, 0); } while (0)
; #define PG8_LDA(dst, b, h) do { _Pragma("unroll") for (int m = 0; m < 4; ++m) _Pragma("unroll") for (int k = 0; k < 2; ++k) dst[m][k] = *(const PG8_LAS bf16x8*)(lds + PG8_SA(b, h) + aoff + m * 2048 + k * 1024); } while (0)
; #define PG8_LDB(dst, b, h) do { _Pragma("unroll") for (int n = 0; n < 2; ++n) _Pragma("unroll") for (int k = 0; k < 2; ++k) dst[n][k] = *(const PG8_LAS bf16x8*)(lds + PG8_SB(b, h) + boff + n * 2048 + k * 1024); } while (0)
; #define PG8_MMA(ai, bj, At, Bt) do { __builtin_amdgcn_s_setprio(1); _Pragma("unroll") for (int m = 0; m < 4; ++m) _Pragma("unroll") for (int n = 0; n < 2; ++n) _Pragma("unroll") for (int k = 0; k < 2; ++k) \
;         acc[ai][bj][m][n] = __builtin_amdgcn_mfma_f32_16x16x32_bf16(Bt[n][k], At[m][k], acc[ai][bj][m][n], 0, 0, 0); __builtin_amdgcn_s_setprio(0); } while (0)
; #define PG8_WAIT_V(n) asm volatile("s_waitcnt vmcnt(" #n ")" ::: "memory")
; #define PG8_WAIT_L(n) asm volatile("s_waitcnt lgkmcnt(" #n ")" ::: "memory")
; #define PG8_BAR __builtin_amdgcn_s_barrier()
; #define PG8_SCHED __builtin_amdgcn_sched_barrier(0)
; template <class Epi, class Sched, bool ALIGN_EPI = false, bool SP2 = false>
; __device__ __forceinline__ void gemm_phase(PG8_LAS unsigned char* lds, const Gemm g, const Sched& S, const Epi& E) {
;     ...
;             PG8_LDB(B0, 1, 0); PG8_LDB(B1, 1, 1); PG8_SCHED; PG8_LDA(At, 1, 0); PG8_STAGE(PG8_SA(0, 1), a2 + hstep, voffA);
;             PG8_WAIT_V(8); PG8_WAIT_L(0); PG8_BAR; PG8_MMA(0, 0, At, B0); PG8_MMA(0, 1, At, B1); PG8_BAR; PG8_SCHED;
;             PG8_LDA(At, 1, 1); PG8_STAGE(PG8_SB(1, 0), b3, voffB); PG8_STAGE(PG8_SB(1, 1), b3 + hstep, voffB); PG8_STAGE(PG8_SA(1, 0), a3, voffA);
;             PG8_WAIT_V(8); PG8_WAIT_L(0); PG8_BAR; PG8_MMA(1, 0, At, B0); PG8_MMA(1, 1, At, B1); PG8_BAR; PG8_SCHED;
	ds_read_b128 v[132:135], v154 offset:32768
	ds_read_b128 v[150:153], v154 offset:33792
	ds_read_b128 v[164:167], v154 offset:34816
	ds_read_b128 v[168:171], v154 offset:35840
	ds_read_b128 v[172:175], v154 offset:49152
	ds_read_b128 v[186:189], v154 offset:50176
	ds_read_b128 v[190:193], v154 offset:51200
	ds_read_b128 v[194:197], v154 offset:52224
	s_add_u32 s34, s34, 0x40000
	s_addc_u32 s35, s35, 0
	s_mov_b32 m0, s58
	ds_read_b128 v[198:201], v163 offset:32768
	ds_read_b128 v[202:205], v163 offset:33792
	ds_read_b128 v[206:209], v163 offset:34816
	ds_read_b128 v[210:213], v163 offset:35840
	ds_read_b128 v[214:217], v163 offset:36864
	ds_read_b128 v[234:237], v163 offset:37888
	ds_read_b128 v[238:241], v163 offset:38912
	ds_read_b128 v[242:245], v163 offset:39936
	global_load_lds_dwordx4 v136, s[34:35]
	s_mov_b32 m0, s59
	s_nop 0
	global_load_lds_dwordx4 v140, s[34:35]
	s_waitcnt vmcnt(8)
	s_waitcnt lgkmcnt(0)
	s_setprio 1
	s_barrier
	v_mfma_f32_16x16x32_bf16 v[124:127], v[132:135], v[198:201], v[124:127]
	v_mfma_f32_16x16x32_bf16 v[120:123], v[164:167], v[198:201], v[120:123]
	v_mfma_f32_16x16x32_bf16 v[112:115], v[132:135], v[206:209], v[112:115]
	v_mfma_f32_16x16x32_bf16 v[104:107], v[164:167], v[206:209], v[104:107]
	v_mfma_f32_16x16x32_bf16 v[96:99], v[132:135], v[214:217], v[96:99]
	v_mfma_f32_16x16x32_bf16 v[88:91], v[164:167], v[214:217], v[88:91]
	v_mfma_f32_16x16x32_bf16 v[80:83], v[132:135], v[238:241], v[80:83]
	v_mfma_f32_16x16x32_bf16 v[72:75], v[164:167], v[238:241], v[72:75]
	v_mfma_f32_16x16x32_bf16 v[124:127], v[150:153], v[202:205], v[124:127]
	v_mfma_f32_16x16x32_bf16 v[120:123], v[168:171], v[202:205], v[120:123]
	v_mfma_f32_16x16x32_bf16 v[112:115], v[150:153], v[210:213], v[112:115]
	v_mfma_f32_16x16x32_bf16 v[104:107], v[168:171], v[210:213], v[104:107]
	v_mfma_f32_16x16x32_bf16 v[96:99], v[150:153], v[234:237], v[96:99]
	v_mfma_f32_16x16x32_bf16 v[88:91], v[168:171], v[234:237], v[88:91]
	v_mfma_f32_16x16x32_bf16 v[80:83], v[150:153], v[242:245], v[80:83]
	v_mfma_f32_16x16x32_bf16 v[72:75], v[168:171], v[242:245], v[72:75]
	s_setprio 0
	s_setprio 1
	v_mfma_f32_16x16x32_bf16 v[116:119], v[172:175], v[198:201], v[116:119]
	v_mfma_f32_16x16x32_bf16 v[108:111], v[190:193], v[198:201], v[108:111]
	v_mfma_f32_16x16x32_bf16 v[100:103], v[172:175], v[206:209], v[100:103]
	v_mfma_f32_16x16x32_bf16 v[92:95], v[190:193], v[206:209], v[92:95]
	v_mfma_f32_16x16x32_bf16 v[84:87], v[172:175], v[214:217], v[84:87]
	v_mfma_f32_16x16x32_bf16 v[76:79], v[190:193], v[214:217], v[76:79]
	v_mfma_f32_16x16x32_bf16 v[68:71], v[172:175], v[238:241], v[68:71]
	v_mfma_f32_16x16x32_bf16 v[64:67], v[190:193], v[238:241], v[64:67]
	v_mfma_f32_16x16x32_bf16 v[116:119], v[186:189], v[202:205], v[116:119]
	v_mfma_f32_16x16x32_bf16 v[108:111], v[194:197], v[202:205], v[108:111]
	v_mfma_f32_16x16x32_bf16 v[100:103], v[186:189], v[210:213], v[100:103]
	v_mfma_f32_16x16x32_bf16 v[92:95], v[194:197], v[210:213], v[92:95]
	v_mfma_f32_16x16x32_bf16 v[84:87], v[186:189], v[234:237], v[84:87]
	v_mfma_f32_16x16x32_bf16 v[76:79], v[194:197], v[234:237], v[76:79]
	v_mfma_f32_16x16x32_bf16 v[68:71], v[186:189], v[242:245], v[68:71]
	v_mfma_f32_16x16x32_bf16 v[64:67], v[194:197], v[242:245], v[64:67]
	s_setprio 0
	s_barrier
	s_add_i32 m0, s2, 0x18000
	s_add_u32 s4, s4, 0x80
	s_addc_u32 s5, s5, 0
	ds_read_b128 v[198:201], v163 offset:49152
	ds_read_b128 v[202:205], v163 offset:50176
	ds_read_b128 v[206:209], v163 offset:51200
	ds_read_b128 v[210:213], v163 offset:52224
	ds_read_b128 v[214:217], v163 offset:53248
	ds_read_b128 v[234:237], v163 offset:54272
	ds_read_b128 v[238:241], v163 offset:55296
	ds_read_b128 v[242:245], v163 offset:56320
	global_load_lds_dwordx4 v138, s[4:5]
	s_add_i32 m0, s2, 0x1a000
	s_add_u32 s72, s4, 0x40000
	s_addc_u32 s73, s5, 0
	global_load_lds_dwordx4 v142, s[4:5]
	s_add_i32 m0, s2, 0x1c000
	s_sub_u32 s34, s34, 0x40000
	s_subb_u32 s35, s35, 0
	global_load_lds_dwordx4 v138, s[72:73]
	s_add_i32 m0, s2, 0x1e000
	s_add_u32 s34, s34, 0x80
	s_addc_u32 s35, s35, 0
	global_load_lds_dwordx4 v142, s[72:73]
	s_mov_b32 m0, s60
	s_nop 0
	global_load_lds_dwordx4 v136, s[34:35]
	s_mov_b32 m0, s61
	s_nop 0
	global_load_lds_dwordx4 v140, s[34:35]
	s_waitcnt vmcnt(8)
	s_waitcnt lgkmcnt(0)
	s_setprio 1
	s_barrier
	v_mfma_f32_16x16x32_bf16 v[60:63], v[132:135], v[198:201], v[60:63]
	v_mfma_f32_16x16x32_bf16 v[56:59], v[164:167], v[198:201], v[56:59]
	v_mfma_f32_16x16x32_bf16 v[48:51], v[132:135], v[206:209], v[48:51]
	v_mfma_f32_16x16x32_bf16 v[40:43], v[164:167], v[206:209], v[40:43]
	v_mfma_f32_16x16x32_bf16 v[32:35], v[132:135], v[214:217], v[32:35]
	v_mfma_f32_16x16x32_bf16 v[24:27], v[164:167], v[214:217], v[24:27]
	v_mfma_f32_16x16x32_bf16 v[16:19], v[132:135], v[238:241], v[16:19]
	v_mfma_f32_16x16x32_bf16 v[8:11], v[164:167], v[238:241], v[8:11]
	v_mfma_f32_16x16x32_bf16 v[60:63], v[150:153], v[202:205], v[60:63]
	v_mfma_f32_16x16x32_bf16 v[56:59], v[168:171], v[202:205], v[56:59]
	v_mfma_f32_16x16x32_bf16 v[48:51], v[150:153], v[210:213], v[48:51]
	v_mfma_f32_16x16x32_bf16 v[40:43], v[168:171], v[210:213], v[40:43]
	v_mfma_f32_16x16x32_bf16 v[32:35], v[150:153], v[234:237], v[32:35]
	v_mfma_f32_16x16x32_bf16 v[24:27], v[168:171], v[234:237], v[24:27]
	v_mfma_f32_16x16x32_bf16 v[16:19], v[150:153], v[242:245], v[16:19]
	v_mfma_f32_16x16x32_bf16 v[8:11], v[168:171], v[242:245], v[8:11]
	s_setprio 0
	s_setprio 1
	v_mfma_f32_16x16x32_bf16 v[52:55], v[172:175], v[198:201], v[52:55]
	v_mfma_f32_16x16x32_bf16 v[44:47], v[190:193], v[198:201], v[44:47]
	v_mfma_f32_16x16x32_bf16 v[36:39], v[172:175], v[206:209], v[36:39]
	v_mfma_f32_16x16x32_bf16 v[28:31], v[190:193], v[206:209], v[28:31]
	v_mfma_f32_16x16x32_bf16 v[20:23], v[172:175], v[214:217], v[20:23]
	v_mfma_f32_16x16x32_bf16 v[12:15], v[190:193], v[214:217], v[12:15]
	v_mfma_f32_16x16x32_bf16 v[4:7], v[172:175], v[238:241], v[4:7]
	v_mfma_f32_16x16x32_bf16 v[0:3], v[190:193], v[238:241], v[0:3]
	v_mfma_f32_16x16x32_bf16 v[52:55], v[186:189], v[202:205], v[52:55]
	v_mfma_f32_16x16x32_bf16 v[44:47], v[194:197], v[202:205], v[44:47]
	v_mfma_f32_16x16x32_bf16 v[36:39], v[186:189], v[210:213], v[36:39]
	v_mfma_f32_16x16x32_bf16 v[28:31], v[194:197], v[210:213], v[28:31]
	v_mfma_f32_16x16x32_bf16 v[20:23], v[186:189], v[234:237], v[20:23]
	v_mfma_f32_16x16x32_bf16 v[12:15], v[194:197], v[234:237], v[12:15]
	v_mfma_f32_16x16x32_bf16 v[4:7], v[186:189], v[242:245], v[4:7]
	v_mfma_f32_16x16x32_bf16 v[0:3], v[194:197], v[242:245], v[0:3]
	s_setprio 0
	s_barrier
	s_add_i32 s70, s70, 2
	s_add_u32 s42, s42, 0x100
	s_addc_u32 s43, s43, 0
	s_cmp_gt_u32 s70, 13
	s_cbranch_scc0 .LBB0_124

; #define PG8_STAGE(bufoff, gbase, voff) do { _Pragma("unroll") for (int _i = 0; _i < 2; ++_i) \
;         __builtin_amdgcn_global_load_lds((const unsigned*)((const char*)(gbase) + (voff)[_i]), (PG8_LAS unsigned*)(lds + (bufoff) + ldsw + _i * 8192), 16, 0, 0); } while (0)
; #define PG8_LDA(dst, b, h) do { _Pragma("unroll") for (int m = 0; m < 4; ++m) _Pragma("unroll") for (int k = 0; k < 2; ++k) dst[m][k] = *(const PG8_LAS bf16x8*)(lds + PG8_SA(b, h) + aoff + m * 2048 + k * 1024); } while (0)
; #define PG8_WAIT_L(n) asm volatile("s_waitcnt lgkmcnt(" #n ")" ::: "memory")
; #define PG8_BAR __builtin_amdgcn_s_barrier()
; #define PG8_SCHED __builtin_amdgcn_sched_barrier(0)
; template <class Epi, class Sched, bool ALIGN_EPI = false, bool SP2 = false>
; __device__ __forceinline__ void gemm_phase(PG8_LAS unsigned char* lds, const Gemm g, const Sched& S, const Epi& E) {
;     ...
;         const bool has_next = S.next(ui + 1, nxt);
;         const char* nA = has_next ? (const char*)g.A + (size_t)nxt.pm * tstep : cA; const char* nB = has_next ? (const char*)g.Bt + (size_t)nxt.pn * tstep : cB;
;         for (int t = 0; t < nt; t += 2) {
;             const bool last = (t == nt - 2);
;             const char* a1 = cA + (size_t)(t + 1) * kstep;
;             const char* a2 = last ? nA : cA + (size_t)(t + 2) * kstep; const char* b2 = last ? nB : cB + (size_t)(t + 2) * kstep;
;             const char* a3 = a2 + kstep; const char* b3 = b2 + kstep;
;             if (last && has_next) S.a_ready(nxt);
;             if constexpr (SP2) {
;             const int relax = __builtin_amdgcn_readfirstlane((t == 0 && ui > 0) ? 1 : 0);
;             PG8_LDB(B0, 0, 0); PG8_LDB(B1, 0, 1); PG8_SCHED; PG8_LDA(At, 0, 0); PG8_STAGE(PG8_SA(1, 1), a1 + hstep, voffA);
;             asm volatile("s_cmp_lg_u32 %0, 0\n\ts_cbranch_scc1 .Lrelax%=\n\ts_waitcnt vmcnt(8)\n.Lrelax%=:\n\ts_waitcnt vmcnt(%1)" :: "s"(relax), "n"(8 + Epi::NST) : "memory", "scc");
;             PG8_WAIT_L(0); PG8_BAR; PG8_MMA(0, 0, At, B0); PG8_MMA(0, 1, At, B1); PG8_BAR; PG8_SCHED;
;             PG8_LDA(At, 0, 1); PG8_STAGE(PG8_SB(0, 0), b2, voffB); PG8_STAGE(PG8_SB(0, 1), b2 + hstep, voffB); PG8_STAGE(PG8_SA(0, 0), a2, voffA);
;             asm volatile("s_cmp_lg_u32 %0, 0\n\ts_cbranch_scc1 .Lrelax%=\n\ts_waitcnt vmcnt(8)\n.Lrelax%=:\n\ts_waitcnt vmcnt(%1)" :: "s"(relax), "n"(8 + Epi::NST) : "memory", "scc");
.LBB0_155:
	s_ashr_i32 s51, s50, 31
	s_lshl_b64 s[30:31], s[50:51], 19
	s_add_u32 s52, s82, s30
	s_addc_u32 s53, s83, s31
	s_and_b64 s[30:31], s[42:43], exec
	s_cselect_b32 s51, s53, s29
	s_cselect_b32 s65, s52, s28
	s_ashr_i32 s49, s48, 31
	s_lshl_b64 s[30:31], s[48:49], 19
	s_add_u32 s54, s78, s30
	s_addc_u32 s55, s79, s31
	s_and_b64 s[30:31], s[42:43], exec
	s_cselect_b32 s49, s55, s5
	s_cselect_b32 s66, s54, s4
	s_cmp_lg_u32 s64, 0
	s_cselect_b64 s[30:31], -1, 0
	s_add_u32 s34, s28, 0x40080
	s_addc_u32 s35, s29, 0
	s_add_u32 s67, s4, 0x100
	v_lshl_add_u64 v[56:57], s[34:35], 0, v[160:161]
	v_lshl_add_u64 v[58:59], s[34:35], 0, v[162:163]
	s_addc_u32 s68, s5, 0
	s_mov_b32 s69, -2
	s_mov_b64 s[40:41], 0
	v_add_u32_e32 v242, 0x10000, v189
	s_add_u32 s34, s28, s40
	s_addc_u32 s35, s29, s41
	s_add_u32 s70, s34, 0x40080
	s_addc_u32 s71, s35, 0
	s_add_u32 s34, s34, 0x100
	s_addc_u32 s35, s35, 0
	s_add_u32 s4, s67, s40
	s_addc_u32 s5, s68, s41
	s_cmpk_eq_i32 s40, 0x700
	s_cselect_b32 s35, s51, s35
	s_cselect_b32 s34, s65, s34
	s_cselect_b32 s5, s49, s5
	s_cselect_b32 s4, s66, s4
	ds_read_b128 v[60:63], v242
	ds_read_b128 v[68:71], v242 offset:1024
	ds_read_b128 v[76:79], v242 offset:2048
	ds_read_b128 v[80:83], v242 offset:3072
	ds_read_b128 v[88:91], v242 offset:16384
	ds_read_b128 v[164:167], v242 offset:17408
	ds_read_b128 v[168:171], v242 offset:18432
	ds_read_b128 v[172:175], v242 offset:19456
	s_add_i32 m0, s37, 0xc000
	ds_read_b128 v[194:197], v193
	ds_read_b128 v[198:201], v193 offset:1024
	ds_read_b128 v[202:205], v193 offset:2048
	ds_read_b128 v[206:209], v193 offset:3072
	ds_read_b128 v[210:213], v193 offset:4096
	ds_read_b128 v[214:217], v193 offset:5120
	ds_read_b128 v[234:237], v193 offset:6144
	ds_read_b128 v[238:241], v193 offset:7168
	global_load_lds_dwordx4 v160, s[70:71]
	s_add_i32 m0, s37, 0xe000
	s_nop 0
	global_load_lds_dwordx4 v162, s[70:71]
	s_cmp_lg_u32 s30, 0
	s_cbranch_scc1 .Lmy_glup_rx1
	s_waitcnt vmcnt(8)
.Lmy_glup_rx1:
	s_waitcnt vmcnt(16)
	s_waitcnt lgkmcnt(0)
	s_setprio 1
	s_barrier
	v_mfma_f32_16x16x32_bf16 v[148:151], v[60:63], v[194:197], 0
	v_mfma_f32_16x16x32_bf16 v[144:147], v[76:79], v[194:197], 0
	v_mfma_f32_16x16x32_bf16 v[132:135], v[60:63], v[202:205], 0
	v_mfma_f32_16x16x32_bf16 v[124:127], v[76:79], v[202:205], 0
	v_mfma_f32_16x16x32_bf16 v[116:119], v[60:63], v[210:213], 0
	v_mfma_f32_16x16x32_bf16 v[108:111], v[76:79], v[210:213], 0
	v_mfma_f32_16x16x32_bf16 v[100:103], v[60:63], v[234:237], 0
	v_mfma_f32_16x16x32_bf16 v[92:95], v[76:79], v[234:237], 0
	v_mfma_f32_16x16x32_bf16 v[148:151], v[68:71], v[198:201], v[148:151]
	v_mfma_f32_16x16x32_bf16 v[144:147], v[80:83], v[198:201], v[144:147]
	v_mfma_f32_16x16x32_bf16 v[132:135], v[68:71], v[206:209], v[132:135]
	v_mfma_f32_16x16x32_bf16 v[124:127], v[80:83], v[206:209], v[124:127]
	v_mfma_f32_16x16x32_bf16 v[116:119], v[68:71], v[214:217], v[116:119]
	v_mfma_f32_16x16x32_bf16 v[108:111], v[80:83], v[214:217], v[108:111]
	v_mfma_f32_16x16x32_bf16 v[100:103], v[68:71], v[238:241], v[100:103]
	v_mfma_f32_16x16x32_bf16 v[92:95], v[80:83], v[238:241], v[92:95]
	s_setprio 0
	s_setprio 1
	v_mfma_f32_16x16x32_bf16 v[140:143], v[88:91], v[194:197], 0
	v_mfma_f32_16x16x32_bf16 v[136:139], v[168:171], v[194:197], 0
	v_mfma_f32_16x16x32_bf16 v[128:131], v[88:91], v[202:205], 0
	v_mfma_f32_16x16x32_bf16 v[120:123], v[168:171], v[202:205], 0
	v_mfma_f32_16x16x32_bf16 v[112:115], v[88:91], v[210:213], 0
	v_mfma_f32_16x16x32_bf16 v[104:107], v[168:171], v[210:213], 0
	v_mfma_f32_16x16x32_bf16 v[96:99], v[88:91], v[234:237], 0
	v_mfma_f32_16x16x32_bf16 v[84:87], v[168:171], v[234:237], 0
	v_mfma_f32_16x16x32_bf16 v[140:143], v[164:167], v[198:201], v[140:143]
	v_mfma_f32_16x16x32_bf16 v[136:139], v[172:175], v[198:201], v[136:139]
	v_mfma_f32_16x16x32_bf16 v[128:131], v[164:167], v[206:209], v[128:131]
	v_mfma_f32_16x16x32_bf16 v[120:123], v[172:175], v[206:209], v[120:123]
	v_mfma_f32_16x16x32_bf16 v[112:115], v[164:167], v[214:217], v[112:115]
	v_mfma_f32_16x16x32_bf16 v[104:107], v[172:175], v[214:217], v[104:107]
	v_mfma_f32_16x16x32_bf16 v[96:99], v[164:167], v[238:241], v[96:99]
	v_mfma_f32_16x16x32_bf16 v[84:87], v[172:175], v[238:241], v[84:87]
	s_setprio 0
	s_barrier
	s_add_i32 m0, s2, 0x10000
	ds_read_b128 v[194:197], v193 offset:16384
	ds_read_b128 v[198:201], v193 offset:17408
	ds_read_b128 v[202:205], v193 offset:18432
	ds_read_b128 v[206:209], v193 offset:19456
	ds_read_b128 v[210:213], v193 offset:20480
	ds_read_b128 v[214:217], v193 offset:21504
	ds_read_b128 v[234:237], v193 offset:22528
	ds_read_b128 v[238:241], v193 offset:23552
	global_load_lds_dwordx4 v176, s[4:5]
	s_add_i32 m0, s2, 0x12000
	s_add_u32 s70, s4, 0x40000
	s_addc_u32 s71, s5, 0
	global_load_lds_dwordx4 v156, s[4:5]
	s_add_i32 m0, s2, 0x14000
	s_nop 0
	global_load_lds_dwordx4 v176, s[70:71]
	s_add_i32 m0, s2, 0x16000
	s_nop 0
	global_load_lds_dwordx4 v156, s[70:71]
	s_mov_b32 m0, s37
	s_nop 0
	global_load_lds_dwordx4 v152, s[34:35]
	s_mov_b32 m0, s57
	s_nop 0
	global_load_lds_dwordx4 v154, s[34:35]
	s_cmp_lg_u32 s30, 0
	s_cbranch_scc1 .Lmy_glup_rx2
	s_waitcnt vmcnt(8)
; #define PG8_STAGE(bufoff, gbase, voff) do { _Pragma("unroll") for (int _i = 0; _i < 2; ++_i) \
;         __builtin_amdgcn_global_load_lds((const unsigned*)((const char*)(gbase) + (voff)[_i]), (PG8_LAS unsigned*)(lds + (bufoff) + ldsw + _i * 8192), 16, 0, 0); } while (0)
; #define PG8_LDA(dst, b, h) do { _Pragma("unroll") for (int m = 0; m < 4; ++m) _Pragma("unroll") for (int k = 0; k < 2; ++k) dst[m][k] = *(const PG8_LAS bf16x8*)(lds + PG8_SA(b, h) + aoff + m * 2048 + k * 1024); } while (0)
; #define PG8_LDB(dst, b, h) do { _Pragma("unroll") for (int n = 0; n < 2; ++n) _Pragma("unroll") for (int k = 0; k < 2; ++k) dst[n][k] = *(const PG8_LAS bf16x8*)(lds + PG8_SB(b, h) + boff + n * 2048 + k * 1024); } while (0)
; #define PG8_MMA(ai, bj, At, Bt) do { __builtin_amdgcn_s_setprio(1); _Pragma("unroll") for (int m = 0; m < 4; ++m) _Pragma("unroll") for (int n = 0; n < 2; ++n) _Pragma("unroll") for (int k = 0; k < 2; ++k) \
;         acc[ai][bj][m][n] = __builtin_amdgcn_mfma_f32_16x16x32_bf16(Bt[n][k], At[m][k], acc[ai][bj][m][n], 0, 0, 0); __builtin_amdgcn_s_setprio(0); } while (0)
; #define PG8_WAIT_V(n) asm volatile("s_waitcnt vmcnt(" #n ")" ::: "memory")
; #define PG8_WAIT_L(n) asm volatile("s_waitcnt lgkmcnt(" #n ")" ::: "memory")
; #define PG8_BAR __builtin_amdgcn_s_barrier()
; #define PG8_SCHED __builtin_amdgcn_sched_barrier(0)
; template <class Epi, class Sched, bool ALIGN_EPI = false, bool SP2 = false>
; __device__ __forceinline__ void gemm_phase(PG8_LAS unsigned char* lds, const Gemm g, const Sched& S, const Epi& E) {
;     ...
;             asm volatile("s_cmp_lg_u32 %0, 0\n\ts_cbranch_scc1 .Lrelax%=\n\ts_waitcnt vmcnt(8)\n.Lrelax%=:\n\ts_waitcnt vmcnt(%1)" :: "s"(relax), "n"(8 + Epi::NST) : "memory", "scc");
;             PG8_WAIT_L(0); PG8_BAR; PG8_MMA(1, 0, At, B0); PG8_MMA(1, 1, At, B1); PG8_BAR; PG8_SCHED;
;             PG8_LDB(B0, 1, 0); PG8_LDB(B1, 1, 1); PG8_SCHED; PG8_LDA(At, 1, 0); PG8_STAGE(PG8_SA(0, 1), a2 + hstep, voffA);
;             PG8_WAIT_V(8); PG8_WAIT_L(0); PG8_BAR; PG8_MMA(0, 0, At, B0); PG8_MMA(0, 1, At, B1); PG8_BAR; PG8_SCHED;
.Lmy_glup_rx2:
	s_waitcnt vmcnt(16)
	s_waitcnt lgkmcnt(0)
	s_setprio 1
	s_barrier
	v_mfma_f32_16x16x32_bf16 v[72:75], v[60:63], v[194:197], 0
	v_mfma_f32_16x16x32_bf16 v[52:55], v[76:79], v[194:197], 0
	v_mfma_f32_16x16x32_bf16 v[44:47], v[60:63], v[202:205], 0
	v_mfma_f32_16x16x32_bf16 v[36:39], v[76:79], v[202:205], 0
	v_mfma_f32_16x16x32_bf16 v[28:31], v[60:63], v[210:213], 0
	v_mfma_f32_16x16x32_bf16 v[20:23], v[76:79], v[210:213], 0
	v_mfma_f32_16x16x32_bf16 v[12:15], v[60:63], v[234:237], 0
	v_mfma_f32_16x16x32_bf16 v[4:7], v[76:79], v[234:237], 0
	v_mfma_f32_16x16x32_bf16 v[72:75], v[68:71], v[198:201], v[72:75]
	v_mfma_f32_16x16x32_bf16 v[52:55], v[80:83], v[198:201], v[52:55]
	v_mfma_f32_16x16x32_bf16 v[44:47], v[68:71], v[206:209], v[44:47]
	v_mfma_f32_16x16x32_bf16 v[36:39], v[80:83], v[206:209], v[36:39]
	v_mfma_f32_16x16x32_bf16 v[28:31], v[68:71], v[214:217], v[28:31]
	v_mfma_f32_16x16x32_bf16 v[20:23], v[80:83], v[214:217], v[20:23]
	v_mfma_f32_16x16x32_bf16 v[12:15], v[68:71], v[238:241], v[12:15]
	v_mfma_f32_16x16x32_bf16 v[4:7], v[80:83], v[238:241], v[4:7]
	s_setprio 0
	s_setprio 1
	v_mfma_f32_16x16x32_bf16 v[48:51], v[168:171], v[194:197], 0
	v_mfma_f32_16x16x32_bf16 v[40:43], v[88:91], v[202:205], 0
	v_mfma_f32_16x16x32_bf16 v[32:35], v[168:171], v[202:205], 0
	v_mfma_f32_16x16x32_bf16 v[24:27], v[88:91], v[210:213], 0
	v_mfma_f32_16x16x32_bf16 v[16:19], v[168:171], v[210:213], 0
	v_mfma_f32_16x16x32_bf16 v[8:11], v[88:91], v[234:237], 0
	v_mfma_f32_16x16x32_bf16 v[0:3], v[168:171], v[234:237], 0
	v_mfma_f32_16x16x32_bf16 v[60:63], v[88:91], v[194:197], 0
	v_mfma_f32_16x16x32_bf16 v[48:51], v[172:175], v[198:201], v[48:51]
	v_mfma_f32_16x16x32_bf16 v[40:43], v[164:167], v[206:209], v[40:43]
	v_mfma_f32_16x16x32_bf16 v[32:35], v[172:175], v[206:209], v[32:35]
	v_mfma_f32_16x16x32_bf16 v[24:27], v[164:167], v[214:217], v[24:27]
	v_mfma_f32_16x16x32_bf16 v[16:19], v[172:175], v[214:217], v[16:19]
	v_mfma_f32_16x16x32_bf16 v[8:11], v[164:167], v[238:241], v[8:11]
	v_mfma_f32_16x16x32_bf16 v[0:3], v[172:175], v[238:241], v[0:3]
	v_mfma_f32_16x16x32_bf16 v[60:63], v[164:167], v[198:201], v[60:63]
	s_setprio 0
	s_barrier
	ds_read_b128 v[64:67], v242 offset:32768
	ds_read_b128 v[68:71], v242 offset:33792
	ds_read_b128 v[76:79], v242 offset:34816
	ds_read_b128 v[80:83], v242 offset:35840
	ds_read_b128 v[88:91], v242 offset:49152
	ds_read_b128 v[164:167], v242 offset:50176
	ds_read_b128 v[168:171], v242 offset:51200
	ds_read_b128 v[172:175], v242 offset:52224
	s_add_u32 s34, s34, 0x40000
	s_addc_u32 s35, s35, 0
	s_mov_b32 m0, s58
	ds_read_b128 v[194:197], v193 offset:32768
	ds_read_b128 v[198:201], v193 offset:33792
	ds_read_b128 v[202:205], v193 offset:34816
	ds_read_b128 v[206:209], v193 offset:35840
	ds_read_b128 v[210:213], v193 offset:36864
	ds_read_b128 v[214:217], v193 offset:37888
	ds_read_b128 v[234:237], v193 offset:38912
	ds_read_b128 v[238:241], v193 offset:39936
	global_load_lds_dwordx4 v152, s[34:35]
	s_mov_b32 m0, s59
	s_nop 0
	global_load_lds_dwordx4 v154, s[34:35]
	s_waitcnt vmcnt(8)
	s_waitcnt lgkmcnt(0)
	s_setprio 1
	s_barrier
	v_mfma_f32_16x16x32_bf16 v[148:151], v[64:67], v[194:197], v[148:151]
	v_mfma_f32_16x16x32_bf16 v[144:147], v[76:79], v[194:197], v[144:147]
	v_mfma_f32_16x16x32_bf16 v[132:135], v[64:67], v[202:205], v[132:135]
	v_mfma_f32_16x16x32_bf16 v[124:127], v[76:79], v[202:205], v[124:127]
	v_mfma_f32_16x16x32_bf16 v[116:119], v[64:67], v[210:213], v[116:119]
	v_mfma_f32_16x16x32_bf16 v[108:111], v[76:79], v[210:213], v[108:111]
	v_mfma_f32_16x16x32_bf16 v[100:103], v[64:67], v[234:237], v[100:103]
	v_mfma_f32_16x16x32_bf16 v[92:95], v[76:79], v[234:237], v[92:95]
	v_mfma_f32_16x16x32_bf16 v[148:151], v[68:71], v[198:201], v[148:151]
	v_mfma_f32_16x16x32_bf16 v[144:147], v[80:83], v[198:201], v[144:147]
	v_mfma_f32_16x16x32_bf16 v[132:135], v[68:71], v[206:209], v[132:135]
	v_mfma_f32_16x16x32_bf16 v[124:127], v[80:83], v[206:209], v[124:127]
	v_mfma_f32_16x16x32_bf16 v[116:119], v[68:71], v[214:217], v[116:119]
	v_mfma_f32_16x16x32_bf16 v[108:111], v[80:83], v[214:217], v[108:111]
	v_mfma_f32_16x16x32_bf16 v[100:103], v[68:71], v[238:241], v[100:103]
	v_mfma_f32_16x16x32_bf16 v[92:95], v[80:83], v[238:241], v[92:95]
	s_setprio 0
	s_setprio 1
	v_mfma_f32_16x16x32_bf16 v[140:143], v[88:91], v[194:197], v[140:143]
	v_mfma_f32_16x16x32_bf16 v[136:139], v[168:171], v[194:197], v[136:139]
	v_mfma_f32_16x16x32_bf16 v[128:131], v[88:91], v[202:205], v[128:131]
	v_mfma_f32_16x16x32_bf16 v[120:123], v[168:171], v[202:205], v[120:123]
	v_mfma_f32_16x16x32_bf16 v[112:115], v[88:91], v[210:213], v[112:115]
	v_mfma_f32_16x16x32_bf16 v[104:107], v[168:171], v[210:213], v[104:107]
	v_mfma_f32_16x16x32_bf16 v[96:99], v[88:91], v[234:237], v[96:99]
	v_mfma_f32_16x16x32_bf16 v[84:87], v[168:171], v[234:237], v[84:87]
	v_mfma_f32_16x16x32_bf16 v[140:143], v[164:167], v[198:201], v[140:143]
	v_mfma_f32_16x16x32_bf16 v[136:139], v[172:175], v[198:201], v[136:139]
	v_mfma_f32_16x16x32_bf16 v[128:131], v[164:167], v[206:209], v[128:131]
	v_mfma_f32_16x16x32_bf16 v[120:123], v[172:175], v[206:209], v[120:123]
	v_mfma_f32_16x16x32_bf16 v[112:115], v[164:167], v[214:217], v[112:115]
	v_mfma_f32_16x16x32_bf16 v[104:107], v[172:175], v[214:217], v[104:107]
	v_mfma_f32_16x16x32_bf16 v[96:99], v[164:167], v[238:241], v[96:99]
	v_mfma_f32_16x16x32_bf16 v[84:87], v[172:175], v[238:241], v[84:87]
	s_setprio 0
	s_barrier
; #define PG8_STAGE(bufoff, gbase, voff) do { _Pragma("unroll") for (int _i = 0; _i < 2; ++_i) \
;         __builtin_amdgcn_global_load_lds((const unsigned*)((const char*)(gbase) + (voff)[_i]), (PG8_LAS unsigned*)(lds + (bufoff) + ldsw + _i * 8192), 16, 0, 0); } while (0)
; #define PG8_LDA(dst, b, h) do { _Pragma("unroll") for (int m = 0; m < 4; ++m) _Pragma("unroll") for (int k = 0; k < 2; ++k) dst[m][k] = *(const PG8_LAS bf16x8*)(lds + PG8_SA(b, h) + aoff + m * 2048 + k * 1024); } while (0)
; #define PG8_LDB(dst, b, h) do { _Pragma("unroll") for (int n = 0; n < 2; ++n) _Pragma("unroll") for (int k = 0; k < 2; ++k) dst[n][k] = *(const PG8_LAS bf16x8*)(lds + PG8_SB(b, h) + boff + n * 2048 + k * 1024); } while (0)
; #define PG8_WAIT_V(n) asm volatile("s_waitcnt vmcnt(" #n ")" ::: "memory")
; #define PG8_WAIT_L(n) asm volatile("s_waitcnt lgkmcnt(" #n ")" ::: "memory")
; #define PG8_BAR __builtin_amdgcn_s_barrier()
; #define PG8_SCHED __builtin_amdgcn_sched_barrier(0)
; template <class Epi, class Sched, bool ALIGN_EPI = false, bool SP2 = false>
; __device__ __forceinline__ void gemm_phase(PG8_LAS unsigned char* lds, const Gemm g, const Sched& S, const Epi& E) {
;     ...
;         for (int t = 0; t < nt; t += 2) {
;             const bool last = (t == nt - 2);
;             const char* a1 = cA + (size_t)(t + 1) * kstep;
;             const char* a2 = last ? nA : cA + (size_t)(t + 2) * kstep; const char* b2 = last ? nB : cB + (size_t)(t + 2) * kstep;
;             const char* a3 = a2 + kstep; const char* b3 = b2 + kstep;
;             if (last && has_next) S.a_ready(nxt);
;             if constexpr (SP2) {
;             const int relax = __builtin_amdgcn_readfirstlane((t == 0 && ui > 0) ? 1 : 0);
;             PG8_LDB(B0, 0, 0); PG8_LDB(B1, 0, 1); PG8_SCHED; PG8_LDA(At, 0, 0); PG8_STAGE(PG8_SA(1, 1), a1 + hstep, voffA);
;             asm volatile("s_cmp_lg_u32 %0, 0\n\ts_cbranch_scc1 .Lrelax%=\n\ts_waitcnt vmcnt(8)\n.Lrelax%=:\n\ts_waitcnt vmcnt(%1)" :: "s"(relax), "n"(8 + Epi::NST) : "memory", "scc");
;             PG8_WAIT_L(0); PG8_BAR; PG8_MMA(0, 0, At, B0); PG8_MMA(0, 1, At, B1); PG8_BAR; PG8_SCHED;
;     ...
;             PG8_LDA(At, 1, 1); PG8_STAGE(PG8_SB(1, 0), b3, voffB); PG8_STAGE(PG8_SB(1, 1), b3 + hstep, voffB); PG8_STAGE(PG8_SA(1, 0), a3, voffA);
;             PG8_WAIT_V(8); PG8_WAIT_L(0); PG8_BAR; PG8_MMA(1, 0, At, B0); PG8_MMA(1, 1, At, B1); PG8_BAR; PG8_SCHED;
	s_add_i32 m0, s2, 0x18000
	s_add_u32 s4, s4, 0x80
	s_addc_u32 s5, s5, 0
	ds_read_b128 v[194:197], v193 offset:49152
	ds_read_b128 v[198:201], v193 offset:50176
	ds_read_b128 v[202:205], v193 offset:51200
	ds_read_b128 v[206:209], v193 offset:52224
	ds_read_b128 v[210:213], v193 offset:53248
	ds_read_b128 v[214:217], v193 offset:54272
	ds_read_b128 v[234:237], v193 offset:55296
	ds_read_b128 v[238:241], v193 offset:56320
	global_load_lds_dwordx4 v176, s[4:5]
	s_add_i32 m0, s2, 0x1a000
	s_add_u32 s70, s4, 0x40000
	s_addc_u32 s71, s5, 0
	global_load_lds_dwordx4 v156, s[4:5]
	s_add_i32 m0, s2, 0x1c000
	s_sub_u32 s34, s34, 0x40000
	s_subb_u32 s35, s35, 0
	global_load_lds_dwordx4 v176, s[70:71]
	s_add_i32 m0, s2, 0x1e000
	s_add_u32 s34, s34, 0x80
	s_addc_u32 s35, s35, 0
	global_load_lds_dwordx4 v156, s[70:71]
	s_mov_b32 m0, s60
	s_nop 0
	global_load_lds_dwordx4 v152, s[34:35]
	s_mov_b32 m0, s61
	s_nop 0
	global_load_lds_dwordx4 v154, s[34:35]
	s_waitcnt vmcnt(8)
	s_waitcnt lgkmcnt(0)
	s_setprio 1
	s_barrier
	v_mfma_f32_16x16x32_bf16 v[72:75], v[64:67], v[194:197], v[72:75]
	v_mfma_f32_16x16x32_bf16 v[52:55], v[76:79], v[194:197], v[52:55]
	v_mfma_f32_16x16x32_bf16 v[44:47], v[64:67], v[202:205], v[44:47]
	v_mfma_f32_16x16x32_bf16 v[36:39], v[76:79], v[202:205], v[36:39]
	v_mfma_f32_16x16x32_bf16 v[28:31], v[64:67], v[210:213], v[28:31]
	v_mfma_f32_16x16x32_bf16 v[20:23], v[76:79], v[210:213], v[20:23]
	v_mfma_f32_16x16x32_bf16 v[12:15], v[64:67], v[234:237], v[12:15]
	v_mfma_f32_16x16x32_bf16 v[4:7], v[76:79], v[234:237], v[4:7]
	v_mfma_f32_16x16x32_bf16 v[72:75], v[68:71], v[198:201], v[72:75]
	v_mfma_f32_16x16x32_bf16 v[52:55], v[80:83], v[198:201], v[52:55]
	v_mfma_f32_16x16x32_bf16 v[44:47], v[68:71], v[206:209], v[44:47]
	v_mfma_f32_16x16x32_bf16 v[36:39], v[80:83], v[206:209], v[36:39]
	v_mfma_f32_16x16x32_bf16 v[28:31], v[68:71], v[214:217], v[28:31]
	v_mfma_f32_16x16x32_bf16 v[20:23], v[80:83], v[214:217], v[20:23]
	v_mfma_f32_16x16x32_bf16 v[12:15], v[68:71], v[238:241], v[12:15]
	v_mfma_f32_16x16x32_bf16 v[4:7], v[80:83], v[238:241], v[4:7]
	s_setprio 0
	s_setprio 1
	v_mfma_f32_16x16x32_bf16 v[60:63], v[88:91], v[194:197], v[60:63]
	v_mfma_f32_16x16x32_bf16 v[48:51], v[168:171], v[194:197], v[48:51]
	v_mfma_f32_16x16x32_bf16 v[40:43], v[88:91], v[202:205], v[40:43]
	v_mfma_f32_16x16x32_bf16 v[32:35], v[168:171], v[202:205], v[32:35]
	v_mfma_f32_16x16x32_bf16 v[24:27], v[88:91], v[210:213], v[24:27]
	v_mfma_f32_16x16x32_bf16 v[16:19], v[168:171], v[210:213], v[16:19]
	v_mfma_f32_16x16x32_bf16 v[8:11], v[88:91], v[234:237], v[8:11]
	v_mfma_f32_16x16x32_bf16 v[0:3], v[168:171], v[234:237], v[0:3]
	v_mfma_f32_16x16x32_bf16 v[64:67], v[164:167], v[198:201], v[60:63]
	v_mfma_f32_16x16x32_bf16 v[48:51], v[172:175], v[198:201], v[48:51]
	v_mfma_f32_16x16x32_bf16 v[40:43], v[164:167], v[206:209], v[40:43]
	v_mfma_f32_16x16x32_bf16 v[32:35], v[172:175], v[206:209], v[32:35]
	v_mfma_f32_16x16x32_bf16 v[24:27], v[164:167], v[214:217], v[24:27]
	v_mfma_f32_16x16x32_bf16 v[16:19], v[172:175], v[214:217], v[16:19]
	v_mfma_f32_16x16x32_bf16 v[8:11], v[164:167], v[238:241], v[8:11]
	v_mfma_f32_16x16x32_bf16 v[0:3], v[172:175], v[238:241], v[0:3]
	s_setprio 0
	s_barrier
	s_add_i32 s69, s69, 2
	s_add_u32 s40, s40, 0x100
	s_addc_u32 s41, s41, 0
	s_cmp_gt_u32 s69, 13
.LBB0_156:
	s_add_u32 s34, s28, s40
	s_addc_u32 s35, s29, s41
	s_add_u32 s70, s34, 0x40080
	s_addc_u32 s71, s35, 0
	s_add_u32 s34, s34, 0x100
	s_addc_u32 s35, s35, 0
	s_add_u32 s4, s67, s40
	s_addc_u32 s5, s68, s41
	s_cmpk_eq_i32 s40, 0x700
	s_cselect_b32 s35, s51, s35
	s_cselect_b32 s34, s65, s34
	s_cselect_b32 s5, s49, s5
	s_cselect_b32 s4, s66, s4
	ds_read_b128 v[60:63], v242
	ds_read_b128 v[68:71], v242 offset:1024
	ds_read_b128 v[76:79], v242 offset:2048
	ds_read_b128 v[80:83], v242 offset:3072
	ds_read_b128 v[88:91], v242 offset:16384
	ds_read_b128 v[164:167], v242 offset:17408
	ds_read_b128 v[168:171], v242 offset:18432
	ds_read_b128 v[172:175], v242 offset:19456
	s_add_i32 m0, s37, 0xc000
	ds_read_b128 v[194:197], v193
	ds_read_b128 v[198:201], v193 offset:1024
	ds_read_b128 v[202:205], v193 offset:2048
	ds_read_b128 v[206:209], v193 offset:3072
	ds_read_b128 v[210:213], v193 offset:4096
	ds_read_b128 v[214:217], v193 offset:5120
	ds_read_b128 v[234:237], v193 offset:6144
	ds_read_b128 v[238:241], v193 offset:7168
	global_load_lds_dwordx4 v160, s[70:71]
	s_add_i32 m0, s37, 0xe000
	s_nop 0
	global_load_lds_dwordx4 v162, s[70:71]
	s_waitcnt vmcnt(8)
	s_waitcnt lgkmcnt(0)
	s_setprio 1
	s_barrier
; #define PG8_STAGE(bufoff, gbase, voff) do { _Pragma("unroll") for (int _i = 0; _i < 2; ++_i) \
;         __builtin_amdgcn_global_load_lds((const unsigned*)((const char*)(gbase) + (voff)[_i]), (PG8_LAS unsigned*)(lds + (bufoff) + ldsw + _i * 8192), 16, 0, 0); } while (0)
; #define PG8_LDA(dst, b, h) do { _Pragma("unroll") for (int m = 0; m < 4; ++m) _Pragma("unroll") for (int k = 0; k < 2; ++k) dst[m][k] = *(const PG8_LAS bf16x8*)(lds + PG8_SA(b, h) + aoff + m * 2048 + k * 1024); } while (0)
; #define PG8_MMA(ai, bj, At, Bt) do { __builtin_amdgcn_s_setprio(1); _Pragma("unroll") for (int m = 0; m < 4; ++m) _Pragma("unroll") for (int n = 0; n < 2; ++n) _Pragma("unroll") for (int k = 0; k < 2; ++k) \
;         acc[ai][bj][m][n] = __builtin_amdgcn_mfma_f32_16x16x32_bf16(Bt[n][k], At[m][k], acc[ai][bj][m][n], 0, 0, 0); __builtin_amdgcn_s_setprio(0); } while (0)
; #define PG8_WAIT_L(n) asm volatile("s_waitcnt lgkmcnt(" #n ")" ::: "memory")
; #define PG8_BAR __builtin_amdgcn_s_barrier()
; #define PG8_SCHED __builtin_amdgcn_sched_barrier(0)
; template <class Epi, class Sched, bool ALIGN_EPI = false, bool SP2 = false>
; __device__ __forceinline__ void gemm_phase(PG8_LAS unsigned char* lds, const Gemm g, const Sched& S, const Epi& E) {
;     ...
;             PG8_WAIT_L(0); PG8_BAR; PG8_MMA(0, 0, At, B0); PG8_MMA(0, 1, At, B1); PG8_BAR; PG8_SCHED;
;             PG8_LDA(At, 0, 1); PG8_STAGE(PG8_SB(0, 0), b2, voffB); PG8_STAGE(PG8_SB(0, 1), b2 + hstep, voffB); PG8_STAGE(PG8_SA(0, 0), a2, voffA);
;             asm volatile("s_cmp_lg_u32 %0, 0\n\ts_cbranch_scc1 .Lrelax%=\n\ts_waitcnt vmcnt(8)\n.Lrelax%=:\n\ts_waitcnt vmcnt(%1)" :: "s"(relax), "n"(8 + Epi::NST) : "memory", "scc");
;             PG8_WAIT_L(0); PG8_BAR; PG8_MMA(1, 0, At, B0); PG8_MMA(1, 1, At, B1); PG8_BAR; PG8_SCHED;
	v_mfma_f32_16x16x32_bf16 v[148:151], v[60:63], v[194:197], v[148:151]
	v_mfma_f32_16x16x32_bf16 v[144:147], v[76:79], v[194:197], v[144:147]
	v_mfma_f32_16x16x32_bf16 v[132:135], v[60:63], v[202:205], v[132:135]
	v_mfma_f32_16x16x32_bf16 v[124:127], v[76:79], v[202:205], v[124:127]
	v_mfma_f32_16x16x32_bf16 v[116:119], v[60:63], v[210:213], v[116:119]
	v_mfma_f32_16x16x32_bf16 v[108:111], v[76:79], v[210:213], v[108:111]
	v_mfma_f32_16x16x32_bf16 v[100:103], v[60:63], v[234:237], v[100:103]
	v_mfma_f32_16x16x32_bf16 v[92:95], v[76:79], v[234:237], v[92:95]
	v_mfma_f32_16x16x32_bf16 v[148:151], v[68:71], v[198:201], v[148:151]
	v_mfma_f32_16x16x32_bf16 v[144:147], v[80:83], v[198:201], v[144:147]
	v_mfma_f32_16x16x32_bf16 v[132:135], v[68:71], v[206:209], v[132:135]
	v_mfma_f32_16x16x32_bf16 v[124:127], v[80:83], v[206:209], v[124:127]
	v_mfma_f32_16x16x32_bf16 v[116:119], v[68:71], v[214:217], v[116:119]
	v_mfma_f32_16x16x32_bf16 v[108:111], v[80:83], v[214:217], v[108:111]
	v_mfma_f32_16x16x32_bf16 v[100:103], v[68:71], v[238:241], v[100:103]
	v_mfma_f32_16x16x32_bf16 v[92:95], v[80:83], v[238:241], v[92:95]
	s_setprio 0
	s_setprio 1
	v_mfma_f32_16x16x32_bf16 v[140:143], v[88:91], v[194:197], v[140:143]
	v_mfma_f32_16x16x32_bf16 v[136:139], v[168:171], v[194:197], v[136:139]
	v_mfma_f32_16x16x32_bf16 v[128:131], v[88:91], v[202:205], v[128:131]
	v_mfma_f32_16x16x32_bf16 v[120:123], v[168:171], v[202:205], v[120:123]
	v_mfma_f32_16x16x32_bf16 v[112:115], v[88:91], v[210:213], v[112:115]
	v_mfma_f32_16x16x32_bf16 v[104:107], v[168:171], v[210:213], v[104:107]
	v_mfma_f32_16x16x32_bf16 v[96:99], v[88:91], v[234:237], v[96:99]
	v_mfma_f32_16x16x32_bf16 v[84:87], v[168:171], v[234:237], v[84:87]
	v_mfma_f32_16x16x32_bf16 v[140:143], v[164:167], v[198:201], v[140:143]
	v_mfma_f32_16x16x32_bf16 v[136:139], v[172:175], v[198:201], v[136:139]
	v_mfma_f32_16x16x32_bf16 v[128:131], v[164:167], v[206:209], v[128:131]
	v_mfma_f32_16x16x32_bf16 v[120:123], v[172:175], v[206:209], v[120:123]
	v_mfma_f32_16x16x32_bf16 v[112:115], v[164:167], v[214:217], v[112:115]
	v_mfma_f32_16x16x32_bf16 v[104:107], v[172:175], v[214:217], v[104:107]
	v_mfma_f32_16x16x32_bf16 v[96:99], v[164:167], v[238:241], v[96:99]
	v_mfma_f32_16x16x32_bf16 v[84:87], v[172:175], v[238:241], v[84:87]
	s_setprio 0
	s_barrier
	s_add_i32 m0, s2, 0x10000
	ds_read_b128 v[194:197], v193 offset:16384
	ds_read_b128 v[198:201], v193 offset:17408
	ds_read_b128 v[202:205], v193 offset:18432
	ds_read_b128 v[206:209], v193 offset:19456
	ds_read_b128 v[210:213], v193 offset:20480
	ds_read_b128 v[214:217], v193 offset:21504
	ds_read_b128 v[234:237], v193 offset:22528
	ds_read_b128 v[238:241], v193 offset:23552
	global_load_lds_dwordx4 v176, s[4:5]
	s_add_i32 m0, s2, 0x12000
	s_add_u32 s70, s4, 0x40000
	s_addc_u32 s71, s5, 0
	global_load_lds_dwordx4 v156, s[4:5]
	s_add_i32 m0, s2, 0x14000
	s_nop 0
	global_load_lds_dwordx4 v176, s[70:71]
	s_add_i32 m0, s2, 0x16000
	s_nop 0
	global_load_lds_dwordx4 v156, s[70:71]
	s_mov_b32 m0, s37
	s_nop 0
	global_load_lds_dwordx4 v152, s[34:35]
	s_mov_b32 m0, s57
	s_nop 0
	global_load_lds_dwordx4 v154, s[34:35]
	s_waitcnt vmcnt(8)
	s_waitcnt lgkmcnt(0)
	s_setprio 1
	s_barrier
	v_mfma_f32_16x16x32_bf16 v[72:75], v[60:63], v[194:197], v[72:75]
	v_mfma_f32_16x16x32_bf16 v[52:55], v[76:79], v[194:197], v[52:55]
	v_mfma_f32_16x16x32_bf16 v[44:47], v[60:63], v[202:205], v[44:47]
	v_mfma_f32_16x16x32_bf16 v[36:39], v[76:79], v[202:205], v[36:39]
	v_mfma_f32_16x16x32_bf16 v[28:31], v[60:63], v[210:213], v[28:31]
	v_mfma_f32_16x16x32_bf16 v[20:23], v[76:79], v[210:213], v[20:23]
	v_mfma_f32_16x16x32_bf16 v[12:15], v[60:63], v[234:237], v[12:15]
	v_mfma_f32_16x16x32_bf16 v[4:7], v[76:79], v[234:237], v[4:7]
	v_mfma_f32_16x16x32_bf16 v[72:75], v[68:71], v[198:201], v[72:75]
	v_mfma_f32_16x16x32_bf16 v[52:55], v[80:83], v[198:201], v[52:55]
	v_mfma_f32_16x16x32_bf16 v[44:47], v[68:71], v[206:209], v[44:47]
	v_mfma_f32_16x16x32_bf16 v[36:39], v[80:83], v[206:209], v[36:39]
	v_mfma_f32_16x16x32_bf16 v[28:31], v[68:71], v[214:217], v[28:31]
	v_mfma_f32_16x16x32_bf16 v[20:23], v[80:83], v[214:217], v[20:23]
	v_mfma_f32_16x16x32_bf16 v[12:15], v[68:71], v[238:241], v[12:15]
	v_mfma_f32_16x16x32_bf16 v[4:7], v[80:83], v[238:241], v[4:7]
	s_setprio 0
	s_setprio 1
	v_mfma_f32_16x16x32_bf16 v[48:51], v[168:171], v[194:197], v[48:51]
	v_mfma_f32_16x16x32_bf16 v[40:43], v[88:91], v[202:205], v[40:43]
	v_mfma_f32_16x16x32_bf16 v[32:35], v[168:171], v[202:205], v[32:35]
	v_mfma_f32_16x16x32_bf16 v[24:27], v[88:91], v[210:213], v[24:27]
	v_mfma_f32_16x16x32_bf16 v[16:19], v[168:171], v[210:213], v[16:19]
	v_mfma_f32_16x16x32_bf16 v[8:11], v[88:91], v[234:237], v[8:11]
	v_mfma_f32_16x16x32_bf16 v[0:3], v[168:171], v[234:237], v[0:3]
	v_mfma_f32_16x16x32_bf16 v[60:63], v[88:91], v[194:197], v[64:67]
	v_mfma_f32_16x16x32_bf16 v[48:51], v[172:175], v[198:201], v[48:51]
	v_mfma_f32_16x16x32_bf16 v[40:43], v[164:167], v[206:209], v[40:43]
	v_mfma_f32_16x16x32_bf16 v[32:35], v[172:175], v[206:209], v[32:35]
	v_mfma_f32_16x16x32_bf16 v[24:27], v[164:167], v[214:217], v[24:27]
	v_mfma_f32_16x16x32_bf16 v[16:19], v[172:175], v[214:217], v[16:19]
	v_mfma_f32_16x16x32_bf16 v[8:11], v[164:167], v[238:241], v[8:11]
	v_mfma_f32_16x16x32_bf16 v[0:3], v[172:175], v[238:241], v[0:3]
	v_mfma_f32_16x16x32_bf16 v[60:63], v[164:167], v[198:201], v[60:63]
	s_setprio 0
	s_barrier
; #define PG8_STAGE(bufoff, gbase, voff) do { _Pragma("unroll") for (int _i = 0; _i < 2; ++_i) \
;         __builtin_amdgcn_global_load_lds((const unsigned*)((const char*)(gbase) + (voff)[_i]), (PG8_LAS unsigned*)(lds + (bufoff) + ldsw + _i * 8192), 16, 0, 0); } while (0)
; #define PG8_LDA(dst, b, h) do { _Pragma("unroll") for (int m = 0; m < 4; ++m) _Pragma("unroll") for (int k = 0; k < 2; ++k) dst[m][k] = *(const PG8_LAS bf16x8*)(lds + PG8_SA(b, h) + aoff + m * 2048 + k * 1024); } while (0)
; #define PG8_LDB(dst, b, h) do { _Pragma("unroll") for (int n = 0; n < 2; ++n) _Pragma("unroll") for (int k = 0; k < 2; ++k) dst[n][k] = *(const PG8_LAS bf16x8*)(lds + PG8_SB(b, h) + boff + n * 2048 + k * 1024); } while (0)
; #define PG8_MMA(ai, bj, At, Bt) do { __builtin_amdgcn_s_setprio(1); _Pragma("unroll") for (int m = 0; m < 4; ++m) _Pragma("unroll") for (int n = 0; n < 2; ++n) _Pragma("unroll") for (int k = 0; k < 2; ++k) \
;         acc[ai][bj][m][n] = __builtin_amdgcn_mfma_f32_16x16x32_bf16(Bt[n][k], At[m][k], acc[ai][bj][m][n], 0, 0, 0); __builtin_amdgcn_s_setprio(0); } while (0)
; #define PG8_WAIT_V(n) asm volatile("s_waitcnt vmcnt(" #n ")" ::: "memory")
; #define PG8_WAIT_L(n) asm volatile("s_waitcnt lgkmcnt(" #n ")" ::: "memory")
; #define PG8_BAR __builtin_amdgcn_s_barrier()
; #define PG8_SCHED __builtin_amdgcn_sched_barrier(0)
; template <class Epi, class Sched, bool ALIGN_EPI = false, bool SP2 = false>
; __device__ __forceinline__ void gemm_phase(PG8_LAS unsigned char* lds, const Gemm g, const Sched& S, const Epi& E) {
;     ...
;             PG8_LDB(B0, 1, 0); PG8_LDB(B1, 1, 1); PG8_SCHED; PG8_LDA(At, 1, 0); PG8_STAGE(PG8_SA(0, 1), a2 + hstep, voffA);
;             PG8_WAIT_V(8); PG8_WAIT_L(0); PG8_BAR; PG8_MMA(0, 0, At, B0); PG8_MMA(0, 1, At, B1); PG8_BAR; PG8_SCHED;
;             PG8_LDA(At, 1, 1); PG8_STAGE(PG8_SB(1, 0), b3, voffB); PG8_STAGE(PG8_SB(1, 1), b3 + hstep, voffB); PG8_STAGE(PG8_SA(1, 0), a3, voffA);
;             PG8_WAIT_V(8); PG8_WAIT_L(0); PG8_BAR; PG8_MMA(1, 0, At, B0); PG8_MMA(1, 1, At, B1); PG8_BAR; PG8_SCHED;
	ds_read_b128 v[64:67], v242 offset:32768
	ds_read_b128 v[68:71], v242 offset:33792
	ds_read_b128 v[76:79], v242 offset:34816
	ds_read_b128 v[80:83], v242 offset:35840
	ds_read_b128 v[88:91], v242 offset:49152
	ds_read_b128 v[164:167], v242 offset:50176
	ds_read_b128 v[168:171], v242 offset:51200
	ds_read_b128 v[172:175], v242 offset:52224
	s_add_u32 s34, s34, 0x40000
	s_addc_u32 s35, s35, 0
	s_mov_b32 m0, s58
	ds_read_b128 v[194:197], v193 offset:32768
	ds_read_b128 v[198:201], v193 offset:33792
	ds_read_b128 v[202:205], v193 offset:34816
	ds_read_b128 v[206:209], v193 offset:35840
	ds_read_b128 v[210:213], v193 offset:36864
	ds_read_b128 v[214:217], v193 offset:37888
	ds_read_b128 v[234:237], v193 offset:38912
	ds_read_b128 v[238:241], v193 offset:39936
	global_load_lds_dwordx4 v152, s[34:35]
	s_mov_b32 m0, s59
	s_nop 0
	global_load_lds_dwordx4 v154, s[34:35]
	s_waitcnt vmcnt(8)
	s_waitcnt lgkmcnt(0)
	s_setprio 1
	s_barrier
	v_mfma_f32_16x16x32_bf16 v[148:151], v[64:67], v[194:197], v[148:151]
	v_mfma_f32_16x16x32_bf16 v[144:147], v[76:79], v[194:197], v[144:147]
	v_mfma_f32_16x16x32_bf16 v[132:135], v[64:67], v[202:205], v[132:135]
	v_mfma_f32_16x16x32_bf16 v[124:127], v[76:79], v[202:205], v[124:127]
	v_mfma_f32_16x16x32_bf16 v[116:119], v[64:67], v[210:213], v[116:119]
	v_mfma_f32_16x16x32_bf16 v[108:111], v[76:79], v[210:213], v[108:111]
	v_mfma_f32_16x16x32_bf16 v[100:103], v[64:67], v[234:237], v[100:103]
	v_mfma_f32_16x16x32_bf16 v[92:95], v[76:79], v[234:237], v[92:95]
	v_mfma_f32_16x16x32_bf16 v[148:151], v[68:71], v[198:201], v[148:151]
	v_mfma_f32_16x16x32_bf16 v[144:147], v[80:83], v[198:201], v[144:147]
	v_mfma_f32_16x16x32_bf16 v[132:135], v[68:71], v[206:209], v[132:135]
	v_mfma_f32_16x16x32_bf16 v[124:127], v[80:83], v[206:209], v[124:127]
	v_mfma_f32_16x16x32_bf16 v[116:119], v[68:71], v[214:217], v[116:119]
	v_mfma_f32_16x16x32_bf16 v[108:111], v[80:83], v[214:217], v[108:111]
	v_mfma_f32_16x16x32_bf16 v[100:103], v[68:71], v[238:241], v[100:103]
	v_mfma_f32_16x16x32_bf16 v[92:95], v[80:83], v[238:241], v[92:95]
	s_setprio 0
	s_setprio 1
	v_mfma_f32_16x16x32_bf16 v[140:143], v[88:91], v[194:197], v[140:143]
	v_mfma_f32_16x16x32_bf16 v[136:139], v[168:171], v[194:197], v[136:139]
	v_mfma_f32_16x16x32_bf16 v[128:131], v[88:91], v[202:205], v[128:131]
	v_mfma_f32_16x16x32_bf16 v[120:123], v[168:171], v[202:205], v[120:123]
	v_mfma_f32_16x16x32_bf16 v[112:115], v[88:91], v[210:213], v[112:115]
	v_mfma_f32_16x16x32_bf16 v[104:107], v[168:171], v[210:213], v[104:107]
	v_mfma_f32_16x16x32_bf16 v[96:99], v[88:91], v[234:237], v[96:99]
	v_mfma_f32_16x16x32_bf16 v[84:87], v[168:171], v[234:237], v[84:87]
	v_mfma_f32_16x16x32_bf16 v[140:143], v[164:167], v[198:201], v[140:143]
	v_mfma_f32_16x16x32_bf16 v[136:139], v[172:175], v[198:201], v[136:139]
	v_mfma_f32_16x16x32_bf16 v[128:131], v[164:167], v[206:209], v[128:131]
	v_mfma_f32_16x16x32_bf16 v[120:123], v[172:175], v[206:209], v[120:123]
	v_mfma_f32_16x16x32_bf16 v[112:115], v[164:167], v[214:217], v[112:115]
	v_mfma_f32_16x16x32_bf16 v[104:107], v[172:175], v[214:217], v[104:107]
	v_mfma_f32_16x16x32_bf16 v[96:99], v[164:167], v[238:241], v[96:99]
	v_mfma_f32_16x16x32_bf16 v[84:87], v[172:175], v[238:241], v[84:87]
	s_setprio 0
	s_barrier
	s_add_i32 m0, s2, 0x18000
	s_add_u32 s4, s4, 0x80
	s_addc_u32 s5, s5, 0
	ds_read_b128 v[194:197], v193 offset:49152
	ds_read_b128 v[198:201], v193 offset:50176
	ds_read_b128 v[202:205], v193 offset:51200
	ds_read_b128 v[206:209], v193 offset:52224
	ds_read_b128 v[210:213], v193 offset:53248
	ds_read_b128 v[214:217], v193 offset:54272
	ds_read_b128 v[234:237], v193 offset:55296
	ds_read_b128 v[238:241], v193 offset:56320
	global_load_lds_dwordx4 v176, s[4:5]
	s_add_i32 m0, s2, 0x1a000
	s_add_u32 s70, s4, 0x40000
	s_addc_u32 s71, s5, 0
	global_load_lds_dwordx4 v156, s[4:5]
	s_add_i32 m0, s2, 0x1c000
	s_sub_u32 s34, s34, 0x40000
	s_subb_u32 s35, s35, 0
	global_load_lds_dwordx4 v176, s[70:71]
	s_add_i32 m0, s2, 0x1e000
	s_add_u32 s34, s34, 0x80
	s_addc_u32 s35, s35, 0
	global_load_lds_dwordx4 v156, s[70:71]
	s_mov_b32 m0, s60
	s_nop 0
	global_load_lds_dwordx4 v152, s[34:35]
	s_mov_b32 m0, s61
	s_nop 0
	global_load_lds_dwordx4 v154, s[34:35]
	s_waitcnt vmcnt(8)
	s_waitcnt lgkmcnt(0)
	s_setprio 1
	s_barrier
	v_mfma_f32_16x16x32_bf16 v[72:75], v[64:67], v[194:197], v[72:75]
	v_mfma_f32_16x16x32_bf16 v[52:55], v[76:79], v[194:197], v[52:55]
	v_mfma_f32_16x16x32_bf16 v[44:47], v[64:67], v[202:205], v[44:47]
	v_mfma_f32_16x16x32_bf16 v[36:39], v[76:79], v[202:205], v[36:39]
	v_mfma_f32_16x16x32_bf16 v[28:31], v[64:67], v[210:213], v[28:31]
	v_mfma_f32_16x16x32_bf16 v[20:23], v[76:79], v[210:213], v[20:23]
	v_mfma_f32_16x16x32_bf16 v[12:15], v[64:67], v[234:237], v[12:15]
	v_mfma_f32_16x16x32_bf16 v[4:7], v[76:79], v[234:237], v[4:7]
	v_mfma_f32_16x16x32_bf16 v[72:75], v[68:71], v[198:201], v[72:75]
	v_mfma_f32_16x16x32_bf16 v[52:55], v[80:83], v[198:201], v[52:55]
	v_mfma_f32_16x16x32_bf16 v[44:47], v[68:71], v[206:209], v[44:47]
	v_mfma_f32_16x16x32_bf16 v[36:39], v[80:83], v[206:209], v[36:39]
	v_mfma_f32_16x16x32_bf16 v[28:31], v[68:71], v[214:217], v[28:31]
	v_mfma_f32_16x16x32_bf16 v[20:23], v[80:83], v[214:217], v[20:23]
	v_mfma_f32_16x16x32_bf16 v[12:15], v[68:71], v[238:241], v[12:15]
	v_mfma_f32_16x16x32_bf16 v[4:7], v[80:83], v[238:241], v[4:7]
	s_setprio 0
	s_setprio 1
	v_mfma_f32_16x16x32_bf16 v[60:63], v[88:91], v[194:197], v[60:63]
	v_mfma_f32_16x16x32_bf16 v[48:51], v[168:171], v[194:197], v[48:51]
	v_mfma_f32_16x16x32_bf16 v[40:43], v[88:91], v[202:205], v[40:43]
	v_mfma_f32_16x16x32_bf16 v[32:35], v[168:171], v[202:205], v[32:35]
	v_mfma_f32_16x16x32_bf16 v[24:27], v[88:91], v[210:213], v[24:27]
	v_mfma_f32_16x16x32_bf16 v[16:19], v[168:171], v[210:213], v[16:19]
	v_mfma_f32_16x16x32_bf16 v[8:11], v[88:91], v[234:237], v[8:11]
	v_mfma_f32_16x16x32_bf16 v[0:3], v[168:171], v[234:237], v[0:3]
	v_mfma_f32_16x16x32_bf16 v[64:67], v[164:167], v[198:201], v[60:63]
	v_mfma_f32_16x16x32_bf16 v[48:51], v[172:175], v[198:201], v[48:51]
	v_mfma_f32_16x16x32_bf16 v[40:43], v[164:167], v[206:209], v[40:43]
	v_mfma_f32_16x16x32_bf16 v[32:35], v[172:175], v[206:209], v[32:35]
	v_mfma_f32_16x16x32_bf16 v[24:27], v[164:167], v[214:217], v[24:27]
	v_mfma_f32_16x16x32_bf16 v[16:19], v[172:175], v[214:217], v[16:19]
	v_mfma_f32_16x16x32_bf16 v[8:11], v[164:167], v[238:241], v[8:11]
	v_mfma_f32_16x16x32_bf16 v[0:3], v[172:175], v[238:241], v[0:3]
	s_setprio 0
	s_barrier
	s_add_i32 s69, s69, 2
	s_add_u32 s40, s40, 0x100
	s_addc_u32 s41, s41, 0
	s_cmp_gt_u32 s69, 13
	s_cbranch_scc0 .LBB0_156

; #define PG8_STAGE(bufoff, gbase, voff) do { _Pragma("unroll") for (int _i = 0; _i < 2; ++_i) \
;         __builtin_amdgcn_global_load_lds((const unsigned*)((const char*)(gbase) + (voff)[_i]), (PG8_LAS unsigned*)(lds + (bufoff) + ldsw + _i * 8192), 16, 0, 0); } while (0)
; #define PG8_LDA(dst, b, h) do { _Pragma("unroll") for (int m = 0; m < 4; ++m) _Pragma("unroll") for (int k = 0; k < 2; ++k) dst[m][k] = *(const PG8_LAS bf16x8*)(lds + PG8_SA(b, h) + aoff + m * 2048 + k * 1024); } while (0)
; #define PG8_WAIT_L(n) asm volatile("s_waitcnt lgkmcnt(" #n ")" ::: "memory")
; #define PG8_BAR __builtin_amdgcn_s_barrier()
; #define PG8_SCHED __builtin_amdgcn_sched_barrier(0)
; template <class Epi, class Sched, bool ALIGN_EPI = false, bool SP2 = false>
; __device__ __forceinline__ void gemm_phase(PG8_LAS unsigned char* lds, const Gemm g, const Sched& S, const Epi& E) {
;     ...
;         const bool has_next = S.next(ui + 1, nxt);
;         const char* nA = has_next ? (const char*)g.A + (size_t)nxt.pm * tstep : cA; const char* nB = has_next ? (const char*)g.Bt + (size_t)nxt.pn * tstep : cB;
;         for (int t = 0; t < nt; t += 2) {
;             const bool last = (t == nt - 2);
;             const char* a1 = cA + (size_t)(t + 1) * kstep;
;             const char* a2 = last ? nA : cA + (size_t)(t + 2) * kstep; const char* b2 = last ? nB : cB + (size_t)(t + 2) * kstep;
;             const char* a3 = a2 + kstep; const char* b3 = b2 + kstep;
;             if (last && has_next) S.a_ready(nxt);
;             if constexpr (SP2) {
;             const int relax = __builtin_amdgcn_readfirstlane((t == 0 && ui > 0) ? 1 : 0);
;             PG8_LDB(B0, 0, 0); PG8_LDB(B1, 0, 1); PG8_SCHED; PG8_LDA(At, 0, 0); PG8_STAGE(PG8_SA(1, 1), a1 + hstep, voffA);
;             asm volatile("s_cmp_lg_u32 %0, 0\n\ts_cbranch_scc1 .Lrelax%=\n\ts_waitcnt vmcnt(8)\n.Lrelax%=:\n\ts_waitcnt vmcnt(%1)" :: "s"(relax), "n"(8 + Epi::NST) : "memory", "scc");
;             PG8_WAIT_L(0); PG8_BAR; PG8_MMA(0, 0, At, B0); PG8_MMA(0, 1, At, B1); PG8_BAR; PG8_SCHED;
;             PG8_LDA(At, 0, 1); PG8_STAGE(PG8_SB(0, 0), b2, voffB); PG8_STAGE(PG8_SB(0, 1), b2 + hstep, voffB); PG8_STAGE(PG8_SA(0, 0), a2, voffA);
;             asm volatile("s_cmp_lg_u32 %0, 0\n\ts_cbranch_scc1 .Lrelax%=\n\ts_waitcnt vmcnt(8)\n.Lrelax%=:\n\ts_waitcnt vmcnt(%1)" :: "s"(relax), "n"(8 + Epi::NST) : "memory", "scc");
.LBB0_192:
	s_cmp_lg_u32 s2, 0
	s_cselect_b64 s[30:31], -1, 0
	s_add_u32 s2, s4, 0x100
	s_addc_u32 s70, s5, 0
	s_add_u32 s4, s28, 0x80
	s_addc_u32 s5, s29, 0
	s_mov_b32 s71, 0
	s_waitcnt vmcnt(24)
	v_lshl_add_u64 v[64:65], s[4:5], 0, v[192:193]
	v_lshl_add_u64 v[66:67], s[4:5], 0, v[194:195]
	s_mov_b64 s[42:43], 0
	s_waitcnt lgkmcnt(0)
	v_add_u32_e32 v216, 0x10000, v234
	s_add_i32 s72, s71, 2
	s_add_u32 s4, s28, s42
	s_addc_u32 s5, s29, s43
	s_add_u32 s76, s4, 0x80
	s_addc_u32 s77, s5, 0
	s_add_u32 s4, s4, 0x100
	s_addc_u32 s5, s5, 0
	s_add_u32 s74, s2, s42
	s_addc_u32 s75, s70, s43
	s_cmp_eq_u32 s64, s71
	s_cselect_b32 s5, s55, s5
	s_cselect_b32 s4, s54, s4
	s_cselect_b32 s75, s57, s75
	s_cselect_b32 s74, s56, s74
	ds_read_b128 v[68:71], v216
	ds_read_b128 v[72:75], v216 offset:1024
	ds_read_b128 v[76:79], v216 offset:2048
	ds_read_b128 v[144:147], v216 offset:3072
	ds_read_b128 v[148:151], v216 offset:16384
	ds_read_b128 v[152:155], v216 offset:17408
	ds_read_b128 v[156:159], v216 offset:18432
	ds_read_b128 v[160:163], v216 offset:19456
	s_add_i32 m0, s36, 0xc000
	ds_read_b128 v[164:167], v236
	ds_read_b128 v[168:171], v236 offset:1024
	ds_read_b128 v[172:175], v236 offset:2048
	ds_read_b128 v[196:199], v236 offset:3072
	ds_read_b128 v[200:203], v236 offset:4096
	ds_read_b128 v[204:207], v236 offset:5120
	ds_read_b128 v[208:211], v236 offset:6144
	ds_read_b128 v[212:215], v236 offset:7168
	global_load_lds_dwordx4 v192, s[76:77]
	s_add_i32 m0, s36, 0xe000
	s_nop 0
	global_load_lds_dwordx4 v194, s[76:77]
	s_cmp_lg_u32 s30, 0
	s_cbranch_scc1 .Lmy_residp_rx1
	s_waitcnt vmcnt(8)
.Lmy_residp_rx1:
	s_waitcnt vmcnt(32)
	s_waitcnt lgkmcnt(0)
	s_setprio 1
	s_barrier
	v_mfma_f32_16x16x32_bf16 v[140:143], v[68:71], v[164:167], 0
	v_mfma_f32_16x16x32_bf16 v[136:139], v[76:79], v[164:167], 0
	v_mfma_f32_16x16x32_bf16 v[124:127], v[68:71], v[172:175], 0
	v_mfma_f32_16x16x32_bf16 v[120:123], v[76:79], v[172:175], 0
	v_mfma_f32_16x16x32_bf16 v[108:111], v[68:71], v[200:203], 0
	v_mfma_f32_16x16x32_bf16 v[104:107], v[76:79], v[200:203], 0
	v_mfma_f32_16x16x32_bf16 v[92:95], v[68:71], v[208:211], 0
	v_mfma_f32_16x16x32_bf16 v[88:91], v[76:79], v[208:211], 0
	v_mfma_f32_16x16x32_bf16 v[140:143], v[72:75], v[168:171], v[140:143]
	v_mfma_f32_16x16x32_bf16 v[136:139], v[144:147], v[168:171], v[136:139]
	v_mfma_f32_16x16x32_bf16 v[124:127], v[72:75], v[196:199], v[124:127]
	v_mfma_f32_16x16x32_bf16 v[120:123], v[144:147], v[196:199], v[120:123]
	v_mfma_f32_16x16x32_bf16 v[108:111], v[72:75], v[204:207], v[108:111]
	v_mfma_f32_16x16x32_bf16 v[104:107], v[144:147], v[204:207], v[104:107]
	v_mfma_f32_16x16x32_bf16 v[92:95], v[72:75], v[212:215], v[92:95]
	v_mfma_f32_16x16x32_bf16 v[88:91], v[144:147], v[212:215], v[88:91]
	s_setprio 0
	s_setprio 1
	v_mfma_f32_16x16x32_bf16 v[132:135], v[148:151], v[164:167], 0
	v_mfma_f32_16x16x32_bf16 v[128:131], v[156:159], v[164:167], 0
	v_mfma_f32_16x16x32_bf16 v[116:119], v[148:151], v[172:175], 0
	v_mfma_f32_16x16x32_bf16 v[112:115], v[156:159], v[172:175], 0
	v_mfma_f32_16x16x32_bf16 v[100:103], v[148:151], v[200:203], 0
	v_mfma_f32_16x16x32_bf16 v[96:99], v[156:159], v[200:203], 0
	v_mfma_f32_16x16x32_bf16 v[84:87], v[148:151], v[208:211], 0
	v_mfma_f32_16x16x32_bf16 v[80:83], v[156:159], v[208:211], 0
	v_mfma_f32_16x16x32_bf16 v[132:135], v[152:155], v[168:171], v[132:135]
	v_mfma_f32_16x16x32_bf16 v[128:131], v[160:163], v[168:171], v[128:131]
	v_mfma_f32_16x16x32_bf16 v[116:119], v[152:155], v[196:199], v[116:119]
	v_mfma_f32_16x16x32_bf16 v[112:115], v[160:163], v[196:199], v[112:115]
	v_mfma_f32_16x16x32_bf16 v[100:103], v[152:155], v[204:207], v[100:103]
	v_mfma_f32_16x16x32_bf16 v[96:99], v[160:163], v[204:207], v[96:99]
	v_mfma_f32_16x16x32_bf16 v[84:87], v[152:155], v[212:215], v[84:87]
	v_mfma_f32_16x16x32_bf16 v[80:83], v[160:163], v[212:215], v[80:83]
	s_setprio 0
	s_barrier
	s_add_i32 m0, s35, 0x10000
	ds_read_b128 v[164:167], v236 offset:16384
	ds_read_b128 v[168:171], v236 offset:17408
	ds_read_b128 v[172:175], v236 offset:18432
	ds_read_b128 v[196:199], v236 offset:19456
	ds_read_b128 v[200:203], v236 offset:20480
	ds_read_b128 v[204:207], v236 offset:21504
	ds_read_b128 v[208:211], v236 offset:22528
	ds_read_b128 v[212:215], v236 offset:23552
	global_load_lds_dwordx4 v176, s[74:75]
	s_add_i32 m0, s35, 0x12000
	s_add_u32 s76, s74, s22
	s_addc_u32 s77, s75, 0
	global_load_lds_dwordx4 v190, s[74:75]
	s_add_i32 m0, s35, 0x14000
	s_nop 0
	global_load_lds_dwordx4 v176, s[76:77]
	s_add_i32 m0, s35, 0x16000
	s_nop 0
	global_load_lds_dwordx4 v190, s[76:77]
	s_mov_b32 m0, s36
	s_nop 0
	global_load_lds_dwordx4 v186, s[4:5]
	s_mov_b32 m0, s37
	s_nop 0
	global_load_lds_dwordx4 v188, s[4:5]
	s_cmp_lg_u32 s30, 0
	s_cbranch_scc1 .Lmy_residp_rx2
	s_waitcnt vmcnt(8)
; #define PG8_STAGE(bufoff, gbase, voff) do { _Pragma("unroll") for (int _i = 0; _i < 2; ++_i) \
;         __builtin_amdgcn_global_load_lds((const unsigned*)((const char*)(gbase) + (voff)[_i]), (PG8_LAS unsigned*)(lds + (bufoff) + ldsw + _i * 8192), 16, 0, 0); } while (0)
; #define PG8_LDA(dst, b, h) do { _Pragma("unroll") for (int m = 0; m < 4; ++m) _Pragma("unroll") for (int k = 0; k < 2; ++k) dst[m][k] = *(const PG8_LAS bf16x8*)(lds + PG8_SA(b, h) + aoff + m * 2048 + k * 1024); } while (0)
; #define PG8_LDB(dst, b, h) do { _Pragma("unroll") for (int n = 0; n < 2; ++n) _Pragma("unroll") for (int k = 0; k < 2; ++k) dst[n][k] = *(const PG8_LAS bf16x8*)(lds + PG8_SB(b, h) + boff + n * 2048 + k * 1024); } while (0)
; #define PG8_MMA(ai, bj, At, Bt) do { __builtin_amdgcn_s_setprio(1); _Pragma("unroll") for (int m = 0; m < 4; ++m) _Pragma("unroll") for (int n = 0; n < 2; ++n) _Pragma("unroll") for (int k = 0; k < 2; ++k) \
;         acc[ai][bj][m][n] = __builtin_amdgcn_mfma_f32_16x16x32_bf16(Bt[n][k], At[m][k], acc[ai][bj][m][n], 0, 0, 0); __builtin_amdgcn_s_setprio(0); } while (0)
; #define PG8_WAIT_V(n) asm volatile("s_waitcnt vmcnt(" #n ")" ::: "memory")
; #define PG8_WAIT_L(n) asm volatile("s_waitcnt lgkmcnt(" #n ")" ::: "memory")
; #define PG8_BAR __builtin_amdgcn_s_barrier()
; #define PG8_SCHED __builtin_amdgcn_sched_barrier(0)
; template <class Epi, class Sched, bool ALIGN_EPI = false, bool SP2 = false>
; __device__ __forceinline__ void gemm_phase(PG8_LAS unsigned char* lds, const Gemm g, const Sched& S, const Epi& E) {
;     ...
;             asm volatile("s_cmp_lg_u32 %0, 0\n\ts_cbranch_scc1 .Lrelax%=\n\ts_waitcnt vmcnt(8)\n.Lrelax%=:\n\ts_waitcnt vmcnt(%1)" :: "s"(relax), "n"(8 + Epi::NST) : "memory", "scc");
;             PG8_WAIT_L(0); PG8_BAR; PG8_MMA(1, 0, At, B0); PG8_MMA(1, 1, At, B1); PG8_BAR; PG8_SCHED;
;             PG8_LDB(B0, 1, 0); PG8_LDB(B1, 1, 1); PG8_SCHED; PG8_LDA(At, 1, 0); PG8_STAGE(PG8_SA(0, 1), a2 + hstep, voffA);
;             PG8_WAIT_V(8); PG8_WAIT_L(0); PG8_BAR; PG8_MMA(0, 0, At, B0); PG8_MMA(0, 1, At, B1); PG8_BAR; PG8_SCHED;
.Lmy_residp_rx2:
	s_waitcnt vmcnt(32)
	s_waitcnt lgkmcnt(0)
	s_setprio 1
	s_barrier
	v_mfma_f32_16x16x32_bf16 v[60:63], v[68:71], v[164:167], 0
	v_mfma_f32_16x16x32_bf16 v[56:59], v[76:79], v[164:167], 0
	v_mfma_f32_16x16x32_bf16 v[44:47], v[68:71], v[172:175], 0
	v_mfma_f32_16x16x32_bf16 v[40:43], v[76:79], v[172:175], 0
	v_mfma_f32_16x16x32_bf16 v[28:31], v[68:71], v[200:203], 0
	v_mfma_f32_16x16x32_bf16 v[24:27], v[76:79], v[200:203], 0
	v_mfma_f32_16x16x32_bf16 v[12:15], v[68:71], v[208:211], 0
	v_mfma_f32_16x16x32_bf16 v[8:11], v[76:79], v[208:211], 0
	v_mfma_f32_16x16x32_bf16 v[60:63], v[72:75], v[168:171], v[60:63]
	v_mfma_f32_16x16x32_bf16 v[56:59], v[144:147], v[168:171], v[56:59]
	v_mfma_f32_16x16x32_bf16 v[44:47], v[72:75], v[196:199], v[44:47]
	v_mfma_f32_16x16x32_bf16 v[40:43], v[144:147], v[196:199], v[40:43]
	v_mfma_f32_16x16x32_bf16 v[28:31], v[72:75], v[204:207], v[28:31]
	v_mfma_f32_16x16x32_bf16 v[24:27], v[144:147], v[204:207], v[24:27]
	v_mfma_f32_16x16x32_bf16 v[12:15], v[72:75], v[212:215], v[12:15]
	v_mfma_f32_16x16x32_bf16 v[8:11], v[144:147], v[212:215], v[8:11]
	s_setprio 0
	s_setprio 1
	v_mfma_f32_16x16x32_bf16 v[52:55], v[148:151], v[164:167], 0
	v_mfma_f32_16x16x32_bf16 v[48:51], v[156:159], v[164:167], 0
	v_mfma_f32_16x16x32_bf16 v[36:39], v[148:151], v[172:175], 0
	v_mfma_f32_16x16x32_bf16 v[32:35], v[156:159], v[172:175], 0
	v_mfma_f32_16x16x32_bf16 v[20:23], v[148:151], v[200:203], 0
	v_mfma_f32_16x16x32_bf16 v[16:19], v[156:159], v[200:203], 0
	v_mfma_f32_16x16x32_bf16 v[4:7], v[148:151], v[208:211], 0
	v_mfma_f32_16x16x32_bf16 v[0:3], v[156:159], v[208:211], 0
	v_mfma_f32_16x16x32_bf16 v[52:55], v[152:155], v[168:171], v[52:55]
	v_mfma_f32_16x16x32_bf16 v[48:51], v[160:163], v[168:171], v[48:51]
	v_mfma_f32_16x16x32_bf16 v[36:39], v[152:155], v[196:199], v[36:39]
	v_mfma_f32_16x16x32_bf16 v[32:35], v[160:163], v[196:199], v[32:35]
	v_mfma_f32_16x16x32_bf16 v[20:23], v[152:155], v[204:207], v[20:23]
	v_mfma_f32_16x16x32_bf16 v[16:19], v[160:163], v[204:207], v[16:19]
	v_mfma_f32_16x16x32_bf16 v[4:7], v[152:155], v[212:215], v[4:7]
	v_mfma_f32_16x16x32_bf16 v[0:3], v[160:163], v[212:215], v[0:3]
	s_setprio 0
	s_barrier
	ds_read_b128 v[68:71], v216 offset:32768
	ds_read_b128 v[72:75], v216 offset:33792
	ds_read_b128 v[76:79], v216 offset:34816
	ds_read_b128 v[144:147], v216 offset:35840
	ds_read_b128 v[148:151], v216 offset:49152
	ds_read_b128 v[152:155], v216 offset:50176
	ds_read_b128 v[156:159], v216 offset:51200
	ds_read_b128 v[160:163], v216 offset:52224
	s_add_u32 s4, s4, s22
	s_addc_u32 s5, s5, 0
	s_mov_b32 m0, s58
	ds_read_b128 v[164:167], v236 offset:32768
	ds_read_b128 v[168:171], v236 offset:33792
	ds_read_b128 v[172:175], v236 offset:34816
	ds_read_b128 v[196:199], v236 offset:35840
	ds_read_b128 v[200:203], v236 offset:36864
	ds_read_b128 v[204:207], v236 offset:37888
	ds_read_b128 v[208:211], v236 offset:38912
	ds_read_b128 v[212:215], v236 offset:39936
	global_load_lds_dwordx4 v186, s[4:5]
	s_mov_b32 m0, s59
	s_nop 0
	global_load_lds_dwordx4 v188, s[4:5]
	s_waitcnt vmcnt(8)
	s_waitcnt lgkmcnt(0)
	s_setprio 1
	s_barrier
	v_mfma_f32_16x16x32_bf16 v[140:143], v[68:71], v[164:167], v[140:143]
	v_mfma_f32_16x16x32_bf16 v[136:139], v[76:79], v[164:167], v[136:139]
	v_mfma_f32_16x16x32_bf16 v[124:127], v[68:71], v[172:175], v[124:127]
	v_mfma_f32_16x16x32_bf16 v[120:123], v[76:79], v[172:175], v[120:123]
	v_mfma_f32_16x16x32_bf16 v[108:111], v[68:71], v[200:203], v[108:111]
	v_mfma_f32_16x16x32_bf16 v[104:107], v[76:79], v[200:203], v[104:107]
	v_mfma_f32_16x16x32_bf16 v[92:95], v[68:71], v[208:211], v[92:95]
	v_mfma_f32_16x16x32_bf16 v[88:91], v[76:79], v[208:211], v[88:91]
	v_mfma_f32_16x16x32_bf16 v[140:143], v[72:75], v[168:171], v[140:143]
	v_mfma_f32_16x16x32_bf16 v[136:139], v[144:147], v[168:171], v[136:139]
	v_mfma_f32_16x16x32_bf16 v[124:127], v[72:75], v[196:199], v[124:127]
	v_mfma_f32_16x16x32_bf16 v[120:123], v[144:147], v[196:199], v[120:123]
	v_mfma_f32_16x16x32_bf16 v[108:111], v[72:75], v[204:207], v[108:111]
	v_mfma_f32_16x16x32_bf16 v[104:107], v[144:147], v[204:207], v[104:107]
	v_mfma_f32_16x16x32_bf16 v[92:95], v[72:75], v[212:215], v[92:95]
	v_mfma_f32_16x16x32_bf16 v[88:91], v[144:147], v[212:215], v[88:91]
	s_setprio 0
	s_setprio 1
	v_mfma_f32_16x16x32_bf16 v[132:135], v[148:151], v[164:167], v[132:135]
	v_mfma_f32_16x16x32_bf16 v[128:131], v[156:159], v[164:167], v[128:131]
	v_mfma_f32_16x16x32_bf16 v[116:119], v[148:151], v[172:175], v[116:119]
	v_mfma_f32_16x16x32_bf16 v[112:115], v[156:159], v[172:175], v[112:115]
	v_mfma_f32_16x16x32_bf16 v[100:103], v[148:151], v[200:203], v[100:103]
	v_mfma_f32_16x16x32_bf16 v[96:99], v[156:159], v[200:203], v[96:99]
	v_mfma_f32_16x16x32_bf16 v[84:87], v[148:151], v[208:211], v[84:87]
	v_mfma_f32_16x16x32_bf16 v[80:83], v[156:159], v[208:211], v[80:83]
	v_mfma_f32_16x16x32_bf16 v[132:135], v[152:155], v[168:171], v[132:135]
	v_mfma_f32_16x16x32_bf16 v[128:131], v[160:163], v[168:171], v[128:131]
	v_mfma_f32_16x16x32_bf16 v[116:119], v[152:155], v[196:199], v[116:119]
	v_mfma_f32_16x16x32_bf16 v[112:115], v[160:163], v[196:199], v[112:115]
	v_mfma_f32_16x16x32_bf16 v[100:103], v[152:155], v[204:207], v[100:103]
	v_mfma_f32_16x16x32_bf16 v[96:99], v[160:163], v[204:207], v[96:99]
	v_mfma_f32_16x16x32_bf16 v[84:87], v[152:155], v[212:215], v[84:87]
	v_mfma_f32_16x16x32_bf16 v[80:83], v[160:163], v[212:215], v[80:83]
	s_setprio 0
	s_barrier
; #define PG8_STAGE(bufoff, gbase, voff) do { _Pragma("unroll") for (int _i = 0; _i < 2; ++_i) \
;         __builtin_amdgcn_global_load_lds((const unsigned*)((const char*)(gbase) + (voff)[_i]), (PG8_LAS unsigned*)(lds + (bufoff) + ldsw + _i * 8192), 16, 0, 0); } while (0)
; #define PG8_LDA(dst, b, h) do { _Pragma("unroll") for (int m = 0; m < 4; ++m) _Pragma("unroll") for (int k = 0; k < 2; ++k) dst[m][k] = *(const PG8_LAS bf16x8*)(lds + PG8_SA(b, h) + aoff + m * 2048 + k * 1024); } while (0)
; #define PG8_LDB(dst, b, h) do { _Pragma("unroll") for (int n = 0; n < 2; ++n) _Pragma("unroll") for (int k = 0; k < 2; ++k) dst[n][k] = *(const PG8_LAS bf16x8*)(lds + PG8_SB(b, h) + boff + n * 2048 + k * 1024); } while (0)
; #define PG8_WAIT_V(n) asm volatile("s_waitcnt vmcnt(" #n ")" ::: "memory")
; #define PG8_WAIT_L(n) asm volatile("s_waitcnt lgkmcnt(" #n ")" ::: "memory")
; #define PG8_BAR __builtin_amdgcn_s_barrier()
; #define PG8_SCHED __builtin_amdgcn_sched_barrier(0)
; template <class Epi, class Sched, bool ALIGN_EPI = false, bool SP2 = false>
; __device__ __forceinline__ void gemm_phase(PG8_LAS unsigned char* lds, const Gemm g, const Sched& S, const Epi& E) {
;     ...
;         for (int t = 0; t < nt; t += 2) {
;             const bool last = (t == nt - 2);
;             const char* a1 = cA + (size_t)(t + 1) * kstep;
;             const char* a2 = last ? nA : cA + (size_t)(t + 2) * kstep; const char* b2 = last ? nB : cB + (size_t)(t + 2) * kstep;
;             const char* a3 = a2 + kstep; const char* b3 = b2 + kstep;
;             if (last && has_next) S.a_ready(nxt);
;             if constexpr (SP2) {
;             const int relax = __builtin_amdgcn_readfirstlane((t == 0 && ui > 0) ? 1 : 0);
;             PG8_LDB(B0, 0, 0); PG8_LDB(B1, 0, 1); PG8_SCHED; PG8_LDA(At, 0, 0); PG8_STAGE(PG8_SA(1, 1), a1 + hstep, voffA);
;             asm volatile("s_cmp_lg_u32 %0, 0\n\ts_cbranch_scc1 .Lrelax%=\n\ts_waitcnt vmcnt(8)\n.Lrelax%=:\n\ts_waitcnt vmcnt(%1)" :: "s"(relax), "n"(8 + Epi::NST) : "memory", "scc");
;             PG8_WAIT_L(0); PG8_BAR; PG8_MMA(0, 0, At, B0); PG8_MMA(0, 1, At, B1); PG8_BAR; PG8_SCHED;
;     ...
;             PG8_LDA(At, 1, 1); PG8_STAGE(PG8_SB(1, 0), b3, voffB); PG8_STAGE(PG8_SB(1, 1), b3 + hstep, voffB); PG8_STAGE(PG8_SA(1, 0), a3, voffA);
;             PG8_WAIT_V(8); PG8_WAIT_L(0); PG8_BAR; PG8_MMA(1, 0, At, B0); PG8_MMA(1, 1, At, B1); PG8_BAR; PG8_SCHED;
	s_add_i32 m0, s35, 0x18000
	s_add_u32 s74, s74, 0x80
	s_addc_u32 s75, s75, 0
	ds_read_b128 v[164:167], v236 offset:49152
	ds_read_b128 v[168:171], v236 offset:50176
	ds_read_b128 v[172:175], v236 offset:51200
	ds_read_b128 v[196:199], v236 offset:52224
	ds_read_b128 v[200:203], v236 offset:53248
	ds_read_b128 v[204:207], v236 offset:54272
	ds_read_b128 v[208:211], v236 offset:55296
	ds_read_b128 v[212:215], v236 offset:56320
	global_load_lds_dwordx4 v176, s[74:75]
	s_add_i32 m0, s35, 0x1a000
	s_add_u32 s76, s74, s22
	s_addc_u32 s77, s75, 0
	global_load_lds_dwordx4 v190, s[74:75]
	s_add_i32 m0, s35, 0x1c000
	s_sub_u32 s4, s4, s22
	s_subb_u32 s5, s5, 0
	global_load_lds_dwordx4 v176, s[76:77]
	s_add_i32 m0, s35, 0x1e000
	s_add_u32 s4, s4, 0x80
	s_addc_u32 s5, s5, 0
	global_load_lds_dwordx4 v190, s[76:77]
	s_mov_b32 m0, s60
	s_nop 0
	global_load_lds_dwordx4 v186, s[4:5]
	s_mov_b32 m0, s61
	s_nop 0
	global_load_lds_dwordx4 v188, s[4:5]
	s_waitcnt vmcnt(8)
	s_waitcnt lgkmcnt(0)
	s_setprio 1
	s_barrier
	v_mfma_f32_16x16x32_bf16 v[60:63], v[68:71], v[164:167], v[60:63]
	v_mfma_f32_16x16x32_bf16 v[56:59], v[76:79], v[164:167], v[56:59]
	v_mfma_f32_16x16x32_bf16 v[44:47], v[68:71], v[172:175], v[44:47]
	v_mfma_f32_16x16x32_bf16 v[40:43], v[76:79], v[172:175], v[40:43]
	v_mfma_f32_16x16x32_bf16 v[28:31], v[68:71], v[200:203], v[28:31]
	v_mfma_f32_16x16x32_bf16 v[24:27], v[76:79], v[200:203], v[24:27]
	v_mfma_f32_16x16x32_bf16 v[12:15], v[68:71], v[208:211], v[12:15]
	v_mfma_f32_16x16x32_bf16 v[8:11], v[76:79], v[208:211], v[8:11]
	v_mfma_f32_16x16x32_bf16 v[60:63], v[72:75], v[168:171], v[60:63]
	v_mfma_f32_16x16x32_bf16 v[56:59], v[144:147], v[168:171], v[56:59]
	v_mfma_f32_16x16x32_bf16 v[44:47], v[72:75], v[196:199], v[44:47]
	v_mfma_f32_16x16x32_bf16 v[40:43], v[144:147], v[196:199], v[40:43]
	v_mfma_f32_16x16x32_bf16 v[28:31], v[72:75], v[204:207], v[28:31]
	v_mfma_f32_16x16x32_bf16 v[24:27], v[144:147], v[204:207], v[24:27]
	v_mfma_f32_16x16x32_bf16 v[12:15], v[72:75], v[212:215], v[12:15]
	v_mfma_f32_16x16x32_bf16 v[8:11], v[144:147], v[212:215], v[8:11]
	s_setprio 0
	s_setprio 1
	v_mfma_f32_16x16x32_bf16 v[52:55], v[148:151], v[164:167], v[52:55]
	v_mfma_f32_16x16x32_bf16 v[48:51], v[156:159], v[164:167], v[48:51]
	v_mfma_f32_16x16x32_bf16 v[36:39], v[148:151], v[172:175], v[36:39]
	v_mfma_f32_16x16x32_bf16 v[32:35], v[156:159], v[172:175], v[32:35]
	v_mfma_f32_16x16x32_bf16 v[20:23], v[148:151], v[200:203], v[20:23]
	v_mfma_f32_16x16x32_bf16 v[16:19], v[156:159], v[200:203], v[16:19]
	v_mfma_f32_16x16x32_bf16 v[4:7], v[148:151], v[208:211], v[4:7]
	v_mfma_f32_16x16x32_bf16 v[0:3], v[156:159], v[208:211], v[0:3]
	v_mfma_f32_16x16x32_bf16 v[52:55], v[152:155], v[168:171], v[52:55]
	v_mfma_f32_16x16x32_bf16 v[48:51], v[160:163], v[168:171], v[48:51]
	v_mfma_f32_16x16x32_bf16 v[36:39], v[152:155], v[196:199], v[36:39]
	v_mfma_f32_16x16x32_bf16 v[32:35], v[160:163], v[196:199], v[32:35]
	v_mfma_f32_16x16x32_bf16 v[20:23], v[152:155], v[204:207], v[20:23]
	v_mfma_f32_16x16x32_bf16 v[16:19], v[160:163], v[204:207], v[16:19]
	v_mfma_f32_16x16x32_bf16 v[4:7], v[152:155], v[212:215], v[4:7]
	v_mfma_f32_16x16x32_bf16 v[0:3], v[160:163], v[212:215], v[0:3]
	s_setprio 0
	s_barrier
	s_add_u32 s42, s42, 0x100
	s_addc_u32 s43, s43, 0
	s_cmp_ge_u32 s72, s63
	s_mov_b32 s71, s72
.LBB0_193:
	s_add_i32 s72, s71, 2
	s_add_u32 s4, s28, s42
	s_addc_u32 s5, s29, s43
	s_add_u32 s76, s4, 0x80
	s_addc_u32 s77, s5, 0
	s_add_u32 s4, s4, 0x100
	s_addc_u32 s5, s5, 0
	s_add_u32 s74, s2, s42
	s_addc_u32 s75, s70, s43
	s_cmp_eq_u32 s64, s71
	s_cselect_b32 s5, s55, s5
	s_cselect_b32 s4, s54, s4
	s_cselect_b32 s75, s57, s75
	s_cselect_b32 s74, s56, s74
	ds_read_b128 v[68:71], v216
	ds_read_b128 v[72:75], v216 offset:1024
	ds_read_b128 v[76:79], v216 offset:2048
	ds_read_b128 v[144:147], v216 offset:3072
	ds_read_b128 v[148:151], v216 offset:16384
	ds_read_b128 v[152:155], v216 offset:17408
	ds_read_b128 v[156:159], v216 offset:18432
	ds_read_b128 v[160:163], v216 offset:19456
	s_add_i32 m0, s36, 0xc000
	ds_read_b128 v[164:167], v236
	ds_read_b128 v[168:171], v236 offset:1024
	ds_read_b128 v[172:175], v236 offset:2048
	ds_read_b128 v[196:199], v236 offset:3072
	ds_read_b128 v[200:203], v236 offset:4096
	ds_read_b128 v[204:207], v236 offset:5120
	ds_read_b128 v[208:211], v236 offset:6144
	ds_read_b128 v[212:215], v236 offset:7168
	global_load_lds_dwordx4 v192, s[76:77]
	s_add_i32 m0, s36, 0xe000
	s_nop 0
	global_load_lds_dwordx4 v194, s[76:77]
	s_waitcnt vmcnt(8)
	s_waitcnt lgkmcnt(0)
	s_setprio 1
	s_barrier
; #define PG8_STAGE(bufoff, gbase, voff) do { _Pragma("unroll") for (int _i = 0; _i < 2; ++_i) \
;         __builtin_amdgcn_global_load_lds((const unsigned*)((const char*)(gbase) + (voff)[_i]), (PG8_LAS unsigned*)(lds + (bufoff) + ldsw + _i * 8192), 16, 0, 0); } while (0)
; #define PG8_LDA(dst, b, h) do { _Pragma("unroll") for (int m = 0; m < 4; ++m) _Pragma("unroll") for (int k = 0; k < 2; ++k) dst[m][k] = *(const PG8_LAS bf16x8*)(lds + PG8_SA(b, h) + aoff + m * 2048 + k * 1024); } while (0)
; #define PG8_MMA(ai, bj, At, Bt) do { __builtin_amdgcn_s_setprio(1); _Pragma("unroll") for (int m = 0; m < 4; ++m) _Pragma("unroll") for (int n = 0; n < 2; ++n) _Pragma("unroll") for (int k = 0; k < 2; ++k) \
;         acc[ai][bj][m][n] = __builtin_amdgcn_mfma_f32_16x16x32_bf16(Bt[n][k], At[m][k], acc[ai][bj][m][n], 0, 0, 0); __builtin_amdgcn_s_setprio(0); } while (0)
; #define PG8_WAIT_L(n) asm volatile("s_waitcnt lgkmcnt(" #n ")" ::: "memory")
; #define PG8_BAR __builtin_amdgcn_s_barrier()
; #define PG8_SCHED __builtin_amdgcn_sched_barrier(0)
; template <class Epi, class Sched, bool ALIGN_EPI = false, bool SP2 = false>
; __device__ __forceinline__ void gemm_phase(PG8_LAS unsigned char* lds, const Gemm g, const Sched& S, const Epi& E) {
;     ...
;             PG8_WAIT_L(0); PG8_BAR; PG8_MMA(0, 0, At, B0); PG8_MMA(0, 1, At, B1); PG8_BAR; PG8_SCHED;
;             PG8_LDA(At, 0, 1); PG8_STAGE(PG8_SB(0, 0), b2, voffB); PG8_STAGE(PG8_SB(0, 1), b2 + hstep, voffB); PG8_STAGE(PG8_SA(0, 0), a2, voffA);
;             asm volatile("s_cmp_lg_u32 %0, 0\n\ts_cbranch_scc1 .Lrelax%=\n\ts_waitcnt vmcnt(8)\n.Lrelax%=:\n\ts_waitcnt vmcnt(%1)" :: "s"(relax), "n"(8 + Epi::NST) : "memory", "scc");
;             PG8_WAIT_L(0); PG8_BAR; PG8_MMA(1, 0, At, B0); PG8_MMA(1, 1, At, B1); PG8_BAR; PG8_SCHED;
	v_mfma_f32_16x16x32_bf16 v[140:143], v[68:71], v[164:167], v[140:143]
	v_mfma_f32_16x16x32_bf16 v[136:139], v[76:79], v[164:167], v[136:139]
	v_mfma_f32_16x16x32_bf16 v[124:127], v[68:71], v[172:175], v[124:127]
	v_mfma_f32_16x16x32_bf16 v[120:123], v[76:79], v[172:175], v[120:123]
	v_mfma_f32_16x16x32_bf16 v[108:111], v[68:71], v[200:203], v[108:111]
	v_mfma_f32_16x16x32_bf16 v[104:107], v[76:79], v[200:203], v[104:107]
	v_mfma_f32_16x16x32_bf16 v[92:95], v[68:71], v[208:211], v[92:95]
	v_mfma_f32_16x16x32_bf16 v[88:91], v[76:79], v[208:211], v[88:91]
	v_mfma_f32_16x16x32_bf16 v[140:143], v[72:75], v[168:171], v[140:143]
	v_mfma_f32_16x16x32_bf16 v[136:139], v[144:147], v[168:171], v[136:139]
	v_mfma_f32_16x16x32_bf16 v[124:127], v[72:75], v[196:199], v[124:127]
	v_mfma_f32_16x16x32_bf16 v[120:123], v[144:147], v[196:199], v[120:123]
	v_mfma_f32_16x16x32_bf16 v[108:111], v[72:75], v[204:207], v[108:111]
	v_mfma_f32_16x16x32_bf16 v[104:107], v[144:147], v[204:207], v[104:107]
	v_mfma_f32_16x16x32_bf16 v[92:95], v[72:75], v[212:215], v[92:95]
	v_mfma_f32_16x16x32_bf16 v[88:91], v[144:147], v[212:215], v[88:91]
	s_setprio 0
	s_setprio 1
	v_mfma_f32_16x16x32_bf16 v[132:135], v[148:151], v[164:167], v[132:135]
	v_mfma_f32_16x16x32_bf16 v[128:131], v[156:159], v[164:167], v[128:131]
	v_mfma_f32_16x16x32_bf16 v[116:119], v[148:151], v[172:175], v[116:119]
	v_mfma_f32_16x16x32_bf16 v[112:115], v[156:159], v[172:175], v[112:115]
	v_mfma_f32_16x16x32_bf16 v[100:103], v[148:151], v[200:203], v[100:103]
	v_mfma_f32_16x16x32_bf16 v[96:99], v[156:159], v[200:203], v[96:99]
	v_mfma_f32_16x16x32_bf16 v[84:87], v[148:151], v[208:211], v[84:87]
	v_mfma_f32_16x16x32_bf16 v[80:83], v[156:159], v[208:211], v[80:83]
	v_mfma_f32_16x16x32_bf16 v[132:135], v[152:155], v[168:171], v[132:135]
	v_mfma_f32_16x16x32_bf16 v[128:131], v[160:163], v[168:171], v[128:131]
	v_mfma_f32_16x16x32_bf16 v[116:119], v[152:155], v[196:199], v[116:119]
	v_mfma_f32_16x16x32_bf16 v[112:115], v[160:163], v[196:199], v[112:115]
	v_mfma_f32_16x16x32_bf16 v[100:103], v[152:155], v[204:207], v[100:103]
	v_mfma_f32_16x16x32_bf16 v[96:99], v[160:163], v[204:207], v[96:99]
	v_mfma_f32_16x16x32_bf16 v[84:87], v[152:155], v[212:215], v[84:87]
	v_mfma_f32_16x16x32_bf16 v[80:83], v[160:163], v[212:215], v[80:83]
	s_setprio 0
	s_barrier
	s_add_i32 m0, s35, 0x10000
	ds_read_b128 v[164:167], v236 offset:16384
	ds_read_b128 v[168:171], v236 offset:17408
	ds_read_b128 v[172:175], v236 offset:18432
	ds_read_b128 v[196:199], v236 offset:19456
	ds_read_b128 v[200:203], v236 offset:20480
	ds_read_b128 v[204:207], v236 offset:21504
	ds_read_b128 v[208:211], v236 offset:22528
	ds_read_b128 v[212:215], v236 offset:23552
	global_load_lds_dwordx4 v176, s[74:75]
	s_add_i32 m0, s35, 0x12000
	s_add_u32 s76, s74, s22
	s_addc_u32 s77, s75, 0
	global_load_lds_dwordx4 v190, s[74:75]
	s_add_i32 m0, s35, 0x14000
	s_nop 0
	global_load_lds_dwordx4 v176, s[76:77]
	s_add_i32 m0, s35, 0x16000
	s_nop 0
	global_load_lds_dwordx4 v190, s[76:77]
	s_mov_b32 m0, s36
	s_nop 0
	global_load_lds_dwordx4 v186, s[4:5]
	s_mov_b32 m0, s37
	s_nop 0
	global_load_lds_dwordx4 v188, s[4:5]
	s_waitcnt vmcnt(8)
	s_waitcnt lgkmcnt(0)
	s_setprio 1
	s_barrier
	v_mfma_f32_16x16x32_bf16 v[60:63], v[68:71], v[164:167], v[60:63]
	v_mfma_f32_16x16x32_bf16 v[56:59], v[76:79], v[164:167], v[56:59]
	v_mfma_f32_16x16x32_bf16 v[44:47], v[68:71], v[172:175], v[44:47]
	v_mfma_f32_16x16x32_bf16 v[40:43], v[76:79], v[172:175], v[40:43]
	v_mfma_f32_16x16x32_bf16 v[28:31], v[68:71], v[200:203], v[28:31]
	v_mfma_f32_16x16x32_bf16 v[24:27], v[76:79], v[200:203], v[24:27]
	v_mfma_f32_16x16x32_bf16 v[12:15], v[68:71], v[208:211], v[12:15]
	v_mfma_f32_16x16x32_bf16 v[8:11], v[76:79], v[208:211], v[8:11]
	v_mfma_f32_16x16x32_bf16 v[60:63], v[72:75], v[168:171], v[60:63]
	v_mfma_f32_16x16x32_bf16 v[56:59], v[144:147], v[168:171], v[56:59]
	v_mfma_f32_16x16x32_bf16 v[44:47], v[72:75], v[196:199], v[44:47]
	v_mfma_f32_16x16x32_bf16 v[40:43], v[144:147], v[196:199], v[40:43]
	v_mfma_f32_16x16x32_bf16 v[28:31], v[72:75], v[204:207], v[28:31]
	v_mfma_f32_16x16x32_bf16 v[24:27], v[144:147], v[204:207], v[24:27]
	v_mfma_f32_16x16x32_bf16 v[12:15], v[72:75], v[212:215], v[12:15]
	v_mfma_f32_16x16x32_bf16 v[8:11], v[144:147], v[212:215], v[8:11]
	s_setprio 0
	s_setprio 1
	v_mfma_f32_16x16x32_bf16 v[52:55], v[148:151], v[164:167], v[52:55]
	v_mfma_f32_16x16x32_bf16 v[48:51], v[156:159], v[164:167], v[48:51]
	v_mfma_f32_16x16x32_bf16 v[36:39], v[148:151], v[172:175], v[36:39]
	v_mfma_f32_16x16x32_bf16 v[32:35], v[156:159], v[172:175], v[32:35]
	v_mfma_f32_16x16x32_bf16 v[20:23], v[148:151], v[200:203], v[20:23]
	v_mfma_f32_16x16x32_bf16 v[16:19], v[156:159], v[200:203], v[16:19]
	v_mfma_f32_16x16x32_bf16 v[4:7], v[148:151], v[208:211], v[4:7]
	v_mfma_f32_16x16x32_bf16 v[0:3], v[156:159], v[208:211], v[0:3]
	v_mfma_f32_16x16x32_bf16 v[52:55], v[152:155], v[168:171], v[52:55]
	v_mfma_f32_16x16x32_bf16 v[48:51], v[160:163], v[168:171], v[48:51]
	v_mfma_f32_16x16x32_bf16 v[36:39], v[152:155], v[196:199], v[36:39]
	v_mfma_f32_16x16x32_bf16 v[32:35], v[160:163], v[196:199], v[32:35]
	v_mfma_f32_16x16x32_bf16 v[20:23], v[152:155], v[204:207], v[20:23]
	v_mfma_f32_16x16x32_bf16 v[16:19], v[160:163], v[204:207], v[16:19]
	v_mfma_f32_16x16x32_bf16 v[4:7], v[152:155], v[212:215], v[4:7]
	v_mfma_f32_16x16x32_bf16 v[0:3], v[160:163], v[212:215], v[0:3]
	s_setprio 0
	s_barrier
; #define PG8_STAGE(bufoff, gbase, voff) do { _Pragma("unroll") for (int _i = 0; _i < 2; ++_i) \
;         __builtin_amdgcn_global_load_lds((const unsigned*)((const char*)(gbase) + (voff)[_i]), (PG8_LAS unsigned*)(lds + (bufoff) + ldsw + _i * 8192), 16, 0, 0); } while (0)
; #define PG8_LDA(dst, b, h) do { _Pragma("unroll") for (int m = 0; m < 4; ++m) _Pragma("unroll") for (int k = 0; k < 2; ++k) dst[m][k] = *(const PG8_LAS bf16x8*)(lds + PG8_SA(b, h) + aoff + m * 2048 + k * 1024); } while (0)
; #define PG8_LDB(dst, b, h) do { _Pragma("unroll") for (int n = 0; n < 2; ++n) _Pragma("unroll") for (int k = 0; k < 2; ++k) dst[n][k] = *(const PG8_LAS bf16x8*)(lds + PG8_SB(b, h) + boff + n * 2048 + k * 1024); } while (0)
; #define PG8_MMA(ai, bj, At, Bt) do { __builtin_amdgcn_s_setprio(1); _Pragma("unroll") for (int m = 0; m < 4; ++m) _Pragma("unroll") for (int n = 0; n < 2; ++n) _Pragma("unroll") for (int k = 0; k < 2; ++k) \
;         acc[ai][bj][m][n] = __builtin_amdgcn_mfma_f32_16x16x32_bf16(Bt[n][k], At[m][k], acc[ai][bj][m][n], 0, 0, 0); __builtin_amdgcn_s_setprio(0); } while (0)
; #define PG8_WAIT_V(n) asm volatile("s_waitcnt vmcnt(" #n ")" ::: "memory")
; #define PG8_WAIT_L(n) asm volatile("s_waitcnt lgkmcnt(" #n ")" ::: "memory")
; #define PG8_BAR __builtin_amdgcn_s_barrier()
; #define PG8_SCHED __builtin_amdgcn_sched_barrier(0)
; template <class Epi, class Sched, bool ALIGN_EPI = false, bool SP2 = false>
; __device__ __forceinline__ void gemm_phase(PG8_LAS unsigned char* lds, const Gemm g, const Sched& S, const Epi& E) {
;     ...
;             PG8_LDB(B0, 1, 0); PG8_LDB(B1, 1, 1); PG8_SCHED; PG8_LDA(At, 1, 0); PG8_STAGE(PG8_SA(0, 1), a2 + hstep, voffA);
;             PG8_WAIT_V(8); PG8_WAIT_L(0); PG8_BAR; PG8_MMA(0, 0, At, B0); PG8_MMA(0, 1, At, B1); PG8_BAR; PG8_SCHED;
;             PG8_LDA(At, 1, 1); PG8_STAGE(PG8_SB(1, 0), b3, voffB); PG8_STAGE(PG8_SB(1, 1), b3 + hstep, voffB); PG8_STAGE(PG8_SA(1, 0), a3, voffA);
;             PG8_WAIT_V(8); PG8_WAIT_L(0); PG8_BAR; PG8_MMA(1, 0, At, B0); PG8_MMA(1, 1, At, B1); PG8_BAR; PG8_SCHED;
	ds_read_b128 v[68:71], v216 offset:32768
	ds_read_b128 v[72:75], v216 offset:33792
	ds_read_b128 v[76:79], v216 offset:34816
	ds_read_b128 v[144:147], v216 offset:35840
	ds_read_b128 v[148:151], v216 offset:49152
	ds_read_b128 v[152:155], v216 offset:50176
	ds_read_b128 v[156:159], v216 offset:51200
	ds_read_b128 v[160:163], v216 offset:52224
	s_add_u32 s4, s4, s22
	s_addc_u32 s5, s5, 0
	s_mov_b32 m0, s58
	ds_read_b128 v[164:167], v236 offset:32768
	ds_read_b128 v[168:171], v236 offset:33792
	ds_read_b128 v[172:175], v236 offset:34816
	ds_read_b128 v[196:199], v236 offset:35840
	ds_read_b128 v[200:203], v236 offset:36864
	ds_read_b128 v[204:207], v236 offset:37888
	ds_read_b128 v[208:211], v236 offset:38912
	ds_read_b128 v[212:215], v236 offset:39936
	global_load_lds_dwordx4 v186, s[4:5]
	s_mov_b32 m0, s59
	s_nop 0
	global_load_lds_dwordx4 v188, s[4:5]
	s_waitcnt vmcnt(8)
	s_waitcnt lgkmcnt(0)
	s_setprio 1
	s_barrier
	v_mfma_f32_16x16x32_bf16 v[140:143], v[68:71], v[164:167], v[140:143]
	v_mfma_f32_16x16x32_bf16 v[136:139], v[76:79], v[164:167], v[136:139]
	v_mfma_f32_16x16x32_bf16 v[124:127], v[68:71], v[172:175], v[124:127]
	v_mfma_f32_16x16x32_bf16 v[120:123], v[76:79], v[172:175], v[120:123]
	v_mfma_f32_16x16x32_bf16 v[108:111], v[68:71], v[200:203], v[108:111]
	v_mfma_f32_16x16x32_bf16 v[104:107], v[76:79], v[200:203], v[104:107]
	v_mfma_f32_16x16x32_bf16 v[92:95], v[68:71], v[208:211], v[92:95]
	v_mfma_f32_16x16x32_bf16 v[88:91], v[76:79], v[208:211], v[88:91]
	v_mfma_f32_16x16x32_bf16 v[140:143], v[72:75], v[168:171], v[140:143]
	v_mfma_f32_16x16x32_bf16 v[136:139], v[144:147], v[168:171], v[136:139]
	v_mfma_f32_16x16x32_bf16 v[124:127], v[72:75], v[196:199], v[124:127]
	v_mfma_f32_16x16x32_bf16 v[120:123], v[144:147], v[196:199], v[120:123]
	v_mfma_f32_16x16x32_bf16 v[108:111], v[72:75], v[204:207], v[108:111]
	v_mfma_f32_16x16x32_bf16 v[104:107], v[144:147], v[204:207], v[104:107]
	v_mfma_f32_16x16x32_bf16 v[92:95], v[72:75], v[212:215], v[92:95]
	v_mfma_f32_16x16x32_bf16 v[88:91], v[144:147], v[212:215], v[88:91]
	s_setprio 0
	s_setprio 1
	v_mfma_f32_16x16x32_bf16 v[132:135], v[148:151], v[164:167], v[132:135]
	v_mfma_f32_16x16x32_bf16 v[128:131], v[156:159], v[164:167], v[128:131]
	v_mfma_f32_16x16x32_bf16 v[116:119], v[148:151], v[172:175], v[116:119]
	v_mfma_f32_16x16x32_bf16 v[112:115], v[156:159], v[172:175], v[112:115]
	v_mfma_f32_16x16x32_bf16 v[100:103], v[148:151], v[200:203], v[100:103]
	v_mfma_f32_16x16x32_bf16 v[96:99], v[156:159], v[200:203], v[96:99]
	v_mfma_f32_16x16x32_bf16 v[84:87], v[148:151], v[208:211], v[84:87]
	v_mfma_f32_16x16x32_bf16 v[80:83], v[156:159], v[208:211], v[80:83]
	v_mfma_f32_16x16x32_bf16 v[132:135], v[152:155], v[168:171], v[132:135]
	v_mfma_f32_16x16x32_bf16 v[128:131], v[160:163], v[168:171], v[128:131]
	v_mfma_f32_16x16x32_bf16 v[116:119], v[152:155], v[196:199], v[116:119]
	v_mfma_f32_16x16x32_bf16 v[112:115], v[160:163], v[196:199], v[112:115]
	v_mfma_f32_16x16x32_bf16 v[100:103], v[152:155], v[204:207], v[100:103]
	v_mfma_f32_16x16x32_bf16 v[96:99], v[160:163], v[204:207], v[96:99]
	v_mfma_f32_16x16x32_bf16 v[84:87], v[152:155], v[212:215], v[84:87]
	v_mfma_f32_16x16x32_bf16 v[80:83], v[160:163], v[212:215], v[80:83]
	s_setprio 0
	s_barrier
	s_add_i32 m0, s35, 0x18000
	s_add_u32 s74, s74, 0x80
	s_addc_u32 s75, s75, 0
	ds_read_b128 v[164:167], v236 offset:49152
	ds_read_b128 v[168:171], v236 offset:50176
	ds_read_b128 v[172:175], v236 offset:51200
	ds_read_b128 v[196:199], v236 offset:52224
	ds_read_b128 v[200:203], v236 offset:53248
	ds_read_b128 v[204:207], v236 offset:54272
	ds_read_b128 v[208:211], v236 offset:55296
	ds_read_b128 v[212:215], v236 offset:56320
	global_load_lds_dwordx4 v176, s[74:75]
	s_add_i32 m0, s35, 0x1a000
	s_add_u32 s76, s74, s22
	s_addc_u32 s77, s75, 0
	global_load_lds_dwordx4 v190, s[74:75]
	s_add_i32 m0, s35, 0x1c000
	s_sub_u32 s4, s4, s22
	s_subb_u32 s5, s5, 0
	global_load_lds_dwordx4 v176, s[76:77]
	s_add_i32 m0, s35, 0x1e000
	s_add_u32 s4, s4, 0x80
	s_addc_u32 s5, s5, 0
	global_load_lds_dwordx4 v190, s[76:77]
	s_mov_b32 m0, s60
	s_nop 0
	global_load_lds_dwordx4 v186, s[4:5]
	s_mov_b32 m0, s61
	s_nop 0
	global_load_lds_dwordx4 v188, s[4:5]
	s_waitcnt vmcnt(8)
	s_waitcnt lgkmcnt(0)
	s_setprio 1
	s_barrier
	v_mfma_f32_16x16x32_bf16 v[60:63], v[68:71], v[164:167], v[60:63]
	v_mfma_f32_16x16x32_bf16 v[56:59], v[76:79], v[164:167], v[56:59]
	v_mfma_f32_16x16x32_bf16 v[44:47], v[68:71], v[172:175], v[44:47]
	v_mfma_f32_16x16x32_bf16 v[40:43], v[76:79], v[172:175], v[40:43]
	v_mfma_f32_16x16x32_bf16 v[28:31], v[68:71], v[200:203], v[28:31]
	v_mfma_f32_16x16x32_bf16 v[24:27], v[76:79], v[200:203], v[24:27]
	v_mfma_f32_16x16x32_bf16 v[12:15], v[68:71], v[208:211], v[12:15]
	v_mfma_f32_16x16x32_bf16 v[8:11], v[76:79], v[208:211], v[8:11]
	v_mfma_f32_16x16x32_bf16 v[60:63], v[72:75], v[168:171], v[60:63]
	v_mfma_f32_16x16x32_bf16 v[56:59], v[144:147], v[168:171], v[56:59]
	v_mfma_f32_16x16x32_bf16 v[44:47], v[72:75], v[196:199], v[44:47]
	v_mfma_f32_16x16x32_bf16 v[40:43], v[144:147], v[196:199], v[40:43]
	v_mfma_f32_16x16x32_bf16 v[28:31], v[72:75], v[204:207], v[28:31]
	v_mfma_f32_16x16x32_bf16 v[24:27], v[144:147], v[204:207], v[24:27]
	v_mfma_f32_16x16x32_bf16 v[12:15], v[72:75], v[212:215], v[12:15]
	v_mfma_f32_16x16x32_bf16 v[8:11], v[144:147], v[212:215], v[8:11]
	s_setprio 0
	s_setprio 1
	v_mfma_f32_16x16x32_bf16 v[52:55], v[148:151], v[164:167], v[52:55]
	v_mfma_f32_16x16x32_bf16 v[48:51], v[156:159], v[164:167], v[48:51]
	v_mfma_f32_16x16x32_bf16 v[36:39], v[148:151], v[172:175], v[36:39]
	v_mfma_f32_16x16x32_bf16 v[32:35], v[156:159], v[172:175], v[32:35]
	v_mfma_f32_16x16x32_bf16 v[20:23], v[148:151], v[200:203], v[20:23]
	v_mfma_f32_16x16x32_bf16 v[16:19], v[156:159], v[200:203], v[16:19]
	v_mfma_f32_16x16x32_bf16 v[4:7], v[148:151], v[208:211], v[4:7]
	v_mfma_f32_16x16x32_bf16 v[0:3], v[156:159], v[208:211], v[0:3]
	v_mfma_f32_16x16x32_bf16 v[52:55], v[152:155], v[168:171], v[52:55]
	v_mfma_f32_16x16x32_bf16 v[48:51], v[160:163], v[168:171], v[48:51]
	v_mfma_f32_16x16x32_bf16 v[36:39], v[152:155], v[196:199], v[36:39]
	v_mfma_f32_16x16x32_bf16 v[32:35], v[160:163], v[196:199], v[32:35]
	v_mfma_f32_16x16x32_bf16 v[20:23], v[152:155], v[204:207], v[20:23]
	v_mfma_f32_16x16x32_bf16 v[16:19], v[160:163], v[204:207], v[16:19]
	v_mfma_f32_16x16x32_bf16 v[4:7], v[152:155], v[212:215], v[4:7]
	v_mfma_f32_16x16x32_bf16 v[0:3], v[160:163], v[212:215], v[0:3]
	s_setprio 0
	s_barrier
	s_add_u32 s42, s42, 0x100
	s_addc_u32 s43, s43, 0
	s_cmp_ge_u32 s72, s63
	s_mov_b32 s71, s72
	s_cbranch_scc0 .LBB0_193

; #define PG8_STAGE(bufoff, gbase, voff) do { _Pragma("unroll") for (int _i = 0; _i < 2; ++_i) \
;         __builtin_amdgcn_global_load_lds((const unsigned*)((const char*)(gbase) + (voff)[_i]), (PG8_LAS unsigned*)(lds + (bufoff) + ldsw + _i * 8192), 16, 0, 0); } while (0)
; #define PG8_LDA(dst, b, h) do { _Pragma("unroll") for (int m = 0; m < 4; ++m) _Pragma("unroll") for (int k = 0; k < 2; ++k) dst[m][k] = *(const PG8_LAS bf16x8*)(lds + PG8_SA(b, h) + aoff + m * 2048 + k * 1024); } while (0)
; #define PG8_WAIT_L(n) asm volatile("s_waitcnt lgkmcnt(" #n ")" ::: "memory")
; #define PG8_BAR __builtin_amdgcn_s_barrier()
; #define PG8_SCHED __builtin_amdgcn_sched_barrier(0)
; template <class Epi, class Sched, bool ALIGN_EPI = false, bool SP2 = false>
; __device__ __forceinline__ void gemm_phase(PG8_LAS unsigned char* lds, const Gemm g, const Sched& S, const Epi& E) {
;     ...
;         const bool has_next = S.next(ui + 1, nxt);
;         const char* nA = has_next ? (const char*)g.A + (size_t)nxt.pm * tstep : cA; const char* nB = has_next ? (const char*)g.Bt + (size_t)nxt.pn * tstep : cB;
;         for (int t = 0; t < nt; t += 2) {
;             const bool last = (t == nt - 2);
;             const char* a1 = cA + (size_t)(t + 1) * kstep;
;             const char* a2 = last ? nA : cA + (size_t)(t + 2) * kstep; const char* b2 = last ? nB : cB + (size_t)(t + 2) * kstep;
;             const char* a3 = a2 + kstep; const char* b3 = b2 + kstep;
;             if (last && has_next) S.a_ready(nxt);
;             if constexpr (SP2) {
;             const int relax = __builtin_amdgcn_readfirstlane((t == 0 && ui > 0) ? 1 : 0);
;             PG8_LDB(B0, 0, 0); PG8_LDB(B1, 0, 1); PG8_SCHED; PG8_LDA(At, 0, 0); PG8_STAGE(PG8_SA(1, 1), a1 + hstep, voffA);
;             asm volatile("s_cmp_lg_u32 %0, 0\n\ts_cbranch_scc1 .Lrelax%=\n\ts_waitcnt vmcnt(8)\n.Lrelax%=:\n\ts_waitcnt vmcnt(%1)" :: "s"(relax), "n"(8 + Epi::NST) : "memory", "scc");
;             PG8_WAIT_L(0); PG8_BAR; PG8_MMA(0, 0, At, B0); PG8_MMA(0, 1, At, B1); PG8_BAR; PG8_SCHED;
;             PG8_LDA(At, 0, 1); PG8_STAGE(PG8_SB(0, 0), b2, voffB); PG8_STAGE(PG8_SB(0, 1), b2 + hstep, voffB); PG8_STAGE(PG8_SA(0, 0), a2, voffA);
;             asm volatile("s_cmp_lg_u32 %0, 0\n\ts_cbranch_scc1 .Lrelax%=\n\ts_waitcnt vmcnt(8)\n.Lrelax%=:\n\ts_waitcnt vmcnt(%1)" :: "s"(relax), "n"(8 + Epi::NST) : "memory", "scc");
.LBB0_235:
	s_ashr_i32 s27, s26, 31
	s_lshl_b64 s[34:35], s[26:27], 19
	s_add_u32 s44, s82, s34
	s_addc_u32 s45, s83, s35
	s_and_b64 s[34:35], s[42:43], exec
	s_cselect_b32 s27, s45, s41
	s_cselect_b32 s59, s44, s40
	s_ashr_i32 s25, s24, 31
	s_lshl_b64 s[34:35], s[24:25], 19
	s_add_u32 s46, s2, s34
	s_addc_u32 s47, s37, s35
	s_and_b64 s[34:35], s[42:43], exec
	s_cselect_b32 s25, s47, s5
	s_cselect_b32 s60, s46, s4
	s_cmp_lg_u32 s58, 0
	s_cselect_b64 s[48:49], -1, 0
	s_add_u32 s34, s40, 0x40080
	s_addc_u32 s35, s41, 0
	s_add_u32 s61, s4, 0x100
	s_waitcnt vmcnt(8)
	v_lshl_add_u64 v[56:57], s[34:35], 0, v[144:145]
	v_lshl_add_u64 v[58:59], s[34:35], 0, v[146:147]
	s_addc_u32 s62, s5, 0
	s_mov_b32 s63, -2
	s_mov_b64 s[50:51], 0
	s_waitcnt lgkmcnt(0)
	v_add_u32_e32 v156, 0x10000, v161
	s_add_u32 s4, s40, s50
	s_addc_u32 s5, s41, s51
	s_add_u32 s64, s4, 0x40080
	s_addc_u32 s65, s5, 0
	s_add_u32 s34, s4, 0x100
	s_addc_u32 s35, s5, 0
	s_add_u32 s4, s61, s50
	s_addc_u32 s5, s62, s51
	s_cmpk_eq_i32 s50, 0x700
	s_cselect_b32 s35, s27, s35
	s_cselect_b32 s34, s59, s34
	s_cselect_b32 s5, s25, s5
	s_cselect_b32 s4, s60, s4
	ds_read_b128 v[60:63], v156
	ds_read_b128 v[148:151], v156 offset:1024
	ds_read_b128 v[152:155], v156 offset:2048
	ds_read_b128 v[166:169], v156 offset:3072
	ds_read_b128 v[170:173], v156 offset:16384
	ds_read_b128 v[186:189], v156 offset:17408
	ds_read_b128 v[190:193], v156 offset:18432
	ds_read_b128 v[194:197], v156 offset:19456
	s_add_i32 m0, s31, 0xc000
	ds_read_b128 v[198:201], v165
	ds_read_b128 v[202:205], v165 offset:1024
	ds_read_b128 v[206:209], v165 offset:2048
	ds_read_b128 v[210:213], v165 offset:3072
	ds_read_b128 v[214:217], v165 offset:4096
	ds_read_b128 v[234:237], v165 offset:5120
	ds_read_b128 v[238:241], v165 offset:6144
	ds_read_b128 v[242:245], v165 offset:7168
	global_load_lds_dwordx4 v144, s[64:65]
	s_add_i32 m0, s31, 0xe000
	s_nop 0
	global_load_lds_dwordx4 v146, s[64:65]
	s_cmp_lg_u32 s48, 0
	s_cbranch_scc1 .Lmy_swp_rx1
	s_waitcnt vmcnt(8)
.Lmy_swp_rx1:
	s_waitcnt vmcnt(16)
	s_waitcnt lgkmcnt(0)
	s_setprio 1
	s_barrier
	v_mfma_f32_16x16x32_bf16 v[132:135], v[60:63], v[198:201], 0
	v_mfma_f32_16x16x32_bf16 v[124:127], v[152:155], v[198:201], 0
	v_mfma_f32_16x16x32_bf16 v[116:119], v[60:63], v[206:209], 0
	v_mfma_f32_16x16x32_bf16 v[108:111], v[152:155], v[206:209], 0
	v_mfma_f32_16x16x32_bf16 v[100:103], v[60:63], v[214:217], 0
	v_mfma_f32_16x16x32_bf16 v[92:95], v[152:155], v[214:217], 0
	v_mfma_f32_16x16x32_bf16 v[84:87], v[60:63], v[238:241], 0
	v_mfma_f32_16x16x32_bf16 v[76:79], v[152:155], v[238:241], 0
	v_mfma_f32_16x16x32_bf16 v[132:135], v[148:151], v[202:205], v[132:135]
	v_mfma_f32_16x16x32_bf16 v[124:127], v[166:169], v[202:205], v[124:127]
	v_mfma_f32_16x16x32_bf16 v[116:119], v[148:151], v[210:213], v[116:119]
	v_mfma_f32_16x16x32_bf16 v[108:111], v[166:169], v[210:213], v[108:111]
	v_mfma_f32_16x16x32_bf16 v[100:103], v[148:151], v[234:237], v[100:103]
	v_mfma_f32_16x16x32_bf16 v[92:95], v[166:169], v[234:237], v[92:95]
	v_mfma_f32_16x16x32_bf16 v[84:87], v[148:151], v[242:245], v[84:87]
	v_mfma_f32_16x16x32_bf16 v[76:79], v[166:169], v[242:245], v[76:79]
	s_setprio 0
	s_setprio 1
	v_mfma_f32_16x16x32_bf16 v[128:131], v[170:173], v[198:201], 0
	v_mfma_f32_16x16x32_bf16 v[120:123], v[190:193], v[198:201], 0
	v_mfma_f32_16x16x32_bf16 v[112:115], v[170:173], v[206:209], 0
	v_mfma_f32_16x16x32_bf16 v[104:107], v[190:193], v[206:209], 0
	v_mfma_f32_16x16x32_bf16 v[96:99], v[170:173], v[214:217], 0
	v_mfma_f32_16x16x32_bf16 v[88:91], v[190:193], v[214:217], 0
	v_mfma_f32_16x16x32_bf16 v[80:83], v[170:173], v[238:241], 0
	v_mfma_f32_16x16x32_bf16 v[72:75], v[190:193], v[238:241], 0
	v_mfma_f32_16x16x32_bf16 v[128:131], v[186:189], v[202:205], v[128:131]
	v_mfma_f32_16x16x32_bf16 v[120:123], v[194:197], v[202:205], v[120:123]
	v_mfma_f32_16x16x32_bf16 v[112:115], v[186:189], v[210:213], v[112:115]
	v_mfma_f32_16x16x32_bf16 v[104:107], v[194:197], v[210:213], v[104:107]
	v_mfma_f32_16x16x32_bf16 v[96:99], v[186:189], v[234:237], v[96:99]
	v_mfma_f32_16x16x32_bf16 v[88:91], v[194:197], v[234:237], v[88:91]
	v_mfma_f32_16x16x32_bf16 v[80:83], v[186:189], v[242:245], v[80:83]
	v_mfma_f32_16x16x32_bf16 v[72:75], v[194:197], v[242:245], v[72:75]
	s_setprio 0
	s_barrier
	s_add_i32 m0, s29, 0x10000
	ds_read_b128 v[198:201], v165 offset:16384
	ds_read_b128 v[202:205], v165 offset:17408
	ds_read_b128 v[206:209], v165 offset:18432
	ds_read_b128 v[210:213], v165 offset:19456
	ds_read_b128 v[214:217], v165 offset:20480
	ds_read_b128 v[234:237], v165 offset:21504
	ds_read_b128 v[238:241], v165 offset:22528
	ds_read_b128 v[242:245], v165 offset:23552
	global_load_lds_dwordx4 v176, s[4:5]
	s_add_i32 m0, s29, 0x12000
	s_add_u32 s64, s4, 0x40000
	s_addc_u32 s65, s5, 0
	global_load_lds_dwordx4 v140, s[4:5]
	s_add_i32 m0, s29, 0x14000
	s_nop 0
	global_load_lds_dwordx4 v176, s[64:65]
	s_add_i32 m0, s29, 0x16000
	s_nop 0
	global_load_lds_dwordx4 v140, s[64:65]
	s_mov_b32 m0, s31
	s_nop 0
	global_load_lds_dwordx4 v136, s[34:35]
	s_mov_b32 m0, s52
	s_nop 0
	global_load_lds_dwordx4 v138, s[34:35]
	s_cmp_lg_u32 s48, 0
	s_cbranch_scc1 .Lmy_swp_rx2
	s_waitcnt vmcnt(8)
; #define PG8_STAGE(bufoff, gbase, voff) do { _Pragma("unroll") for (int _i = 0; _i < 2; ++_i) \
;         __builtin_amdgcn_global_load_lds((const unsigned*)((const char*)(gbase) + (voff)[_i]), (PG8_LAS unsigned*)(lds + (bufoff) + ldsw + _i * 8192), 16, 0, 0); } while (0)
; #define PG8_LDA(dst, b, h) do { _Pragma("unroll") for (int m = 0; m < 4; ++m) _Pragma("unroll") for (int k = 0; k < 2; ++k) dst[m][k] = *(const PG8_LAS bf16x8*)(lds + PG8_SA(b, h) + aoff + m * 2048 + k * 1024); } while (0)
; #define PG8_LDB(dst, b, h) do { _Pragma("unroll") for (int n = 0; n < 2; ++n) _Pragma("unroll") for (int k = 0; k < 2; ++k) dst[n][k] = *(const PG8_LAS bf16x8*)(lds + PG8_SB(b, h) + boff + n * 2048 + k * 1024); } while (0)
; #define PG8_MMA(ai, bj, At, Bt) do { __builtin_amdgcn_s_setprio(1); _Pragma("unroll") for (int m = 0; m < 4; ++m) _Pragma("unroll") for (int n = 0; n < 2; ++n) _Pragma("unroll") for (int k = 0; k < 2; ++k) \
;         acc[ai][bj][m][n] = __builtin_amdgcn_mfma_f32_16x16x32_bf16(Bt[n][k], At[m][k], acc[ai][bj][m][n], 0, 0, 0); __builtin_amdgcn_s_setprio(0); } while (0)
; #define PG8_WAIT_V(n) asm volatile("s_waitcnt vmcnt(" #n ")" ::: "memory")
; #define PG8_WAIT_L(n) asm volatile("s_waitcnt lgkmcnt(" #n ")" ::: "memory")
; #define PG8_BAR __builtin_amdgcn_s_barrier()
; #define PG8_SCHED __builtin_amdgcn_sched_barrier(0)
; template <class Epi, class Sched, bool ALIGN_EPI = false, bool SP2 = false>
; __device__ __forceinline__ void gemm_phase(PG8_LAS unsigned char* lds, const Gemm g, const Sched& S, const Epi& E) {
;     ...
;             asm volatile("s_cmp_lg_u32 %0, 0\n\ts_cbranch_scc1 .Lrelax%=\n\ts_waitcnt vmcnt(8)\n.Lrelax%=:\n\ts_waitcnt vmcnt(%1)" :: "s"(relax), "n"(8 + Epi::NST) : "memory", "scc");
;             PG8_WAIT_L(0); PG8_BAR; PG8_MMA(1, 0, At, B0); PG8_MMA(1, 1, At, B1); PG8_BAR; PG8_SCHED;
;             PG8_LDB(B0, 1, 0); PG8_LDB(B1, 1, 1); PG8_SCHED; PG8_LDA(At, 1, 0); PG8_STAGE(PG8_SA(0, 1), a2 + hstep, voffA);
;             PG8_WAIT_V(8); PG8_WAIT_L(0); PG8_BAR; PG8_MMA(0, 0, At, B0); PG8_MMA(0, 1, At, B1); PG8_BAR; PG8_SCHED;
.Lmy_swp_rx2:
	s_waitcnt vmcnt(16)
	s_waitcnt lgkmcnt(0)
	s_setprio 1
	s_barrier
	v_mfma_f32_16x16x32_bf16 v[68:71], v[60:63], v[198:201], 0
	v_mfma_f32_16x16x32_bf16 v[52:55], v[152:155], v[198:201], 0
	v_mfma_f32_16x16x32_bf16 v[44:47], v[60:63], v[206:209], 0
	v_mfma_f32_16x16x32_bf16 v[36:39], v[152:155], v[206:209], 0
	v_mfma_f32_16x16x32_bf16 v[28:31], v[60:63], v[214:217], 0
	v_mfma_f32_16x16x32_bf16 v[20:23], v[152:155], v[214:217], 0
	v_mfma_f32_16x16x32_bf16 v[12:15], v[60:63], v[238:241], 0
	v_mfma_f32_16x16x32_bf16 v[4:7], v[152:155], v[238:241], 0
	v_mfma_f32_16x16x32_bf16 v[68:71], v[148:151], v[202:205], v[68:71]
	v_mfma_f32_16x16x32_bf16 v[52:55], v[166:169], v[202:205], v[52:55]
	v_mfma_f32_16x16x32_bf16 v[44:47], v[148:151], v[210:213], v[44:47]
	v_mfma_f32_16x16x32_bf16 v[36:39], v[166:169], v[210:213], v[36:39]
	v_mfma_f32_16x16x32_bf16 v[28:31], v[148:151], v[234:237], v[28:31]
	v_mfma_f32_16x16x32_bf16 v[20:23], v[166:169], v[234:237], v[20:23]
	v_mfma_f32_16x16x32_bf16 v[12:15], v[148:151], v[242:245], v[12:15]
	v_mfma_f32_16x16x32_bf16 v[4:7], v[166:169], v[242:245], v[4:7]
	s_setprio 0
	s_setprio 1
	v_mfma_f32_16x16x32_bf16 v[48:51], v[190:193], v[198:201], 0
	v_mfma_f32_16x16x32_bf16 v[40:43], v[170:173], v[206:209], 0
	v_mfma_f32_16x16x32_bf16 v[32:35], v[190:193], v[206:209], 0
	v_mfma_f32_16x16x32_bf16 v[24:27], v[170:173], v[214:217], 0
	v_mfma_f32_16x16x32_bf16 v[16:19], v[190:193], v[214:217], 0
	v_mfma_f32_16x16x32_bf16 v[8:11], v[170:173], v[238:241], 0
	v_mfma_f32_16x16x32_bf16 v[0:3], v[190:193], v[238:241], 0
	v_mfma_f32_16x16x32_bf16 v[60:63], v[170:173], v[198:201], 0
	v_mfma_f32_16x16x32_bf16 v[48:51], v[194:197], v[202:205], v[48:51]
	v_mfma_f32_16x16x32_bf16 v[40:43], v[186:189], v[210:213], v[40:43]
	v_mfma_f32_16x16x32_bf16 v[32:35], v[194:197], v[210:213], v[32:35]
	v_mfma_f32_16x16x32_bf16 v[24:27], v[186:189], v[234:237], v[24:27]
	v_mfma_f32_16x16x32_bf16 v[16:19], v[194:197], v[234:237], v[16:19]
	v_mfma_f32_16x16x32_bf16 v[8:11], v[186:189], v[242:245], v[8:11]
	v_mfma_f32_16x16x32_bf16 v[0:3], v[194:197], v[242:245], v[0:3]
	v_mfma_f32_16x16x32_bf16 v[60:63], v[186:189], v[202:205], v[60:63]
	s_setprio 0
	s_barrier
	ds_read_b128 v[64:67], v156 offset:32768
	ds_read_b128 v[148:151], v156 offset:33792
	ds_read_b128 v[152:155], v156 offset:34816
	ds_read_b128 v[166:169], v156 offset:35840
	ds_read_b128 v[170:173], v156 offset:49152
	ds_read_b128 v[186:189], v156 offset:50176
	ds_read_b128 v[190:193], v156 offset:51200
	ds_read_b128 v[194:197], v156 offset:52224
	s_add_u32 s34, s34, 0x40000
	s_addc_u32 s35, s35, 0
	s_mov_b32 m0, s53
	ds_read_b128 v[198:201], v165 offset:32768
	ds_read_b128 v[202:205], v165 offset:33792
	ds_read_b128 v[206:209], v165 offset:34816
	ds_read_b128 v[210:213], v165 offset:35840
	ds_read_b128 v[214:217], v165 offset:36864
	ds_read_b128 v[234:237], v165 offset:37888
	ds_read_b128 v[238:241], v165 offset:38912
	ds_read_b128 v[242:245], v165 offset:39936
	global_load_lds_dwordx4 v136, s[34:35]
	s_mov_b32 m0, s54
	s_nop 0
	global_load_lds_dwordx4 v138, s[34:35]
	s_waitcnt vmcnt(8)
	s_waitcnt lgkmcnt(0)
	s_setprio 1
	s_barrier
	v_mfma_f32_16x16x32_bf16 v[132:135], v[64:67], v[198:201], v[132:135]
	v_mfma_f32_16x16x32_bf16 v[124:127], v[152:155], v[198:201], v[124:127]
	v_mfma_f32_16x16x32_bf16 v[116:119], v[64:67], v[206:209], v[116:119]
	v_mfma_f32_16x16x32_bf16 v[108:111], v[152:155], v[206:209], v[108:111]
	v_mfma_f32_16x16x32_bf16 v[100:103], v[64:67], v[214:217], v[100:103]
	v_mfma_f32_16x16x32_bf16 v[92:95], v[152:155], v[214:217], v[92:95]
	v_mfma_f32_16x16x32_bf16 v[84:87], v[64:67], v[238:241], v[84:87]
	v_mfma_f32_16x16x32_bf16 v[76:79], v[152:155], v[238:241], v[76:79]
	v_mfma_f32_16x16x32_bf16 v[132:135], v[148:151], v[202:205], v[132:135]
	v_mfma_f32_16x16x32_bf16 v[124:127], v[166:169], v[202:205], v[124:127]
	v_mfma_f32_16x16x32_bf16 v[116:119], v[148:151], v[210:213], v[116:119]
	v_mfma_f32_16x16x32_bf16 v[108:111], v[166:169], v[210:213], v[108:111]
	v_mfma_f32_16x16x32_bf16 v[100:103], v[148:151], v[234:237], v[100:103]
	v_mfma_f32_16x16x32_bf16 v[92:95], v[166:169], v[234:237], v[92:95]
	v_mfma_f32_16x16x32_bf16 v[84:87], v[148:151], v[242:245], v[84:87]
	v_mfma_f32_16x16x32_bf16 v[76:79], v[166:169], v[242:245], v[76:79]
	s_setprio 0
	s_setprio 1
	v_mfma_f32_16x16x32_bf16 v[128:131], v[170:173], v[198:201], v[128:131]
	v_mfma_f32_16x16x32_bf16 v[120:123], v[190:193], v[198:201], v[120:123]
	v_mfma_f32_16x16x32_bf16 v[112:115], v[170:173], v[206:209], v[112:115]
	v_mfma_f32_16x16x32_bf16 v[104:107], v[190:193], v[206:209], v[104:107]
	v_mfma_f32_16x16x32_bf16 v[96:99], v[170:173], v[214:217], v[96:99]
	v_mfma_f32_16x16x32_bf16 v[88:91], v[190:193], v[214:217], v[88:91]
	v_mfma_f32_16x16x32_bf16 v[80:83], v[170:173], v[238:241], v[80:83]
	v_mfma_f32_16x16x32_bf16 v[72:75], v[190:193], v[238:241], v[72:75]
	v_mfma_f32_16x16x32_bf16 v[128:131], v[186:189], v[202:205], v[128:131]
	v_mfma_f32_16x16x32_bf16 v[120:123], v[194:197], v[202:205], v[120:123]
	v_mfma_f32_16x16x32_bf16 v[112:115], v[186:189], v[210:213], v[112:115]
	v_mfma_f32_16x16x32_bf16 v[104:107], v[194:197], v[210:213], v[104:107]
	v_mfma_f32_16x16x32_bf16 v[96:99], v[186:189], v[234:237], v[96:99]
	v_mfma_f32_16x16x32_bf16 v[88:91], v[194:197], v[234:237], v[88:91]
	v_mfma_f32_16x16x32_bf16 v[80:83], v[186:189], v[242:245], v[80:83]
	v_mfma_f32_16x16x32_bf16 v[72:75], v[194:197], v[242:245], v[72:75]
	s_setprio 0
	s_barrier
; #define PG8_STAGE(bufoff, gbase, voff) do { _Pragma("unroll") for (int _i = 0; _i < 2; ++_i) \
;         __builtin_amdgcn_global_load_lds((const unsigned*)((const char*)(gbase) + (voff)[_i]), (PG8_LAS unsigned*)(lds + (bufoff) + ldsw + _i * 8192), 16, 0, 0); } while (0)
; #define PG8_LDA(dst, b, h) do { _Pragma("unroll") for (int m = 0; m < 4; ++m) _Pragma("unroll") for (int k = 0; k < 2; ++k) dst[m][k] = *(const PG8_LAS bf16x8*)(lds + PG8_SA(b, h) + aoff + m * 2048 + k * 1024); } while (0)
; #define PG8_LDB(dst, b, h) do { _Pragma("unroll") for (int n = 0; n < 2; ++n) _Pragma("unroll") for (int k = 0; k < 2; ++k) dst[n][k] = *(const PG8_LAS bf16x8*)(lds + PG8_SB(b, h) + boff + n * 2048 + k * 1024); } while (0)
; #define PG8_WAIT_V(n) asm volatile("s_waitcnt vmcnt(" #n ")" ::: "memory")
; #define PG8_WAIT_L(n) asm volatile("s_waitcnt lgkmcnt(" #n ")" ::: "memory")
; #define PG8_BAR __builtin_amdgcn_s_barrier()
; #define PG8_SCHED __builtin_amdgcn_sched_barrier(0)
; template <class Epi, class Sched, bool ALIGN_EPI = false, bool SP2 = false>
; __device__ __forceinline__ void gemm_phase(PG8_LAS unsigned char* lds, const Gemm g, const Sched& S, const Epi& E) {
;     ...
;         for (int t = 0; t < nt; t += 2) {
;             const bool last = (t == nt - 2);
;             const char* a1 = cA + (size_t)(t + 1) * kstep;
;             const char* a2 = last ? nA : cA + (size_t)(t + 2) * kstep; const char* b2 = last ? nB : cB + (size_t)(t + 2) * kstep;
;             const char* a3 = a2 + kstep; const char* b3 = b2 + kstep;
;             if (last && has_next) S.a_ready(nxt);
;             if constexpr (SP2) {
;             const int relax = __builtin_amdgcn_readfirstlane((t == 0 && ui > 0) ? 1 : 0);
;             PG8_LDB(B0, 0, 0); PG8_LDB(B1, 0, 1); PG8_SCHED; PG8_LDA(At, 0, 0); PG8_STAGE(PG8_SA(1, 1), a1 + hstep, voffA);
;             asm volatile("s_cmp_lg_u32 %0, 0\n\ts_cbranch_scc1 .Lrelax%=\n\ts_waitcnt vmcnt(8)\n.Lrelax%=:\n\ts_waitcnt vmcnt(%1)" :: "s"(relax), "n"(8 + Epi::NST) : "memory", "scc");
;             PG8_WAIT_L(0); PG8_BAR; PG8_MMA(0, 0, At, B0); PG8_MMA(0, 1, At, B1); PG8_BAR; PG8_SCHED;
;     ...
;             PG8_LDA(At, 1, 1); PG8_STAGE(PG8_SB(1, 0), b3, voffB); PG8_STAGE(PG8_SB(1, 1), b3 + hstep, voffB); PG8_STAGE(PG8_SA(1, 0), a3, voffA);
;             PG8_WAIT_V(8); PG8_WAIT_L(0); PG8_BAR; PG8_MMA(1, 0, At, B0); PG8_MMA(1, 1, At, B1); PG8_BAR; PG8_SCHED;
	s_add_i32 m0, s29, 0x18000
	s_add_u32 s4, s4, 0x80
	s_addc_u32 s5, s5, 0
	ds_read_b128 v[198:201], v165 offset:49152
	ds_read_b128 v[202:205], v165 offset:50176
	ds_read_b128 v[206:209], v165 offset:51200
	ds_read_b128 v[210:213], v165 offset:52224
	ds_read_b128 v[214:217], v165 offset:53248
	ds_read_b128 v[234:237], v165 offset:54272
	ds_read_b128 v[238:241], v165 offset:55296
	ds_read_b128 v[242:245], v165 offset:56320
	global_load_lds_dwordx4 v176, s[4:5]
	s_add_i32 m0, s29, 0x1a000
	s_add_u32 s64, s4, 0x40000
	s_addc_u32 s65, s5, 0
	global_load_lds_dwordx4 v140, s[4:5]
	s_add_i32 m0, s29, 0x1c000
	s_add_u32 s34, s34, 0xfffc0080
	s_addc_u32 s35, s35, -1
	global_load_lds_dwordx4 v176, s[64:65]
	s_add_i32 m0, s29, 0x1e000
	s_nop 0
	global_load_lds_dwordx4 v140, s[64:65]
	s_mov_b32 m0, s55
	s_nop 0
	global_load_lds_dwordx4 v136, s[34:35]
	s_mov_b32 m0, s56
	s_nop 0
	global_load_lds_dwordx4 v138, s[34:35]
	s_waitcnt vmcnt(8)
	s_waitcnt lgkmcnt(0)
	s_setprio 1
	s_barrier
	v_mfma_f32_16x16x32_bf16 v[68:71], v[64:67], v[198:201], v[68:71]
	v_mfma_f32_16x16x32_bf16 v[52:55], v[152:155], v[198:201], v[52:55]
	v_mfma_f32_16x16x32_bf16 v[44:47], v[64:67], v[206:209], v[44:47]
	v_mfma_f32_16x16x32_bf16 v[36:39], v[152:155], v[206:209], v[36:39]
	v_mfma_f32_16x16x32_bf16 v[28:31], v[64:67], v[214:217], v[28:31]
	v_mfma_f32_16x16x32_bf16 v[20:23], v[152:155], v[214:217], v[20:23]
	v_mfma_f32_16x16x32_bf16 v[12:15], v[64:67], v[238:241], v[12:15]
	v_mfma_f32_16x16x32_bf16 v[4:7], v[152:155], v[238:241], v[4:7]
	v_mfma_f32_16x16x32_bf16 v[68:71], v[148:151], v[202:205], v[68:71]
	v_mfma_f32_16x16x32_bf16 v[52:55], v[166:169], v[202:205], v[52:55]
	v_mfma_f32_16x16x32_bf16 v[44:47], v[148:151], v[210:213], v[44:47]
	v_mfma_f32_16x16x32_bf16 v[36:39], v[166:169], v[210:213], v[36:39]
	v_mfma_f32_16x16x32_bf16 v[28:31], v[148:151], v[234:237], v[28:31]
	v_mfma_f32_16x16x32_bf16 v[20:23], v[166:169], v[234:237], v[20:23]
	v_mfma_f32_16x16x32_bf16 v[12:15], v[148:151], v[242:245], v[12:15]
	v_mfma_f32_16x16x32_bf16 v[4:7], v[166:169], v[242:245], v[4:7]
	s_setprio 0
	s_setprio 1
	v_mfma_f32_16x16x32_bf16 v[60:63], v[170:173], v[198:201], v[60:63]
	v_mfma_f32_16x16x32_bf16 v[48:51], v[190:193], v[198:201], v[48:51]
	v_mfma_f32_16x16x32_bf16 v[40:43], v[170:173], v[206:209], v[40:43]
	v_mfma_f32_16x16x32_bf16 v[32:35], v[190:193], v[206:209], v[32:35]
	v_mfma_f32_16x16x32_bf16 v[24:27], v[170:173], v[214:217], v[24:27]
	v_mfma_f32_16x16x32_bf16 v[16:19], v[190:193], v[214:217], v[16:19]
	v_mfma_f32_16x16x32_bf16 v[8:11], v[170:173], v[238:241], v[8:11]
	v_mfma_f32_16x16x32_bf16 v[0:3], v[190:193], v[238:241], v[0:3]
	v_mfma_f32_16x16x32_bf16 v[64:67], v[186:189], v[202:205], v[60:63]
	v_mfma_f32_16x16x32_bf16 v[48:51], v[194:197], v[202:205], v[48:51]
	v_mfma_f32_16x16x32_bf16 v[40:43], v[186:189], v[210:213], v[40:43]
	v_mfma_f32_16x16x32_bf16 v[32:35], v[194:197], v[210:213], v[32:35]
	v_mfma_f32_16x16x32_bf16 v[24:27], v[186:189], v[234:237], v[24:27]
	v_mfma_f32_16x16x32_bf16 v[16:19], v[194:197], v[234:237], v[16:19]
	v_mfma_f32_16x16x32_bf16 v[8:11], v[186:189], v[242:245], v[8:11]
	v_mfma_f32_16x16x32_bf16 v[0:3], v[194:197], v[242:245], v[0:3]
	s_setprio 0
	s_barrier
	s_add_i32 s63, s63, 2
	s_add_u32 s50, s50, 0x100
	s_addc_u32 s51, s51, 0
	s_cmp_gt_u32 s63, 13
.LBB0_236:
	s_add_u32 s4, s40, s50
	s_addc_u32 s5, s41, s51
	s_add_u32 s64, s4, 0x40080
	s_addc_u32 s65, s5, 0
	s_add_u32 s34, s4, 0x100
	s_addc_u32 s35, s5, 0
	s_add_u32 s4, s61, s50
	s_addc_u32 s5, s62, s51
	s_cmpk_eq_i32 s50, 0x700
	s_cselect_b32 s35, s27, s35
	s_cselect_b32 s34, s59, s34
	s_cselect_b32 s5, s25, s5
	s_cselect_b32 s4, s60, s4
	ds_read_b128 v[60:63], v156
	ds_read_b128 v[148:151], v156 offset:1024
	ds_read_b128 v[152:155], v156 offset:2048
	ds_read_b128 v[166:169], v156 offset:3072
	ds_read_b128 v[170:173], v156 offset:16384
	ds_read_b128 v[186:189], v156 offset:17408
	ds_read_b128 v[190:193], v156 offset:18432
	ds_read_b128 v[194:197], v156 offset:19456
	s_add_i32 m0, s31, 0xc000
	ds_read_b128 v[198:201], v165
	ds_read_b128 v[202:205], v165 offset:1024
	ds_read_b128 v[206:209], v165 offset:2048
	ds_read_b128 v[210:213], v165 offset:3072
	ds_read_b128 v[214:217], v165 offset:4096
	ds_read_b128 v[234:237], v165 offset:5120
	ds_read_b128 v[238:241], v165 offset:6144
	ds_read_b128 v[242:245], v165 offset:7168
	global_load_lds_dwordx4 v144, s[64:65]
	s_add_i32 m0, s31, 0xe000
	s_nop 0
	global_load_lds_dwordx4 v146, s[64:65]
	s_waitcnt vmcnt(8)
	s_waitcnt lgkmcnt(0)
	s_setprio 1
	s_barrier
; #define PG8_STAGE(bufoff, gbase, voff) do { _Pragma("unroll") for (int _i = 0; _i < 2; ++_i) \
;         __builtin_amdgcn_global_load_lds((const unsigned*)((const char*)(gbase) + (voff)[_i]), (PG8_LAS unsigned*)(lds + (bufoff) + ldsw + _i * 8192), 16, 0, 0); } while (0)
; #define PG8_LDA(dst, b, h) do { _Pragma("unroll") for (int m = 0; m < 4; ++m) _Pragma("unroll") for (int k = 0; k < 2; ++k) dst[m][k] = *(const PG8_LAS bf16x8*)(lds + PG8_SA(b, h) + aoff + m * 2048 + k * 1024); } while (0)
; #define PG8_LDB(dst, b, h) do { _Pragma("unroll") for (int n = 0; n < 2; ++n) _Pragma("unroll") for (int k = 0; k < 2; ++k) dst[n][k] = *(const PG8_LAS bf16x8*)(lds + PG8_SB(b, h) + boff + n * 2048 + k * 1024); } while (0)
; #define PG8_MMA(ai, bj, At, Bt) do { __builtin_amdgcn_s_setprio(1); _Pragma("unroll") for (int m = 0; m < 4; ++m) _Pragma("unroll") for (int n = 0; n < 2; ++n) _Pragma("unroll") for (int k = 0; k < 2; ++k) \
;         acc[ai][bj][m][n] = __builtin_amdgcn_mfma_f32_16x16x32_bf16(Bt[n][k], At[m][k], acc[ai][bj][m][n], 0, 0, 0); __builtin_amdgcn_s_setprio(0); } while (0)
; #define PG8_WAIT_L(n) asm volatile("s_waitcnt lgkmcnt(" #n ")" ::: "memory")
; #define PG8_BAR __builtin_amdgcn_s_barrier()
; #define PG8_SCHED __builtin_amdgcn_sched_barrier(0)
; template <class Epi, class Sched, bool ALIGN_EPI = false, bool SP2 = false>
; __device__ __forceinline__ void gemm_phase(PG8_LAS unsigned char* lds, const Gemm g, const Sched& S, const Epi& E) {
;     ...
;             PG8_LDB(B0, 0, 0); PG8_LDB(B1, 0, 1); PG8_SCHED; PG8_LDA(At, 0, 0); PG8_STAGE(PG8_SA(1, 1), a1 + hstep, voffA);
;             asm volatile("s_cmp_lg_u32 %0, 0\n\ts_cbranch_scc1 .Lrelax%=\n\ts_waitcnt vmcnt(8)\n.Lrelax%=:\n\ts_waitcnt vmcnt(%1)" :: "s"(relax), "n"(8 + Epi::NST) : "memory", "scc");
;             PG8_WAIT_L(0); PG8_BAR; PG8_MMA(0, 0, At, B0); PG8_MMA(0, 1, At, B1); PG8_BAR; PG8_SCHED;
;             PG8_LDA(At, 0, 1); PG8_STAGE(PG8_SB(0, 0), b2, voffB); PG8_STAGE(PG8_SB(0, 1), b2 + hstep, voffB); PG8_STAGE(PG8_SA(0, 0), a2, voffA);
;             asm volatile("s_cmp_lg_u32 %0, 0\n\ts_cbranch_scc1 .Lrelax%=\n\ts_waitcnt vmcnt(8)\n.Lrelax%=:\n\ts_waitcnt vmcnt(%1)" :: "s"(relax), "n"(8 + Epi::NST) : "memory", "scc");
;             PG8_WAIT_L(0); PG8_BAR; PG8_MMA(1, 0, At, B0); PG8_MMA(1, 1, At, B1); PG8_BAR; PG8_SCHED;
	v_mfma_f32_16x16x32_bf16 v[132:135], v[60:63], v[198:201], v[132:135]
	v_mfma_f32_16x16x32_bf16 v[124:127], v[152:155], v[198:201], v[124:127]
	v_mfma_f32_16x16x32_bf16 v[116:119], v[60:63], v[206:209], v[116:119]
	v_mfma_f32_16x16x32_bf16 v[108:111], v[152:155], v[206:209], v[108:111]
	v_mfma_f32_16x16x32_bf16 v[100:103], v[60:63], v[214:217], v[100:103]
	v_mfma_f32_16x16x32_bf16 v[92:95], v[152:155], v[214:217], v[92:95]
	v_mfma_f32_16x16x32_bf16 v[84:87], v[60:63], v[238:241], v[84:87]
	v_mfma_f32_16x16x32_bf16 v[76:79], v[152:155], v[238:241], v[76:79]
	v_mfma_f32_16x16x32_bf16 v[132:135], v[148:151], v[202:205], v[132:135]
	v_mfma_f32_16x16x32_bf16 v[124:127], v[166:169], v[202:205], v[124:127]
	v_mfma_f32_16x16x32_bf16 v[116:119], v[148:151], v[210:213], v[116:119]
	v_mfma_f32_16x16x32_bf16 v[108:111], v[166:169], v[210:213], v[108:111]
	v_mfma_f32_16x16x32_bf16 v[100:103], v[148:151], v[234:237], v[100:103]
	v_mfma_f32_16x16x32_bf16 v[92:95], v[166:169], v[234:237], v[92:95]
	v_mfma_f32_16x16x32_bf16 v[84:87], v[148:151], v[242:245], v[84:87]
	v_mfma_f32_16x16x32_bf16 v[76:79], v[166:169], v[242:245], v[76:79]
	s_setprio 0
	s_setprio 1
	v_mfma_f32_16x16x32_bf16 v[128:131], v[170:173], v[198:201], v[128:131]
	v_mfma_f32_16x16x32_bf16 v[120:123], v[190:193], v[198:201], v[120:123]
	v_mfma_f32_16x16x32_bf16 v[112:115], v[170:173], v[206:209], v[112:115]
	v_mfma_f32_16x16x32_bf16 v[104:107], v[190:193], v[206:209], v[104:107]
	v_mfma_f32_16x16x32_bf16 v[96:99], v[170:173], v[214:217], v[96:99]
	v_mfma_f32_16x16x32_bf16 v[88:91], v[190:193], v[214:217], v[88:91]
	v_mfma_f32_16x16x32_bf16 v[80:83], v[170:173], v[238:241], v[80:83]
	v_mfma_f32_16x16x32_bf16 v[72:75], v[190:193], v[238:241], v[72:75]
	v_mfma_f32_16x16x32_bf16 v[128:131], v[186:189], v[202:205], v[128:131]
	v_mfma_f32_16x16x32_bf16 v[120:123], v[194:197], v[202:205], v[120:123]
	v_mfma_f32_16x16x32_bf16 v[112:115], v[186:189], v[210:213], v[112:115]
	v_mfma_f32_16x16x32_bf16 v[104:107], v[194:197], v[210:213], v[104:107]
	v_mfma_f32_16x16x32_bf16 v[96:99], v[186:189], v[234:237], v[96:99]
	v_mfma_f32_16x16x32_bf16 v[88:91], v[194:197], v[234:237], v[88:91]
	v_mfma_f32_16x16x32_bf16 v[80:83], v[186:189], v[242:245], v[80:83]
	v_mfma_f32_16x16x32_bf16 v[72:75], v[194:197], v[242:245], v[72:75]
	s_setprio 0
	s_barrier
	s_add_i32 m0, s29, 0x10000
	ds_read_b128 v[198:201], v165 offset:16384
	ds_read_b128 v[202:205], v165 offset:17408
	ds_read_b128 v[206:209], v165 offset:18432
	ds_read_b128 v[210:213], v165 offset:19456
	ds_read_b128 v[214:217], v165 offset:20480
	ds_read_b128 v[234:237], v165 offset:21504
	ds_read_b128 v[238:241], v165 offset:22528
	ds_read_b128 v[242:245], v165 offset:23552
	global_load_lds_dwordx4 v176, s[4:5]
	s_add_i32 m0, s29, 0x12000
	s_add_u32 s64, s4, 0x40000
	s_addc_u32 s65, s5, 0
	global_load_lds_dwordx4 v140, s[4:5]
	s_add_i32 m0, s29, 0x14000
	s_nop 0
	global_load_lds_dwordx4 v176, s[64:65]
	s_add_i32 m0, s29, 0x16000
	s_nop 0
	global_load_lds_dwordx4 v140, s[64:65]
	s_mov_b32 m0, s31
	s_nop 0
	global_load_lds_dwordx4 v136, s[34:35]
	s_mov_b32 m0, s52
	s_nop 0
	global_load_lds_dwordx4 v138, s[34:35]
	s_waitcnt vmcnt(8)
	s_waitcnt lgkmcnt(0)
	s_setprio 1
	s_barrier
	v_mfma_f32_16x16x32_bf16 v[68:71], v[60:63], v[198:201], v[68:71]
	v_mfma_f32_16x16x32_bf16 v[52:55], v[152:155], v[198:201], v[52:55]
	v_mfma_f32_16x16x32_bf16 v[44:47], v[60:63], v[206:209], v[44:47]
	v_mfma_f32_16x16x32_bf16 v[36:39], v[152:155], v[206:209], v[36:39]
	v_mfma_f32_16x16x32_bf16 v[28:31], v[60:63], v[214:217], v[28:31]
	v_mfma_f32_16x16x32_bf16 v[20:23], v[152:155], v[214:217], v[20:23]
	v_mfma_f32_16x16x32_bf16 v[12:15], v[60:63], v[238:241], v[12:15]
	v_mfma_f32_16x16x32_bf16 v[4:7], v[152:155], v[238:241], v[4:7]
	v_mfma_f32_16x16x32_bf16 v[68:71], v[148:151], v[202:205], v[68:71]
	v_mfma_f32_16x16x32_bf16 v[52:55], v[166:169], v[202:205], v[52:55]
	v_mfma_f32_16x16x32_bf16 v[44:47], v[148:151], v[210:213], v[44:47]
	v_mfma_f32_16x16x32_bf16 v[36:39], v[166:169], v[210:213], v[36:39]
	v_mfma_f32_16x16x32_bf16 v[28:31], v[148:151], v[234:237], v[28:31]
	v_mfma_f32_16x16x32_bf16 v[20:23], v[166:169], v[234:237], v[20:23]
	v_mfma_f32_16x16x32_bf16 v[12:15], v[148:151], v[242:245], v[12:15]
	v_mfma_f32_16x16x32_bf16 v[4:7], v[166:169], v[242:245], v[4:7]
	s_setprio 0
	s_setprio 1
	v_mfma_f32_16x16x32_bf16 v[48:51], v[190:193], v[198:201], v[48:51]
	v_mfma_f32_16x16x32_bf16 v[40:43], v[170:173], v[206:209], v[40:43]
	v_mfma_f32_16x16x32_bf16 v[32:35], v[190:193], v[206:209], v[32:35]
	v_mfma_f32_16x16x32_bf16 v[24:27], v[170:173], v[214:217], v[24:27]
	v_mfma_f32_16x16x32_bf16 v[16:19], v[190:193], v[214:217], v[16:19]
	v_mfma_f32_16x16x32_bf16 v[8:11], v[170:173], v[238:241], v[8:11]
	v_mfma_f32_16x16x32_bf16 v[0:3], v[190:193], v[238:241], v[0:3]
	v_mfma_f32_16x16x32_bf16 v[60:63], v[170:173], v[198:201], v[64:67]
	v_mfma_f32_16x16x32_bf16 v[48:51], v[194:197], v[202:205], v[48:51]
	v_mfma_f32_16x16x32_bf16 v[40:43], v[186:189], v[210:213], v[40:43]
	v_mfma_f32_16x16x32_bf16 v[32:35], v[194:197], v[210:213], v[32:35]
	v_mfma_f32_16x16x32_bf16 v[24:27], v[186:189], v[234:237], v[24:27]
	v_mfma_f32_16x16x32_bf16 v[16:19], v[194:197], v[234:237], v[16:19]
	v_mfma_f32_16x16x32_bf16 v[8:11], v[186:189], v[242:245], v[8:11]
	v_mfma_f32_16x16x32_bf16 v[0:3], v[194:197], v[242:245], v[0:3]
	v_mfma_f32_16x16x32_bf16 v[60:63], v[186:189], v[202:205], v[60:63]
	s_setprio 0
	s_barrier
; #define PG8_STAGE(bufoff, gbase, voff) do { _Pragma("unroll") for (int _i = 0; _i < 2; ++_i) \
;         __builtin_amdgcn_global_load_lds((const unsigned*)((const char*)(gbase) + (voff)[_i]), (PG8_LAS unsigned*)(lds + (bufoff) + ldsw + _i * 8192), 16, 0, 0); } while (0)
; #define PG8_LDA(dst, b, h) do { _Pragma("unroll") for (int m = 0; m < 4; ++m) _Pragma("unroll") for (int k = 0; k < 2; ++k) dst[m][k] = *(const PG8_LAS bf16x8*)(lds + PG8_SA(b, h) + aoff + m * 2048 + k * 1024); } while (0)
; #define PG8_LDB(dst, b, h) do { _Pragma("unroll") for (int n = 0; n < 2; ++n) _Pragma("unroll") for (int k = 0; k < 2; ++k) dst[n][k] = *(const PG8_LAS bf16x8*)(lds + PG8_SB(b, h) + boff + n * 2048 + k * 1024); } while (0)
; #define PG8_MMA(ai, bj, At, Bt) do { __builtin_amdgcn_s_setprio(1); _Pragma("unroll") for (int m = 0; m < 4; ++m) _Pragma("unroll") for (int n = 0; n < 2; ++n) _Pragma("unroll") for (int k = 0; k < 2; ++k) \
;         acc[ai][bj][m][n] = __builtin_amdgcn_mfma_f32_16x16x32_bf16(Bt[n][k], At[m][k], acc[ai][bj][m][n], 0, 0, 0); __builtin_amdgcn_s_setprio(0); } while (0)
; #define PG8_WAIT_V(n) asm volatile("s_waitcnt vmcnt(" #n ")" ::: "memory")
; #define PG8_WAIT_L(n) asm volatile("s_waitcnt lgkmcnt(" #n ")" ::: "memory")
; #define PG8_BAR __builtin_amdgcn_s_barrier()
; #define PG8_SCHED __builtin_amdgcn_sched_barrier(0)
; template <class Epi, class Sched, bool ALIGN_EPI = false, bool SP2 = false>
; __device__ __forceinline__ void gemm_phase(PG8_LAS unsigned char* lds, const Gemm g, const Sched& S, const Epi& E) {
;     ...
;             PG8_LDB(B0, 1, 0); PG8_LDB(B1, 1, 1); PG8_SCHED; PG8_LDA(At, 1, 0); PG8_STAGE(PG8_SA(0, 1), a2 + hstep, voffA);
;             PG8_WAIT_V(8); PG8_WAIT_L(0); PG8_BAR; PG8_MMA(0, 0, At, B0); PG8_MMA(0, 1, At, B1); PG8_BAR; PG8_SCHED;
;             PG8_LDA(At, 1, 1); PG8_STAGE(PG8_SB(1, 0), b3, voffB); PG8_STAGE(PG8_SB(1, 1), b3 + hstep, voffB); PG8_STAGE(PG8_SA(1, 0), a3, voffA);
;             PG8_WAIT_V(8); PG8_WAIT_L(0); PG8_BAR; PG8_MMA(1, 0, At, B0); PG8_MMA(1, 1, At, B1); PG8_BAR; PG8_SCHED;
	ds_read_b128 v[64:67], v156 offset:32768
	ds_read_b128 v[148:151], v156 offset:33792
	ds_read_b128 v[152:155], v156 offset:34816
	ds_read_b128 v[166:169], v156 offset:35840
	ds_read_b128 v[170:173], v156 offset:49152
	ds_read_b128 v[186:189], v156 offset:50176
	ds_read_b128 v[190:193], v156 offset:51200
	ds_read_b128 v[194:197], v156 offset:52224
	s_add_u32 s34, s34, 0x40000
	s_addc_u32 s35, s35, 0
	s_mov_b32 m0, s53
	ds_read_b128 v[198:201], v165 offset:32768
	ds_read_b128 v[202:205], v165 offset:33792
	ds_read_b128 v[206:209], v165 offset:34816
	ds_read_b128 v[210:213], v165 offset:35840
	ds_read_b128 v[214:217], v165 offset:36864
	ds_read_b128 v[234:237], v165 offset:37888
	ds_read_b128 v[238:241], v165 offset:38912
	ds_read_b128 v[242:245], v165 offset:39936
	global_load_lds_dwordx4 v136, s[34:35]
	s_mov_b32 m0, s54
	s_nop 0
	global_load_lds_dwordx4 v138, s[34:35]
	s_waitcnt vmcnt(8)
	s_waitcnt lgkmcnt(0)
	s_setprio 1
	s_barrier
	v_mfma_f32_16x16x32_bf16 v[132:135], v[64:67], v[198:201], v[132:135]
	v_mfma_f32_16x16x32_bf16 v[124:127], v[152:155], v[198:201], v[124:127]
	v_mfma_f32_16x16x32_bf16 v[116:119], v[64:67], v[206:209], v[116:119]
	v_mfma_f32_16x16x32_bf16 v[108:111], v[152:155], v[206:209], v[108:111]
	v_mfma_f32_16x16x32_bf16 v[100:103], v[64:67], v[214:217], v[100:103]
	v_mfma_f32_16x16x32_bf16 v[92:95], v[152:155], v[214:217], v[92:95]
	v_mfma_f32_16x16x32_bf16 v[84:87], v[64:67], v[238:241], v[84:87]
	v_mfma_f32_16x16x32_bf16 v[76:79], v[152:155], v[238:241], v[76:79]
	v_mfma_f32_16x16x32_bf16 v[132:135], v[148:151], v[202:205], v[132:135]
	v_mfma_f32_16x16x32_bf16 v[124:127], v[166:169], v[202:205], v[124:127]
	v_mfma_f32_16x16x32_bf16 v[116:119], v[148:151], v[210:213], v[116:119]
	v_mfma_f32_16x16x32_bf16 v[108:111], v[166:169], v[210:213], v[108:111]
	v_mfma_f32_16x16x32_bf16 v[100:103], v[148:151], v[234:237], v[100:103]
	v_mfma_f32_16x16x32_bf16 v[92:95], v[166:169], v[234:237], v[92:95]
	v_mfma_f32_16x16x32_bf16 v[84:87], v[148:151], v[242:245], v[84:87]
	v_mfma_f32_16x16x32_bf16 v[76:79], v[166:169], v[242:245], v[76:79]
	s_setprio 0
	s_setprio 1
	v_mfma_f32_16x16x32_bf16 v[128:131], v[170:173], v[198:201], v[128:131]
	v_mfma_f32_16x16x32_bf16 v[120:123], v[190:193], v[198:201], v[120:123]
	v_mfma_f32_16x16x32_bf16 v[112:115], v[170:173], v[206:209], v[112:115]
	v_mfma_f32_16x16x32_bf16 v[104:107], v[190:193], v[206:209], v[104:107]
	v_mfma_f32_16x16x32_bf16 v[96:99], v[170:173], v[214:217], v[96:99]
	v_mfma_f32_16x16x32_bf16 v[88:91], v[190:193], v[214:217], v[88:91]
	v_mfma_f32_16x16x32_bf16 v[80:83], v[170:173], v[238:241], v[80:83]
	v_mfma_f32_16x16x32_bf16 v[72:75], v[190:193], v[238:241], v[72:75]
	v_mfma_f32_16x16x32_bf16 v[128:131], v[186:189], v[202:205], v[128:131]
	v_mfma_f32_16x16x32_bf16 v[120:123], v[194:197], v[202:205], v[120:123]
	v_mfma_f32_16x16x32_bf16 v[112:115], v[186:189], v[210:213], v[112:115]
	v_mfma_f32_16x16x32_bf16 v[104:107], v[194:197], v[210:213], v[104:107]
	v_mfma_f32_16x16x32_bf16 v[96:99], v[186:189], v[234:237], v[96:99]
	v_mfma_f32_16x16x32_bf16 v[88:91], v[194:197], v[234:237], v[88:91]
	v_mfma_f32_16x16x32_bf16 v[80:83], v[186:189], v[242:245], v[80:83]
	v_mfma_f32_16x16x32_bf16 v[72:75], v[194:197], v[242:245], v[72:75]
	s_setprio 0
	s_barrier
	s_add_i32 m0, s29, 0x18000
	s_add_u32 s4, s4, 0x80
	s_addc_u32 s5, s5, 0
	ds_read_b128 v[198:201], v165 offset:49152
	ds_read_b128 v[202:205], v165 offset:50176
	ds_read_b128 v[206:209], v165 offset:51200
	ds_read_b128 v[210:213], v165 offset:52224
	ds_read_b128 v[214:217], v165 offset:53248
	ds_read_b128 v[234:237], v165 offset:54272
	ds_read_b128 v[238:241], v165 offset:55296
	ds_read_b128 v[242:245], v165 offset:56320
	global_load_lds_dwordx4 v176, s[4:5]
	s_add_i32 m0, s29, 0x1a000
	s_add_u32 s64, s4, 0x40000
	s_addc_u32 s65, s5, 0
	global_load_lds_dwordx4 v140, s[4:5]
	s_add_i32 m0, s29, 0x1c000
	s_add_u32 s34, s34, 0xfffc0080
	s_addc_u32 s35, s35, -1
	global_load_lds_dwordx4 v176, s[64:65]
	s_add_i32 m0, s29, 0x1e000
	s_nop 0
	global_load_lds_dwordx4 v140, s[64:65]
	s_mov_b32 m0, s55
	s_nop 0
	global_load_lds_dwordx4 v136, s[34:35]
	s_mov_b32 m0, s56
	s_nop 0
	global_load_lds_dwordx4 v138, s[34:35]
	s_waitcnt vmcnt(8)
	s_waitcnt lgkmcnt(0)
	s_setprio 1
	s_barrier
	v_mfma_f32_16x16x32_bf16 v[68:71], v[64:67], v[198:201], v[68:71]
	v_mfma_f32_16x16x32_bf16 v[52:55], v[152:155], v[198:201], v[52:55]
	v_mfma_f32_16x16x32_bf16 v[44:47], v[64:67], v[206:209], v[44:47]
	v_mfma_f32_16x16x32_bf16 v[36:39], v[152:155], v[206:209], v[36:39]
	v_mfma_f32_16x16x32_bf16 v[28:31], v[64:67], v[214:217], v[28:31]
	v_mfma_f32_16x16x32_bf16 v[20:23], v[152:155], v[214:217], v[20:23]
	v_mfma_f32_16x16x32_bf16 v[12:15], v[64:67], v[238:241], v[12:15]
	v_mfma_f32_16x16x32_bf16 v[4:7], v[152:155], v[238:241], v[4:7]
	v_mfma_f32_16x16x32_bf16 v[68:71], v[148:151], v[202:205], v[68:71]
	v_mfma_f32_16x16x32_bf16 v[52:55], v[166:169], v[202:205], v[52:55]
	v_mfma_f32_16x16x32_bf16 v[44:47], v[148:151], v[210:213], v[44:47]
	v_mfma_f32_16x16x32_bf16 v[36:39], v[166:169], v[210:213], v[36:39]
	v_mfma_f32_16x16x32_bf16 v[28:31], v[148:151], v[234:237], v[28:31]
	v_mfma_f32_16x16x32_bf16 v[20:23], v[166:169], v[234:237], v[20:23]
	v_mfma_f32_16x16x32_bf16 v[12:15], v[148:151], v[242:245], v[12:15]
	v_mfma_f32_16x16x32_bf16 v[4:7], v[166:169], v[242:245], v[4:7]
	s_setprio 0
	s_setprio 1
	v_mfma_f32_16x16x32_bf16 v[60:63], v[170:173], v[198:201], v[60:63]
	v_mfma_f32_16x16x32_bf16 v[48:51], v[190:193], v[198:201], v[48:51]
	v_mfma_f32_16x16x32_bf16 v[40:43], v[170:173], v[206:209], v[40:43]
	v_mfma_f32_16x16x32_bf16 v[32:35], v[190:193], v[206:209], v[32:35]
	v_mfma_f32_16x16x32_bf16 v[24:27], v[170:173], v[214:217], v[24:27]
	v_mfma_f32_16x16x32_bf16 v[16:19], v[190:193], v[214:217], v[16:19]
	v_mfma_f32_16x16x32_bf16 v[8:11], v[170:173], v[238:241], v[8:11]
	v_mfma_f32_16x16x32_bf16 v[0:3], v[190:193], v[238:241], v[0:3]
	v_mfma_f32_16x16x32_bf16 v[64:67], v[186:189], v[202:205], v[60:63]
	v_mfma_f32_16x16x32_bf16 v[48:51], v[194:197], v[202:205], v[48:51]
	v_mfma_f32_16x16x32_bf16 v[40:43], v[186:189], v[210:213], v[40:43]
	v_mfma_f32_16x16x32_bf16 v[32:35], v[194:197], v[210:213], v[32:35]
	v_mfma_f32_16x16x32_bf16 v[24:27], v[186:189], v[234:237], v[24:27]
	v_mfma_f32_16x16x32_bf16 v[16:19], v[194:197], v[234:237], v[16:19]
	v_mfma_f32_16x16x32_bf16 v[8:11], v[186:189], v[242:245], v[8:11]
	v_mfma_f32_16x16x32_bf16 v[0:3], v[194:197], v[242:245], v[0:3]
	s_setprio 0
	s_barrier
	s_add_i32 s63, s63, 2
	s_add_u32 s50, s50, 0x100
	s_addc_u32 s51, s51, 0
	s_cmp_gt_u32 s63, 13
	s_cbranch_scc0 .LBB0_236
